# early2 + tail priority + faster wake, and the mid-burst setprio 0/1 toggle removed (burst stays at priority 1)
# baseline (speedup 1.0000x reference)
; #define PG8_STAGE(bufoff, gbase, voff) do { _Pragma("unroll") for (int _i = 0; _i < 2; ++_i) \
;         __builtin_amdgcn_global_load_lds((const unsigned*)((const char*)(gbase) + (voff)[_i]), (PG8_LAS unsigned*)(lds + (bufoff) + ldsw + _i * 8192), 16, 0, 0); } while (0)
; #define PG8_LDA(dst, b, h) do { _Pragma("unroll") for (int m = 0; m < 4; ++m) _Pragma("unroll") for (int k = 0; k < 2; ++k) dst[m][k] = *(const PG8_LAS bf16x8*)(lds + PG8_SA(b, h) + aoff + m * 2048 + k * 1024); } while (0)
; #define PG8_LDB(dst, b, h) do { _Pragma("unroll") for (int n = 0; n < 2; ++n) _Pragma("unroll") for (int k = 0; k < 2; ++k) dst[n][k] = *(const PG8_LAS bf16x8*)(lds + PG8_SB(b, h) + boff + n * 2048 + k * 1024); } while (0)
; #define PG8_MMA(ai, bj, At, Bt) do { __builtin_amdgcn_s_setprio(1); _Pragma("unroll") for (int m = 0; m < 4; ++m) _Pragma("unroll") for (int n = 0; n < 2; ++n) _Pragma("unroll") for (int k = 0; k < 2; ++k) \
;         acc[ai][bj][m][n] = __builtin_amdgcn_mfma_f32_16x16x32_bf16(Bt[n][k], At[m][k], acc[ai][bj][m][n], 0, 0, 0); __builtin_amdgcn_s_setprio(0); } while (0)
; #define PG8_WAIT_V(n) asm volatile("s_waitcnt vmcnt(" #n ")" ::: "memory")
; #define PG8_WAIT_L(n) asm volatile("s_waitcnt lgkmcnt(" #n ")" ::: "memory")
; #define PG8_BAR __builtin_amdgcn_s_barrier()
; template <class Epi, class Sched, bool ALIGN_EPI = false, bool SP2 = false>
; __device__ __forceinline__ void gemm_phase(PG8_LAS unsigned char* lds, const Gemm g, const Sched& S, const Epi& E) {
;     ...
;         for (int t = 0; t < nt; t += 2) {
;             const bool last = (t == nt - 2);
;             const char* a1 = cA + (size_t)(t + 1) * kstep;
;             const char* a2 = last ? nA : cA + (size_t)(t + 2) * kstep; const char* b2 = last ? nB : cB + (size_t)(t + 2) * kstep;
;             const char* a3 = a2 + kstep; const char* b3 = b2 + kstep;
;             if constexpr (SP2) {
;             PG8_LDB(B0, 0, 0); PG8_LDB(B1, 0, 1); PG8_SCHED; PG8_LDA(At, 0, 0); PG8_STAGE(PG8_SA(1, 1), a1 + hstep, voffA);
;             PG8_WAIT_V(8); PG8_WAIT_L(0); PG8_BAR; PG8_MMA(0, 0, At, B0); PG8_MMA(0, 1, At, B1); PG8_BAR; PG8_SCHED;
;             PG8_LDA(At, 0, 1); PG8_STAGE(PG8_SB(0, 0), b2, voffB); PG8_STAGE(PG8_SB(0, 1), b2 + hstep, voffB); PG8_STAGE(PG8_SA(0, 0), a2, voffA);
;             PG8_WAIT_V(8); PG8_WAIT_L(0); PG8_BAR; PG8_MMA(1, 0, At, B0); PG8_MMA(1, 1, At, B1); PG8_BAR; PG8_SCHED;
.LBB0_200:
	ds_read_b128 v[148:151], v164
	ds_read_b128 v[152:155], v164 offset:1024
	ds_read_b128 v[156:159], v164 offset:2048
	ds_read_b128 v[168:171], v164 offset:3072
	ds_read_b128 v[172:175], v165
	ds_read_b128 v[176:179], v165 offset:1024
	ds_read_b128 v[180:183], v165 offset:2048
	ds_read_b128 v[184:187], v165 offset:3072
	s_add_u32 s52, s70, 0xfff80080
	s_addc_u32 s53, s71, -1
	s_cmp_eq_u32 s93, 28
	s_cselect_b32 s75, s39, s53
	s_cselect_b32 s74, s69, s52
	s_cselect_b32 s73, s35, s92
	s_cselect_b32 s72, s90, s91
	v_lshl_add_u64 v[220:221], s[70:71], 0, v[138:139]
	s_add_i32 m0, s33, 0xc000
	ds_read_b128 v[188:191], v166
	ds_read_b128 v[192:195], v166 offset:1024
	ds_read_b128 v[196:199], v166 offset:2048
	ds_read_b128 v[200:203], v166 offset:3072
	ds_read_b128 v[204:207], v166 offset:4096
	ds_read_b128 v[208:211], v166 offset:5120
	ds_read_b128 v[212:215], v166 offset:6144
	ds_read_b128 v[216:219], v166 offset:7168
	global_load_lds_dwordx4 v[220:221], off
	v_lshl_add_u64 v[220:221], s[70:71], 0, v[140:141]
	s_add_i32 m0, s33, 0xe000
	s_nop 0
	global_load_lds_dwordx4 v[220:221], off
	s_waitcnt vmcnt(8)
	s_waitcnt lgkmcnt(0)
	s_setprio 1
	s_barrier
	v_mfma_f32_16x16x32_bf16 v[124:127], v[148:151], v[188:191], v[124:127]
	v_mfma_f32_16x16x32_bf16 v[120:123], v[156:159], v[188:191], v[120:123]
	v_mfma_f32_16x16x32_bf16 v[116:119], v[148:151], v[196:199], v[116:119]
	v_mfma_f32_16x16x32_bf16 v[108:111], v[156:159], v[196:199], v[108:111]
	v_mfma_f32_16x16x32_bf16 v[100:103], v[148:151], v[204:207], v[100:103]
	v_mfma_f32_16x16x32_bf16 v[92:95], v[156:159], v[204:207], v[92:95]
	v_mfma_f32_16x16x32_bf16 v[84:87], v[148:151], v[212:215], v[84:87]
	v_mfma_f32_16x16x32_bf16 v[76:79], v[156:159], v[212:215], v[76:79]
	v_mfma_f32_16x16x32_bf16 v[124:127], v[152:155], v[192:195], v[124:127]
	v_mfma_f32_16x16x32_bf16 v[120:123], v[168:171], v[192:195], v[120:123]
	v_mfma_f32_16x16x32_bf16 v[116:119], v[152:155], v[200:203], v[116:119]
	v_mfma_f32_16x16x32_bf16 v[108:111], v[168:171], v[200:203], v[108:111]
	v_mfma_f32_16x16x32_bf16 v[100:103], v[152:155], v[208:211], v[100:103]
	v_mfma_f32_16x16x32_bf16 v[92:95], v[168:171], v[208:211], v[92:95]
	v_mfma_f32_16x16x32_bf16 v[84:87], v[152:155], v[216:219], v[84:87]
	v_mfma_f32_16x16x32_bf16 v[76:79], v[168:171], v[216:219], v[76:79]
	v_mfma_f32_16x16x32_bf16 v[112:115], v[172:175], v[188:191], v[112:115]
	v_mfma_f32_16x16x32_bf16 v[104:107], v[180:183], v[188:191], v[104:107]
	v_mfma_f32_16x16x32_bf16 v[96:99], v[172:175], v[196:199], v[96:99]
	v_mfma_f32_16x16x32_bf16 v[88:91], v[180:183], v[196:199], v[88:91]
	v_mfma_f32_16x16x32_bf16 v[80:83], v[172:175], v[204:207], v[80:83]
	v_mfma_f32_16x16x32_bf16 v[72:75], v[180:183], v[204:207], v[72:75]
	v_mfma_f32_16x16x32_bf16 v[68:71], v[172:175], v[212:215], v[68:71]
	v_mfma_f32_16x16x32_bf16 v[64:67], v[180:183], v[212:215], v[64:67]
	v_mfma_f32_16x16x32_bf16 v[112:115], v[176:179], v[192:195], v[112:115]
	v_mfma_f32_16x16x32_bf16 v[104:107], v[184:187], v[192:195], v[104:107]
	v_mfma_f32_16x16x32_bf16 v[96:99], v[176:179], v[200:203], v[96:99]
	v_mfma_f32_16x16x32_bf16 v[88:91], v[184:187], v[200:203], v[88:91]
	v_mfma_f32_16x16x32_bf16 v[80:83], v[176:179], v[208:211], v[80:83]
	v_mfma_f32_16x16x32_bf16 v[72:75], v[184:187], v[208:211], v[72:75]
	s_setprio 2
	s_barrier
	v_mfma_f32_16x16x32_bf16 v[68:71], v[176:179], v[216:219], v[68:71]
	v_mfma_f32_16x16x32_bf16 v[64:67], v[184:187], v[216:219], v[64:67]
	s_setprio 0
	s_add_i32 s52, s84, s3
	v_lshl_add_u64 v[220:221], s[72:73], 0, v[132:133]
	s_mov_b32 m0, s52
	ds_read_b128 v[188:191], v166 offset:16384
	ds_read_b128 v[192:195], v166 offset:17408
	ds_read_b128 v[196:199], v166 offset:18432
	ds_read_b128 v[200:203], v166 offset:19456
	ds_read_b128 v[204:207], v166 offset:20480
	ds_read_b128 v[208:211], v166 offset:21504
	ds_read_b128 v[212:215], v166 offset:22528
	ds_read_b128 v[216:219], v166 offset:23552
	global_load_lds_dwordx4 v[220:221], off
	s_add_i32 m0, s52, 0x2000
	s_add_u32 s96, s72, 0x80000
	v_lshl_add_u64 v[222:223], s[72:73], 0, v[128:129]
	s_addc_u32 s97, s73, 0
	s_add_i32 s52, s85, s3
	global_load_lds_dwordx4 v[222:223], off
	v_lshl_add_u64 v[224:225], s[96:97], 0, v[132:133]
	s_mov_b32 m0, s52
	v_lshl_add_u64 v[226:227], s[74:75], 0, v[130:131]
	global_load_lds_dwordx4 v[224:225], off
	v_lshl_add_u64 v[224:225], s[96:97], 0, v[128:129]
	s_add_i32 m0, s52, 0x2000
	s_nop 0
	global_load_lds_dwordx4 v[224:225], off
	v_lshl_add_u64 v[224:225], s[74:75], 0, v[134:135]
	s_mov_b32 m0, s33
	s_nop 0
	global_load_lds_dwordx4 v[224:225], off
	s_mov_b32 m0, s76
	s_nop 0
	global_load_lds_dwordx4 v[226:227], off
	s_waitcnt vmcnt(8)
	s_waitcnt lgkmcnt(0)
	s_setprio 1
	s_barrier
; #define PG8_STAGE(bufoff, gbase, voff) do { _Pragma("unroll") for (int _i = 0; _i < 2; ++_i) \
;         __builtin_amdgcn_global_load_lds((const unsigned*)((const char*)(gbase) + (voff)[_i]), (PG8_LAS unsigned*)(lds + (bufoff) + ldsw + _i * 8192), 16, 0, 0); } while (0)
; #define PG8_LDA(dst, b, h) do { _Pragma("unroll") for (int m = 0; m < 4; ++m) _Pragma("unroll") for (int k = 0; k < 2; ++k) dst[m][k] = *(const PG8_LAS bf16x8*)(lds + PG8_SA(b, h) + aoff + m * 2048 + k * 1024); } while (0)
; #define PG8_LDB(dst, b, h) do { _Pragma("unroll") for (int n = 0; n < 2; ++n) _Pragma("unroll") for (int k = 0; k < 2; ++k) dst[n][k] = *(const PG8_LAS bf16x8*)(lds + PG8_SB(b, h) + boff + n * 2048 + k * 1024); } while (0)
; #define PG8_MMA(ai, bj, At, Bt) do { __builtin_amdgcn_s_setprio(1); _Pragma("unroll") for (int m = 0; m < 4; ++m) _Pragma("unroll") for (int n = 0; n < 2; ++n) _Pragma("unroll") for (int k = 0; k < 2; ++k) \
;         acc[ai][bj][m][n] = __builtin_amdgcn_mfma_f32_16x16x32_bf16(Bt[n][k], At[m][k], acc[ai][bj][m][n], 0, 0, 0); __builtin_amdgcn_s_setprio(0); } while (0)
; #define PG8_WAIT_V(n) asm volatile("s_waitcnt vmcnt(" #n ")" ::: "memory")
; #define PG8_WAIT_L(n) asm volatile("s_waitcnt lgkmcnt(" #n ")" ::: "memory")
; #define PG8_BAR __builtin_amdgcn_s_barrier()
; #define PG8_SCHED __builtin_amdgcn_sched_barrier(0)
; template <class Epi, class Sched, bool ALIGN_EPI = false, bool SP2 = false>
; __device__ __forceinline__ void gemm_phase(PG8_LAS unsigned char* lds, const Gemm g, const Sched& S, const Epi& E) {
;     ...
;             PG8_WAIT_V(8); PG8_WAIT_L(0); PG8_BAR; PG8_MMA(1, 0, At, B0); PG8_MMA(1, 1, At, B1); PG8_BAR; PG8_SCHED;
;             PG8_LDB(B0, 1, 0); PG8_LDB(B1, 1, 1); PG8_SCHED; PG8_LDA(At, 1, 0); PG8_STAGE(PG8_SA(0, 1), a2 + hstep, voffA);
;             PG8_WAIT_V(8); PG8_WAIT_L(0); PG8_BAR; PG8_MMA(0, 0, At, B0); PG8_MMA(0, 1, At, B1); PG8_BAR; PG8_SCHED;
	v_mfma_f32_16x16x32_bf16 v[60:63], v[148:151], v[188:191], v[60:63]
	v_mfma_f32_16x16x32_bf16 v[56:59], v[156:159], v[188:191], v[56:59]
	v_mfma_f32_16x16x32_bf16 v[52:55], v[148:151], v[196:199], v[52:55]
	v_mfma_f32_16x16x32_bf16 v[44:47], v[156:159], v[196:199], v[44:47]
	v_mfma_f32_16x16x32_bf16 v[36:39], v[148:151], v[204:207], v[36:39]
	v_mfma_f32_16x16x32_bf16 v[28:31], v[156:159], v[204:207], v[28:31]
	v_mfma_f32_16x16x32_bf16 v[20:23], v[148:151], v[212:215], v[20:23]
	v_mfma_f32_16x16x32_bf16 v[12:15], v[156:159], v[212:215], v[12:15]
	v_mfma_f32_16x16x32_bf16 v[60:63], v[152:155], v[192:195], v[60:63]
	v_mfma_f32_16x16x32_bf16 v[56:59], v[168:171], v[192:195], v[56:59]
	v_mfma_f32_16x16x32_bf16 v[52:55], v[152:155], v[200:203], v[52:55]
	v_mfma_f32_16x16x32_bf16 v[44:47], v[168:171], v[200:203], v[44:47]
	v_mfma_f32_16x16x32_bf16 v[36:39], v[152:155], v[208:211], v[36:39]
	v_mfma_f32_16x16x32_bf16 v[28:31], v[168:171], v[208:211], v[28:31]
	v_mfma_f32_16x16x32_bf16 v[20:23], v[152:155], v[216:219], v[20:23]
	v_mfma_f32_16x16x32_bf16 v[12:15], v[168:171], v[216:219], v[12:15]
	v_mfma_f32_16x16x32_bf16 v[48:51], v[172:175], v[188:191], v[48:51]
	v_mfma_f32_16x16x32_bf16 v[40:43], v[180:183], v[188:191], v[40:43]
	v_mfma_f32_16x16x32_bf16 v[32:35], v[172:175], v[196:199], v[32:35]
	v_mfma_f32_16x16x32_bf16 v[24:27], v[180:183], v[196:199], v[24:27]
	v_mfma_f32_16x16x32_bf16 v[16:19], v[172:175], v[204:207], v[16:19]
	v_mfma_f32_16x16x32_bf16 v[8:11], v[180:183], v[204:207], v[8:11]
	v_mfma_f32_16x16x32_bf16 v[4:7], v[172:175], v[212:215], v[4:7]
	v_mfma_f32_16x16x32_bf16 v[0:3], v[180:183], v[212:215], v[0:3]
	v_mfma_f32_16x16x32_bf16 v[48:51], v[176:179], v[192:195], v[48:51]
	v_mfma_f32_16x16x32_bf16 v[40:43], v[184:187], v[192:195], v[40:43]
	v_mfma_f32_16x16x32_bf16 v[32:35], v[176:179], v[200:203], v[32:35]
	v_mfma_f32_16x16x32_bf16 v[24:27], v[184:187], v[200:203], v[24:27]
	v_mfma_f32_16x16x32_bf16 v[16:19], v[176:179], v[208:211], v[16:19]
	v_mfma_f32_16x16x32_bf16 v[8:11], v[184:187], v[208:211], v[8:11]
	s_setprio 2
	s_barrier
	v_mfma_f32_16x16x32_bf16 v[4:7], v[176:179], v[216:219], v[4:7]
	v_mfma_f32_16x16x32_bf16 v[0:3], v[184:187], v[216:219], v[0:3]
	s_setprio 0
	s_add_i32 s52, 0, 0x18000
	v_add_u32_e32 v136, s52, v161
	s_add_i32 s53, 0, 0x1c000
	ds_read_b128 v[148:151], v136
	ds_read_b128 v[152:155], v136 offset:1024
	ds_read_b128 v[156:159], v136 offset:2048
	ds_read_b128 v[168:171], v136 offset:3072
	v_add_u32_e32 v136, s53, v161
	ds_read_b128 v[172:175], v136
	ds_read_b128 v[176:179], v136 offset:1024
	ds_read_b128 v[180:183], v136 offset:2048
	ds_read_b128 v[184:187], v136 offset:3072
	s_add_u32 s74, s74, 0x80000
	s_addc_u32 s75, s75, 0
	s_mov_b32 m0, s77
	v_lshl_add_u64 v[228:229], s[74:75], 0, v[134:135]
	ds_read_b128 v[188:191], v166 offset:32768
	ds_read_b128 v[192:195], v166 offset:33792
	ds_read_b128 v[196:199], v166 offset:34816
	ds_read_b128 v[200:203], v166 offset:35840
	ds_read_b128 v[204:207], v166 offset:36864
	ds_read_b128 v[208:211], v166 offset:37888
	ds_read_b128 v[212:215], v166 offset:38912
	ds_read_b128 v[216:219], v166 offset:39936
	global_load_lds_dwordx4 v[228:229], off
	v_lshl_add_u64 v[228:229], s[74:75], 0, v[130:131]
	s_mov_b32 m0, s78
	s_nop 0
	global_load_lds_dwordx4 v[228:229], off
	s_waitcnt vmcnt(8)
	s_waitcnt lgkmcnt(0)
	s_setprio 1
	s_barrier
	v_mfma_f32_16x16x32_bf16 v[124:127], v[148:151], v[188:191], v[124:127]
	v_mfma_f32_16x16x32_bf16 v[120:123], v[156:159], v[188:191], v[120:123]
	v_mfma_f32_16x16x32_bf16 v[116:119], v[148:151], v[196:199], v[116:119]
	v_mfma_f32_16x16x32_bf16 v[108:111], v[156:159], v[196:199], v[108:111]
	v_mfma_f32_16x16x32_bf16 v[100:103], v[148:151], v[204:207], v[100:103]
	v_mfma_f32_16x16x32_bf16 v[92:95], v[156:159], v[204:207], v[92:95]
	v_mfma_f32_16x16x32_bf16 v[84:87], v[148:151], v[212:215], v[84:87]
	v_mfma_f32_16x16x32_bf16 v[76:79], v[156:159], v[212:215], v[76:79]
	v_mfma_f32_16x16x32_bf16 v[124:127], v[152:155], v[192:195], v[124:127]
	v_mfma_f32_16x16x32_bf16 v[120:123], v[168:171], v[192:195], v[120:123]
	v_mfma_f32_16x16x32_bf16 v[116:119], v[152:155], v[200:203], v[116:119]
	v_mfma_f32_16x16x32_bf16 v[108:111], v[168:171], v[200:203], v[108:111]
	v_mfma_f32_16x16x32_bf16 v[100:103], v[152:155], v[208:211], v[100:103]
	v_mfma_f32_16x16x32_bf16 v[92:95], v[168:171], v[208:211], v[92:95]
	v_mfma_f32_16x16x32_bf16 v[84:87], v[152:155], v[216:219], v[84:87]
	v_mfma_f32_16x16x32_bf16 v[76:79], v[168:171], v[216:219], v[76:79]
	v_mfma_f32_16x16x32_bf16 v[112:115], v[172:175], v[188:191], v[112:115]
	v_mfma_f32_16x16x32_bf16 v[104:107], v[180:183], v[188:191], v[104:107]
	v_mfma_f32_16x16x32_bf16 v[96:99], v[172:175], v[196:199], v[96:99]
	v_mfma_f32_16x16x32_bf16 v[88:91], v[180:183], v[196:199], v[88:91]
	v_mfma_f32_16x16x32_bf16 v[80:83], v[172:175], v[204:207], v[80:83]
	v_mfma_f32_16x16x32_bf16 v[72:75], v[180:183], v[204:207], v[72:75]
	v_mfma_f32_16x16x32_bf16 v[68:71], v[172:175], v[212:215], v[68:71]
	v_mfma_f32_16x16x32_bf16 v[64:67], v[180:183], v[212:215], v[64:67]
	v_mfma_f32_16x16x32_bf16 v[112:115], v[176:179], v[192:195], v[112:115]
	v_mfma_f32_16x16x32_bf16 v[104:107], v[184:187], v[192:195], v[104:107]
	v_mfma_f32_16x16x32_bf16 v[96:99], v[176:179], v[200:203], v[96:99]
	v_mfma_f32_16x16x32_bf16 v[88:91], v[184:187], v[200:203], v[88:91]
	v_mfma_f32_16x16x32_bf16 v[80:83], v[176:179], v[208:211], v[80:83]
	v_mfma_f32_16x16x32_bf16 v[72:75], v[184:187], v[208:211], v[72:75]
	s_setprio 2
	s_barrier
; #define PG8_STAGE(bufoff, gbase, voff) do { _Pragma("unroll") for (int _i = 0; _i < 2; ++_i) \
;         __builtin_amdgcn_global_load_lds((const unsigned*)((const char*)(gbase) + (voff)[_i]), (PG8_LAS unsigned*)(lds + (bufoff) + ldsw + _i * 8192), 16, 0, 0); } while (0)
; #define PG8_LDA(dst, b, h) do { _Pragma("unroll") for (int m = 0; m < 4; ++m) _Pragma("unroll") for (int k = 0; k < 2; ++k) dst[m][k] = *(const PG8_LAS bf16x8*)(lds + PG8_SA(b, h) + aoff + m * 2048 + k * 1024); } while (0)
; #define PG8_MMA(ai, bj, At, Bt) do { __builtin_amdgcn_s_setprio(1); _Pragma("unroll") for (int m = 0; m < 4; ++m) _Pragma("unroll") for (int n = 0; n < 2; ++n) _Pragma("unroll") for (int k = 0; k < 2; ++k) \
;         acc[ai][bj][m][n] = __builtin_amdgcn_mfma_f32_16x16x32_bf16(Bt[n][k], At[m][k], acc[ai][bj][m][n], 0, 0, 0); __builtin_amdgcn_s_setprio(0); } while (0)
; #define PG8_WAIT_V(n) asm volatile("s_waitcnt vmcnt(" #n ")" ::: "memory")
; #define PG8_WAIT_L(n) asm volatile("s_waitcnt lgkmcnt(" #n ")" ::: "memory")
; #define PG8_BAR __builtin_amdgcn_s_barrier()
; #define PG8_SCHED __builtin_amdgcn_sched_barrier(0)
; template <class Epi, class Sched, bool ALIGN_EPI = false, bool SP2 = false>
; __device__ __forceinline__ void gemm_phase(PG8_LAS unsigned char* lds, const Gemm g, const Sched& S, const Epi& E) {
;     ...
;             PG8_WAIT_V(8); PG8_WAIT_L(0); PG8_BAR; PG8_MMA(0, 0, At, B0); PG8_MMA(0, 1, At, B1); PG8_BAR; PG8_SCHED;
;             PG8_LDA(At, 1, 1); PG8_STAGE(PG8_SB(1, 0), b3, voffB); PG8_STAGE(PG8_SB(1, 1), b3 + hstep, voffB); PG8_STAGE(PG8_SA(1, 0), a3, voffA);
;             PG8_WAIT_V(8); PG8_WAIT_L(0); PG8_BAR; PG8_MMA(1, 0, At, B0); PG8_MMA(1, 1, At, B1); PG8_BAR; PG8_SCHED;
;     ...
;         if constexpr (ALIGN_EPI) { if (wr == 0) PG8_BAR; }
	v_mfma_f32_16x16x32_bf16 v[68:71], v[176:179], v[216:219], v[68:71]
	v_mfma_f32_16x16x32_bf16 v[64:67], v[184:187], v[216:219], v[64:67]
	s_setprio 0
	s_add_i32 s52, s52, s3
	v_lshl_add_u64 v[220:221], v[220:221], 0, s[12:13]
	s_mov_b32 m0, s52
	ds_read_b128 v[188:191], v166 offset:49152
	ds_read_b128 v[192:195], v166 offset:50176
	ds_read_b128 v[196:199], v166 offset:51200
	ds_read_b128 v[200:203], v166 offset:52224
	ds_read_b128 v[204:207], v166 offset:53248
	ds_read_b128 v[208:211], v166 offset:54272
	ds_read_b128 v[212:215], v166 offset:55296
	ds_read_b128 v[216:219], v166 offset:56320
	global_load_lds_dwordx4 v[220:221], off
	s_add_i32 m0, s52, 0x2000
	s_add_u32 s72, s72, 0x80080
	v_lshl_add_u64 v[220:221], v[222:223], 0, s[12:13]
	s_addc_u32 s73, s73, 0
	s_add_i32 s52, s53, s3
	global_load_lds_dwordx4 v[220:221], off
	v_lshl_add_u64 v[220:221], s[72:73], 0, v[132:133]
	s_mov_b32 m0, s52
	s_nop 0
	global_load_lds_dwordx4 v[220:221], off
	v_lshl_add_u64 v[220:221], s[72:73], 0, v[128:129]
	s_add_i32 m0, s52, 0x2000
	s_nop 0
	global_load_lds_dwordx4 v[220:221], off
	v_lshl_add_u64 v[220:221], v[224:225], 0, s[12:13]
	s_mov_b32 m0, s80
	s_nop 0
	global_load_lds_dwordx4 v[220:221], off
	v_lshl_add_u64 v[220:221], v[226:227], 0, s[12:13]
	s_mov_b32 m0, s81
	s_nop 0
	global_load_lds_dwordx4 v[220:221], off
	s_waitcnt vmcnt(8)
	s_waitcnt lgkmcnt(0)
	s_setprio 1
	s_barrier
	v_mfma_f32_16x16x32_bf16 v[60:63], v[148:151], v[188:191], v[60:63]
	v_mfma_f32_16x16x32_bf16 v[56:59], v[156:159], v[188:191], v[56:59]
	v_mfma_f32_16x16x32_bf16 v[52:55], v[148:151], v[196:199], v[52:55]
	v_mfma_f32_16x16x32_bf16 v[44:47], v[156:159], v[196:199], v[44:47]
	v_mfma_f32_16x16x32_bf16 v[36:39], v[148:151], v[204:207], v[36:39]
	v_mfma_f32_16x16x32_bf16 v[28:31], v[156:159], v[204:207], v[28:31]
	v_mfma_f32_16x16x32_bf16 v[20:23], v[148:151], v[212:215], v[20:23]
	v_mfma_f32_16x16x32_bf16 v[12:15], v[156:159], v[212:215], v[12:15]
	v_mfma_f32_16x16x32_bf16 v[60:63], v[152:155], v[192:195], v[60:63]
	v_mfma_f32_16x16x32_bf16 v[56:59], v[168:171], v[192:195], v[56:59]
	v_mfma_f32_16x16x32_bf16 v[52:55], v[152:155], v[200:203], v[52:55]
	v_mfma_f32_16x16x32_bf16 v[44:47], v[168:171], v[200:203], v[44:47]
	v_mfma_f32_16x16x32_bf16 v[36:39], v[152:155], v[208:211], v[36:39]
	v_mfma_f32_16x16x32_bf16 v[28:31], v[168:171], v[208:211], v[28:31]
	v_mfma_f32_16x16x32_bf16 v[20:23], v[152:155], v[216:219], v[20:23]
	v_mfma_f32_16x16x32_bf16 v[12:15], v[168:171], v[216:219], v[12:15]
	v_mfma_f32_16x16x32_bf16 v[48:51], v[172:175], v[188:191], v[48:51]
	v_mfma_f32_16x16x32_bf16 v[40:43], v[180:183], v[188:191], v[40:43]
	v_mfma_f32_16x16x32_bf16 v[32:35], v[172:175], v[196:199], v[32:35]
	v_mfma_f32_16x16x32_bf16 v[24:27], v[180:183], v[196:199], v[24:27]
	v_mfma_f32_16x16x32_bf16 v[16:19], v[172:175], v[204:207], v[16:19]
	v_mfma_f32_16x16x32_bf16 v[8:11], v[180:183], v[204:207], v[8:11]
	v_mfma_f32_16x16x32_bf16 v[4:7], v[172:175], v[212:215], v[4:7]
	v_mfma_f32_16x16x32_bf16 v[0:3], v[180:183], v[212:215], v[0:3]
	v_mfma_f32_16x16x32_bf16 v[48:51], v[176:179], v[192:195], v[48:51]
	v_mfma_f32_16x16x32_bf16 v[40:43], v[184:187], v[192:195], v[40:43]
	v_mfma_f32_16x16x32_bf16 v[32:35], v[176:179], v[200:203], v[32:35]
	v_mfma_f32_16x16x32_bf16 v[24:27], v[184:187], v[200:203], v[24:27]
	v_mfma_f32_16x16x32_bf16 v[16:19], v[176:179], v[208:211], v[16:19]
	v_mfma_f32_16x16x32_bf16 v[8:11], v[184:187], v[208:211], v[8:11]
	s_setprio 2
	s_barrier
	v_mfma_f32_16x16x32_bf16 v[4:7], v[176:179], v[216:219], v[4:7]
	v_mfma_f32_16x16x32_bf16 v[0:3], v[184:187], v[216:219], v[0:3]
	s_setprio 0
	s_add_i32 s93, s93, 2
	s_add_u32 s70, s70, 0x100
	s_addc_u32 s71, s71, 0
	s_add_u32 s91, s91, 0x100
	s_addc_u32 s92, s92, 0
	s_cmp_gt_u32 s93, 29
	s_cbranch_scc0 .LBB0_200
	s_and_b64 vcc, exec, s[14:15]
	s_cbranch_vccz .LBB0_203
	s_barrier

; #define PG8_STAGE(bufoff, gbase, voff) do { _Pragma("unroll") for (int _i = 0; _i < 2; ++_i) \
;         __builtin_amdgcn_global_load_lds((const unsigned*)((const char*)(gbase) + (voff)[_i]), (PG8_LAS unsigned*)(lds + (bufoff) + ldsw + _i * 8192), 16, 0, 0); } while (0)
; #define PG8_LDA(dst, b, h) do { _Pragma("unroll") for (int m = 0; m < 4; ++m) _Pragma("unroll") for (int k = 0; k < 2; ++k) dst[m][k] = *(const PG8_LAS bf16x8*)(lds + PG8_SA(b, h) + aoff + m * 2048 + k * 1024); } while (0)
; #define PG8_LDB(dst, b, h) do { _Pragma("unroll") for (int n = 0; n < 2; ++n) _Pragma("unroll") for (int k = 0; k < 2; ++k) dst[n][k] = *(const PG8_LAS bf16x8*)(lds + PG8_SB(b, h) + boff + n * 2048 + k * 1024); } while (0)
; #define PG8_MMA(ai, bj, At, Bt) do { __builtin_amdgcn_s_setprio(1); _Pragma("unroll") for (int m = 0; m < 4; ++m) _Pragma("unroll") for (int n = 0; n < 2; ++n) _Pragma("unroll") for (int k = 0; k < 2; ++k) \
;         acc[ai][bj][m][n] = __builtin_amdgcn_mfma_f32_16x16x32_bf16(Bt[n][k], At[m][k], acc[ai][bj][m][n], 0, 0, 0); __builtin_amdgcn_s_setprio(0); } while (0)
; #define PG8_WAIT_V(n) asm volatile("s_waitcnt vmcnt(" #n ")" ::: "memory")
; #define PG8_WAIT_L(n) asm volatile("s_waitcnt lgkmcnt(" #n ")" ::: "memory")
; #define PG8_BAR __builtin_amdgcn_s_barrier()
; template <class Epi, class Sched, bool ALIGN_EPI = false, bool SP2 = false>
; __device__ __forceinline__ void gemm_phase(PG8_LAS unsigned char* lds, const Gemm g, const Sched& S, const Epi& E) {
;     ...
;         for (int t = 0; t < nt; t += 2) {
;             const bool last = (t == nt - 2);
;             const char* a1 = cA + (size_t)(t + 1) * kstep;
;             const char* a2 = last ? nA : cA + (size_t)(t + 2) * kstep; const char* b2 = last ? nB : cB + (size_t)(t + 2) * kstep;
;             const char* a3 = a2 + kstep; const char* b3 = b2 + kstep;
;             if constexpr (SP2) {
;             PG8_LDB(B0, 0, 0); PG8_LDB(B1, 0, 1); PG8_SCHED; PG8_LDA(At, 0, 0); PG8_STAGE(PG8_SA(1, 1), a1 + hstep, voffA);
;             PG8_WAIT_V(8); PG8_WAIT_L(0); PG8_BAR; PG8_MMA(0, 0, At, B0); PG8_MMA(0, 1, At, B1); PG8_BAR; PG8_SCHED;
;             PG8_LDA(At, 0, 1); PG8_STAGE(PG8_SB(0, 0), b2, voffB); PG8_STAGE(PG8_SB(0, 1), b2 + hstep, voffB); PG8_STAGE(PG8_SA(0, 0), a2, voffA);
;             PG8_WAIT_V(8); PG8_WAIT_L(0); PG8_BAR; PG8_MMA(1, 0, At, B0); PG8_MMA(1, 1, At, B1); PG8_BAR; PG8_SCHED;
.LBB0_374:
	ds_read_b128 v[128:131], v230
	ds_read_b128 v[132:135], v230 offset:1024
	ds_read_b128 v[158:161], v230 offset:2048
	ds_read_b128 v[162:165], v230 offset:3072
	ds_read_b128 v[166:169], v231
	ds_read_b128 v[170:173], v231 offset:1024
	ds_read_b128 v[174:177], v231 offset:2048
	ds_read_b128 v[178:181], v231 offset:3072
	s_add_u32 s52, s76, 0xfff80080
	s_addc_u32 s53, s77, -1
	s_cmp_eq_u32 vcc_hi, 28
	s_cselect_b32 s81, s11, s53
	s_cselect_b32 s80, s55, s52
	s_cselect_b32 s79, s51, vcc_lo
	s_cselect_b32 s78, s73, s75
	v_lshl_add_u64 v[214:215], s[76:77], 0, v[150:151]
	s_add_i32 m0, s28, 0xc000
	ds_read_b128 v[182:185], v232
	ds_read_b128 v[186:189], v232 offset:1024
	ds_read_b128 v[190:193], v232 offset:2048
	ds_read_b128 v[194:197], v232 offset:3072
	ds_read_b128 v[198:201], v232 offset:4096
	ds_read_b128 v[202:205], v232 offset:5120
	ds_read_b128 v[206:209], v232 offset:6144
	ds_read_b128 v[210:213], v232 offset:7168
	global_load_lds_dwordx4 v[214:215], off
	v_lshl_add_u64 v[214:215], s[76:77], 0, v[152:153]
	s_add_i32 m0, s28, 0xe000
	s_nop 0
	global_load_lds_dwordx4 v[214:215], off
	s_waitcnt vmcnt(8)
	s_waitcnt lgkmcnt(0)
	s_setprio 1
	s_barrier
	v_mfma_f32_16x16x32_bf16 v[124:127], v[128:131], v[182:185], v[124:127]
	v_mfma_f32_16x16x32_bf16 v[120:123], v[158:161], v[182:185], v[120:123]
	v_mfma_f32_16x16x32_bf16 v[116:119], v[128:131], v[190:193], v[116:119]
	v_mfma_f32_16x16x32_bf16 v[112:115], v[158:161], v[190:193], v[112:115]
	v_mfma_f32_16x16x32_bf16 v[108:111], v[128:131], v[198:201], v[108:111]
	v_mfma_f32_16x16x32_bf16 v[104:107], v[158:161], v[198:201], v[104:107]
	v_mfma_f32_16x16x32_bf16 v[100:103], v[128:131], v[206:209], v[100:103]
	v_mfma_f32_16x16x32_bf16 v[96:99], v[158:161], v[206:209], v[96:99]
	v_mfma_f32_16x16x32_bf16 v[124:127], v[132:135], v[186:189], v[124:127]
	v_mfma_f32_16x16x32_bf16 v[120:123], v[162:165], v[186:189], v[120:123]
	v_mfma_f32_16x16x32_bf16 v[116:119], v[132:135], v[194:197], v[116:119]
	v_mfma_f32_16x16x32_bf16 v[112:115], v[162:165], v[194:197], v[112:115]
	v_mfma_f32_16x16x32_bf16 v[108:111], v[132:135], v[202:205], v[108:111]
	v_mfma_f32_16x16x32_bf16 v[104:107], v[162:165], v[202:205], v[104:107]
	v_mfma_f32_16x16x32_bf16 v[100:103], v[132:135], v[210:213], v[100:103]
	v_mfma_f32_16x16x32_bf16 v[96:99], v[162:165], v[210:213], v[96:99]
	v_mfma_f32_16x16x32_bf16 v[60:63], v[166:169], v[182:185], v[60:63]
	v_mfma_f32_16x16x32_bf16 v[56:59], v[174:177], v[182:185], v[56:59]
	v_mfma_f32_16x16x32_bf16 v[52:55], v[166:169], v[190:193], v[52:55]
	v_mfma_f32_16x16x32_bf16 v[48:51], v[174:177], v[190:193], v[48:51]
	v_mfma_f32_16x16x32_bf16 v[44:47], v[166:169], v[198:201], v[44:47]
	v_mfma_f32_16x16x32_bf16 v[40:43], v[174:177], v[198:201], v[40:43]
	v_mfma_f32_16x16x32_bf16 v[36:39], v[166:169], v[206:209], v[36:39]
	v_mfma_f32_16x16x32_bf16 v[32:35], v[174:177], v[206:209], v[32:35]
	v_mfma_f32_16x16x32_bf16 v[60:63], v[170:173], v[186:189], v[60:63]
	v_mfma_f32_16x16x32_bf16 v[56:59], v[178:181], v[186:189], v[56:59]
	v_mfma_f32_16x16x32_bf16 v[52:55], v[170:173], v[194:197], v[52:55]
	v_mfma_f32_16x16x32_bf16 v[48:51], v[178:181], v[194:197], v[48:51]
	v_mfma_f32_16x16x32_bf16 v[44:47], v[170:173], v[202:205], v[44:47]
	v_mfma_f32_16x16x32_bf16 v[40:43], v[178:181], v[202:205], v[40:43]
	s_setprio 2
	s_barrier
	v_mfma_f32_16x16x32_bf16 v[36:39], v[170:173], v[210:213], v[36:39]
	v_mfma_f32_16x16x32_bf16 v[32:35], v[178:181], v[210:213], v[32:35]
	s_setprio 0
	s_add_i32 s52, s93, s3
	v_lshl_add_u64 v[214:215], s[78:79], 0, v[138:139]
	s_mov_b32 m0, s52
	ds_read_b128 v[182:185], v232 offset:16384
	ds_read_b128 v[186:189], v232 offset:17408
	ds_read_b128 v[190:193], v232 offset:18432
	ds_read_b128 v[194:197], v232 offset:19456
	ds_read_b128 v[198:201], v232 offset:20480
	ds_read_b128 v[202:205], v232 offset:21504
	ds_read_b128 v[206:209], v232 offset:22528
	ds_read_b128 v[210:213], v232 offset:23552
	global_load_lds_dwordx4 v[214:215], off
	s_add_i32 m0, s52, 0x2000
	s_add_u32 s52, s78, 0x80000
	v_lshl_add_u64 v[216:217], s[78:79], 0, v[142:143]
	s_addc_u32 s53, s79, 0
	s_add_i32 s56, s10, s3
	global_load_lds_dwordx4 v[216:217], off
	v_lshl_add_u64 v[218:219], s[52:53], 0, v[138:139]
	s_mov_b32 m0, s56
	v_lshl_add_u64 v[220:221], s[80:81], 0, v[140:141]
	global_load_lds_dwordx4 v[218:219], off
	v_lshl_add_u64 v[218:219], s[52:53], 0, v[142:143]
	s_add_i32 m0, s56, 0x2000
	s_nop 0
	global_load_lds_dwordx4 v[218:219], off
	v_lshl_add_u64 v[218:219], s[80:81], 0, v[136:137]
	s_mov_b32 m0, s28
	s_nop 0
	global_load_lds_dwordx4 v[218:219], off
	s_mov_b32 m0, s29
	s_nop 0
	global_load_lds_dwordx4 v[220:221], off
	s_waitcnt vmcnt(8)
	s_waitcnt lgkmcnt(0)
	s_setprio 1
	s_barrier
; #define PG8_STAGE(bufoff, gbase, voff) do { _Pragma("unroll") for (int _i = 0; _i < 2; ++_i) \
;         __builtin_amdgcn_global_load_lds((const unsigned*)((const char*)(gbase) + (voff)[_i]), (PG8_LAS unsigned*)(lds + (bufoff) + ldsw + _i * 8192), 16, 0, 0); } while (0)
; #define PG8_LDA(dst, b, h) do { _Pragma("unroll") for (int m = 0; m < 4; ++m) _Pragma("unroll") for (int k = 0; k < 2; ++k) dst[m][k] = *(const PG8_LAS bf16x8*)(lds + PG8_SA(b, h) + aoff + m * 2048 + k * 1024); } while (0)
; #define PG8_LDB(dst, b, h) do { _Pragma("unroll") for (int n = 0; n < 2; ++n) _Pragma("unroll") for (int k = 0; k < 2; ++k) dst[n][k] = *(const PG8_LAS bf16x8*)(lds + PG8_SB(b, h) + boff + n * 2048 + k * 1024); } while (0)
; #define PG8_MMA(ai, bj, At, Bt) do { __builtin_amdgcn_s_setprio(1); _Pragma("unroll") for (int m = 0; m < 4; ++m) _Pragma("unroll") for (int n = 0; n < 2; ++n) _Pragma("unroll") for (int k = 0; k < 2; ++k) \
;         acc[ai][bj][m][n] = __builtin_amdgcn_mfma_f32_16x16x32_bf16(Bt[n][k], At[m][k], acc[ai][bj][m][n], 0, 0, 0); __builtin_amdgcn_s_setprio(0); } while (0)
; #define PG8_WAIT_V(n) asm volatile("s_waitcnt vmcnt(" #n ")" ::: "memory")
; #define PG8_WAIT_L(n) asm volatile("s_waitcnt lgkmcnt(" #n ")" ::: "memory")
; #define PG8_BAR __builtin_amdgcn_s_barrier()
; #define PG8_SCHED __builtin_amdgcn_sched_barrier(0)
; template <class Epi, class Sched, bool ALIGN_EPI = false, bool SP2 = false>
; __device__ __forceinline__ void gemm_phase(PG8_LAS unsigned char* lds, const Gemm g, const Sched& S, const Epi& E) {
;     ...
;             PG8_WAIT_V(8); PG8_WAIT_L(0); PG8_BAR; PG8_MMA(1, 0, At, B0); PG8_MMA(1, 1, At, B1); PG8_BAR; PG8_SCHED;
;             PG8_LDB(B0, 1, 0); PG8_LDB(B1, 1, 1); PG8_SCHED; PG8_LDA(At, 1, 0); PG8_STAGE(PG8_SA(0, 1), a2 + hstep, voffA);
;             PG8_WAIT_V(8); PG8_WAIT_L(0); PG8_BAR; PG8_MMA(0, 0, At, B0); PG8_MMA(0, 1, At, B1); PG8_BAR; PG8_SCHED;
	v_mfma_f32_16x16x32_bf16 v[92:95], v[128:131], v[182:185], v[92:95]
	v_mfma_f32_16x16x32_bf16 v[88:91], v[158:161], v[182:185], v[88:91]
	v_mfma_f32_16x16x32_bf16 v[84:87], v[128:131], v[190:193], v[84:87]
	v_mfma_f32_16x16x32_bf16 v[80:83], v[158:161], v[190:193], v[80:83]
	v_mfma_f32_16x16x32_bf16 v[76:79], v[128:131], v[198:201], v[76:79]
	v_mfma_f32_16x16x32_bf16 v[72:75], v[158:161], v[198:201], v[72:75]
	v_mfma_f32_16x16x32_bf16 v[68:71], v[128:131], v[206:209], v[68:71]
	v_mfma_f32_16x16x32_bf16 v[64:67], v[158:161], v[206:209], v[64:67]
	v_mfma_f32_16x16x32_bf16 v[92:95], v[132:135], v[186:189], v[92:95]
	v_mfma_f32_16x16x32_bf16 v[88:91], v[162:165], v[186:189], v[88:91]
	v_mfma_f32_16x16x32_bf16 v[84:87], v[132:135], v[194:197], v[84:87]
	v_mfma_f32_16x16x32_bf16 v[80:83], v[162:165], v[194:197], v[80:83]
	v_mfma_f32_16x16x32_bf16 v[76:79], v[132:135], v[202:205], v[76:79]
	v_mfma_f32_16x16x32_bf16 v[72:75], v[162:165], v[202:205], v[72:75]
	v_mfma_f32_16x16x32_bf16 v[68:71], v[132:135], v[210:213], v[68:71]
	v_mfma_f32_16x16x32_bf16 v[64:67], v[162:165], v[210:213], v[64:67]
	v_mfma_f32_16x16x32_bf16 v[28:31], v[166:169], v[182:185], v[28:31]
	v_mfma_f32_16x16x32_bf16 v[24:27], v[174:177], v[182:185], v[24:27]
	v_mfma_f32_16x16x32_bf16 v[20:23], v[166:169], v[190:193], v[20:23]
	v_mfma_f32_16x16x32_bf16 v[16:19], v[174:177], v[190:193], v[16:19]
	v_mfma_f32_16x16x32_bf16 v[12:15], v[166:169], v[198:201], v[12:15]
	v_mfma_f32_16x16x32_bf16 v[8:11], v[174:177], v[198:201], v[8:11]
	v_mfma_f32_16x16x32_bf16 v[4:7], v[166:169], v[206:209], v[4:7]
	v_mfma_f32_16x16x32_bf16 v[0:3], v[174:177], v[206:209], v[0:3]
	v_mfma_f32_16x16x32_bf16 v[28:31], v[170:173], v[186:189], v[28:31]
	v_mfma_f32_16x16x32_bf16 v[24:27], v[178:181], v[186:189], v[24:27]
	v_mfma_f32_16x16x32_bf16 v[20:23], v[170:173], v[194:197], v[20:23]
	v_mfma_f32_16x16x32_bf16 v[16:19], v[178:181], v[194:197], v[16:19]
	v_mfma_f32_16x16x32_bf16 v[12:15], v[170:173], v[202:205], v[12:15]
	v_mfma_f32_16x16x32_bf16 v[8:11], v[178:181], v[202:205], v[8:11]
	s_setprio 2
	s_barrier
	v_mfma_f32_16x16x32_bf16 v[4:7], v[170:173], v[210:213], v[4:7]
	v_mfma_f32_16x16x32_bf16 v[0:3], v[178:181], v[210:213], v[0:3]
	s_setprio 0
	s_add_i32 s56, 0, 0x18000
	s_add_i32 s57, 0, 0x1c000
	v_add_u32_e32 v162, s56, v228
	v_add_u32_e32 v178, s57, v228
	ds_read_b128 v[128:131], v162
	ds_read_b128 v[132:135], v162 offset:1024
	ds_read_b128 v[158:161], v162 offset:2048
	ds_read_b128 v[162:165], v162 offset:3072
	ds_read_b128 v[166:169], v178
	ds_read_b128 v[170:173], v178 offset:1024
	ds_read_b128 v[174:177], v178 offset:2048
	ds_read_b128 v[178:181], v178 offset:3072
	s_add_u32 s52, s80, 0x80000
	s_addc_u32 s53, s81, 0
	s_mov_b32 m0, s33
	v_lshl_add_u64 v[234:235], s[52:53], 0, v[136:137]
	ds_read_b128 v[182:185], v232 offset:32768
	ds_read_b128 v[186:189], v232 offset:33792
	ds_read_b128 v[190:193], v232 offset:34816
	ds_read_b128 v[194:197], v232 offset:35840
	ds_read_b128 v[198:201], v232 offset:36864
	ds_read_b128 v[202:205], v232 offset:37888
	ds_read_b128 v[206:209], v232 offset:38912
	ds_read_b128 v[210:213], v232 offset:39936
	global_load_lds_dwordx4 v[234:235], off
	v_lshl_add_u64 v[234:235], s[52:53], 0, v[140:141]
	s_mov_b32 m0, s38
	s_nop 0
	global_load_lds_dwordx4 v[234:235], off
	s_waitcnt vmcnt(8)
	s_waitcnt lgkmcnt(0)
	s_setprio 1
	s_barrier
	v_mfma_f32_16x16x32_bf16 v[124:127], v[128:131], v[182:185], v[124:127]
	v_mfma_f32_16x16x32_bf16 v[120:123], v[158:161], v[182:185], v[120:123]
	v_mfma_f32_16x16x32_bf16 v[116:119], v[128:131], v[190:193], v[116:119]
	v_mfma_f32_16x16x32_bf16 v[112:115], v[158:161], v[190:193], v[112:115]
	v_mfma_f32_16x16x32_bf16 v[108:111], v[128:131], v[198:201], v[108:111]
	v_mfma_f32_16x16x32_bf16 v[104:107], v[158:161], v[198:201], v[104:107]
	v_mfma_f32_16x16x32_bf16 v[100:103], v[128:131], v[206:209], v[100:103]
	v_mfma_f32_16x16x32_bf16 v[96:99], v[158:161], v[206:209], v[96:99]
	v_mfma_f32_16x16x32_bf16 v[124:127], v[132:135], v[186:189], v[124:127]
	v_mfma_f32_16x16x32_bf16 v[120:123], v[162:165], v[186:189], v[120:123]
	v_mfma_f32_16x16x32_bf16 v[116:119], v[132:135], v[194:197], v[116:119]
	v_mfma_f32_16x16x32_bf16 v[112:115], v[162:165], v[194:197], v[112:115]
	v_mfma_f32_16x16x32_bf16 v[108:111], v[132:135], v[202:205], v[108:111]
	v_mfma_f32_16x16x32_bf16 v[104:107], v[162:165], v[202:205], v[104:107]
	v_mfma_f32_16x16x32_bf16 v[100:103], v[132:135], v[210:213], v[100:103]
	v_mfma_f32_16x16x32_bf16 v[96:99], v[162:165], v[210:213], v[96:99]
	v_mfma_f32_16x16x32_bf16 v[60:63], v[166:169], v[182:185], v[60:63]
	v_mfma_f32_16x16x32_bf16 v[56:59], v[174:177], v[182:185], v[56:59]
	v_mfma_f32_16x16x32_bf16 v[52:55], v[166:169], v[190:193], v[52:55]
	v_mfma_f32_16x16x32_bf16 v[48:51], v[174:177], v[190:193], v[48:51]
	v_mfma_f32_16x16x32_bf16 v[44:47], v[166:169], v[198:201], v[44:47]
	v_mfma_f32_16x16x32_bf16 v[40:43], v[174:177], v[198:201], v[40:43]
	v_mfma_f32_16x16x32_bf16 v[36:39], v[166:169], v[206:209], v[36:39]
	v_mfma_f32_16x16x32_bf16 v[32:35], v[174:177], v[206:209], v[32:35]
	v_mfma_f32_16x16x32_bf16 v[60:63], v[170:173], v[186:189], v[60:63]
	v_mfma_f32_16x16x32_bf16 v[56:59], v[178:181], v[186:189], v[56:59]
	v_mfma_f32_16x16x32_bf16 v[52:55], v[170:173], v[194:197], v[52:55]
	v_mfma_f32_16x16x32_bf16 v[48:51], v[178:181], v[194:197], v[48:51]
	v_mfma_f32_16x16x32_bf16 v[44:47], v[170:173], v[202:205], v[44:47]
	v_mfma_f32_16x16x32_bf16 v[40:43], v[178:181], v[202:205], v[40:43]
	s_setprio 2
	s_barrier
; #define PG8_STAGE(bufoff, gbase, voff) do { _Pragma("unroll") for (int _i = 0; _i < 2; ++_i) \
;         __builtin_amdgcn_global_load_lds((const unsigned*)((const char*)(gbase) + (voff)[_i]), (PG8_LAS unsigned*)(lds + (bufoff) + ldsw + _i * 8192), 16, 0, 0); } while (0)
; #define PG8_LDA(dst, b, h) do { _Pragma("unroll") for (int m = 0; m < 4; ++m) _Pragma("unroll") for (int k = 0; k < 2; ++k) dst[m][k] = *(const PG8_LAS bf16x8*)(lds + PG8_SA(b, h) + aoff + m * 2048 + k * 1024); } while (0)
; #define PG8_MMA(ai, bj, At, Bt) do { __builtin_amdgcn_s_setprio(1); _Pragma("unroll") for (int m = 0; m < 4; ++m) _Pragma("unroll") for (int n = 0; n < 2; ++n) _Pragma("unroll") for (int k = 0; k < 2; ++k) \
;         acc[ai][bj][m][n] = __builtin_amdgcn_mfma_f32_16x16x32_bf16(Bt[n][k], At[m][k], acc[ai][bj][m][n], 0, 0, 0); __builtin_amdgcn_s_setprio(0); } while (0)
; #define PG8_WAIT_V(n) asm volatile("s_waitcnt vmcnt(" #n ")" ::: "memory")
; #define PG8_WAIT_L(n) asm volatile("s_waitcnt lgkmcnt(" #n ")" ::: "memory")
; #define PG8_BAR __builtin_amdgcn_s_barrier()
; #define PG8_SCHED __builtin_amdgcn_sched_barrier(0)
; template <class Epi, class Sched, bool ALIGN_EPI = false, bool SP2 = false>
; __device__ __forceinline__ void gemm_phase(PG8_LAS unsigned char* lds, const Gemm g, const Sched& S, const Epi& E) {
;     ...
;             PG8_WAIT_V(8); PG8_WAIT_L(0); PG8_BAR; PG8_MMA(0, 0, At, B0); PG8_MMA(0, 1, At, B1); PG8_BAR; PG8_SCHED;
;             PG8_LDA(At, 1, 1); PG8_STAGE(PG8_SB(1, 0), b3, voffB); PG8_STAGE(PG8_SB(1, 1), b3 + hstep, voffB); PG8_STAGE(PG8_SA(1, 0), a3, voffA);
;             PG8_WAIT_V(8); PG8_WAIT_L(0); PG8_BAR; PG8_MMA(1, 0, At, B0); PG8_MMA(1, 1, At, B1); PG8_BAR; PG8_SCHED;
;     ...
;         if constexpr (ALIGN_EPI) { if (wr == 0) PG8_BAR; }
	v_mfma_f32_16x16x32_bf16 v[36:39], v[170:173], v[210:213], v[36:39]
	v_mfma_f32_16x16x32_bf16 v[32:35], v[178:181], v[210:213], v[32:35]
	s_setprio 0
	s_add_i32 s52, s56, s3
	v_lshl_add_u64 v[214:215], v[214:215], 0, s[14:15]
	s_mov_b32 m0, s52
	ds_read_b128 v[182:185], v232 offset:49152
	ds_read_b128 v[186:189], v232 offset:50176
	ds_read_b128 v[190:193], v232 offset:51200
	ds_read_b128 v[194:197], v232 offset:52224
	ds_read_b128 v[198:201], v232 offset:53248
	ds_read_b128 v[202:205], v232 offset:54272
	ds_read_b128 v[206:209], v232 offset:55296
	ds_read_b128 v[210:213], v232 offset:56320
	global_load_lds_dwordx4 v[214:215], off
	s_add_i32 m0, s52, 0x2000
	s_add_u32 s52, s78, 0x80080
	v_lshl_add_u64 v[214:215], v[216:217], 0, s[14:15]
	s_addc_u32 s53, s79, 0
	s_add_i32 s56, s57, s3
	global_load_lds_dwordx4 v[214:215], off
	v_lshl_add_u64 v[214:215], s[52:53], 0, v[138:139]
	s_mov_b32 m0, s56
	s_nop 0
	global_load_lds_dwordx4 v[214:215], off
	v_lshl_add_u64 v[214:215], s[52:53], 0, v[142:143]
	s_add_i32 m0, s56, 0x2000
	s_nop 0
	global_load_lds_dwordx4 v[214:215], off
	v_lshl_add_u64 v[214:215], v[218:219], 0, s[14:15]
	s_mov_b32 m0, s88
	s_nop 0
	global_load_lds_dwordx4 v[214:215], off
	v_lshl_add_u64 v[214:215], v[220:221], 0, s[14:15]
	s_mov_b32 m0, s89
	s_nop 0
	global_load_lds_dwordx4 v[214:215], off
	s_waitcnt vmcnt(8)
	s_waitcnt lgkmcnt(0)
	s_setprio 1
	s_barrier
	v_mfma_f32_16x16x32_bf16 v[92:95], v[128:131], v[182:185], v[92:95]
	v_mfma_f32_16x16x32_bf16 v[88:91], v[158:161], v[182:185], v[88:91]
	v_mfma_f32_16x16x32_bf16 v[84:87], v[128:131], v[190:193], v[84:87]
	v_mfma_f32_16x16x32_bf16 v[80:83], v[158:161], v[190:193], v[80:83]
	v_mfma_f32_16x16x32_bf16 v[76:79], v[128:131], v[198:201], v[76:79]
	v_mfma_f32_16x16x32_bf16 v[72:75], v[158:161], v[198:201], v[72:75]
	v_mfma_f32_16x16x32_bf16 v[68:71], v[128:131], v[206:209], v[68:71]
	v_mfma_f32_16x16x32_bf16 v[64:67], v[158:161], v[206:209], v[64:67]
	v_mfma_f32_16x16x32_bf16 v[92:95], v[132:135], v[186:189], v[92:95]
	v_mfma_f32_16x16x32_bf16 v[88:91], v[162:165], v[186:189], v[88:91]
	v_mfma_f32_16x16x32_bf16 v[84:87], v[132:135], v[194:197], v[84:87]
	v_mfma_f32_16x16x32_bf16 v[80:83], v[162:165], v[194:197], v[80:83]
	v_mfma_f32_16x16x32_bf16 v[76:79], v[132:135], v[202:205], v[76:79]
	v_mfma_f32_16x16x32_bf16 v[72:75], v[162:165], v[202:205], v[72:75]
	v_mfma_f32_16x16x32_bf16 v[68:71], v[132:135], v[210:213], v[68:71]
	v_mfma_f32_16x16x32_bf16 v[64:67], v[162:165], v[210:213], v[64:67]
	v_mfma_f32_16x16x32_bf16 v[28:31], v[166:169], v[182:185], v[28:31]
	v_mfma_f32_16x16x32_bf16 v[24:27], v[174:177], v[182:185], v[24:27]
	v_mfma_f32_16x16x32_bf16 v[20:23], v[166:169], v[190:193], v[20:23]
	v_mfma_f32_16x16x32_bf16 v[16:19], v[174:177], v[190:193], v[16:19]
	v_mfma_f32_16x16x32_bf16 v[12:15], v[166:169], v[198:201], v[12:15]
	v_mfma_f32_16x16x32_bf16 v[8:11], v[174:177], v[198:201], v[8:11]
	v_mfma_f32_16x16x32_bf16 v[4:7], v[166:169], v[206:209], v[4:7]
	v_mfma_f32_16x16x32_bf16 v[0:3], v[174:177], v[206:209], v[0:3]
	v_mfma_f32_16x16x32_bf16 v[28:31], v[170:173], v[186:189], v[28:31]
	v_mfma_f32_16x16x32_bf16 v[24:27], v[178:181], v[186:189], v[24:27]
	v_mfma_f32_16x16x32_bf16 v[20:23], v[170:173], v[194:197], v[20:23]
	v_mfma_f32_16x16x32_bf16 v[16:19], v[178:181], v[194:197], v[16:19]
	v_mfma_f32_16x16x32_bf16 v[12:15], v[170:173], v[202:205], v[12:15]
	v_mfma_f32_16x16x32_bf16 v[8:11], v[178:181], v[202:205], v[8:11]
	s_setprio 2
	s_barrier
	v_mfma_f32_16x16x32_bf16 v[4:7], v[170:173], v[210:213], v[4:7]
	v_mfma_f32_16x16x32_bf16 v[0:3], v[178:181], v[210:213], v[0:3]
	s_setprio 0
	s_add_i32 vcc_hi, vcc_hi, 2
	s_add_u32 s76, s76, 0x100
	s_addc_u32 s77, s77, 0
	s_add_u32 s75, s75, 0x100
	s_addc_u32 vcc_lo, vcc_lo, 0
	s_cmp_gt_u32 vcc_hi, 29
	s_cbranch_scc0 .LBB0_374
	s_and_b64 vcc, exec, s[48:49]
	s_cbranch_vccz .LBB0_377
	s_barrier

; #define PG8_STAGE(bufoff, gbase, voff) do { _Pragma("unroll") for (int _i = 0; _i < 2; ++_i) \
;         __builtin_amdgcn_global_load_lds((const unsigned*)((const char*)(gbase) + (voff)[_i]), (PG8_LAS unsigned*)(lds + (bufoff) + ldsw + _i * 8192), 16, 0, 0); } while (0)
; #define PG8_LDA(dst, b, h) do { _Pragma("unroll") for (int m = 0; m < 4; ++m) _Pragma("unroll") for (int k = 0; k < 2; ++k) dst[m][k] = *(const PG8_LAS bf16x8*)(lds + PG8_SA(b, h) + aoff + m * 2048 + k * 1024); } while (0)
; #define PG8_LDB(dst, b, h) do { _Pragma("unroll") for (int n = 0; n < 2; ++n) _Pragma("unroll") for (int k = 0; k < 2; ++k) dst[n][k] = *(const PG8_LAS bf16x8*)(lds + PG8_SB(b, h) + boff + n * 2048 + k * 1024); } while (0)
; #define PG8_MMA(ai, bj, At, Bt) do { __builtin_amdgcn_s_setprio(1); _Pragma("unroll") for (int m = 0; m < 4; ++m) _Pragma("unroll") for (int n = 0; n < 2; ++n) _Pragma("unroll") for (int k = 0; k < 2; ++k) \
;         acc[ai][bj][m][n] = __builtin_amdgcn_mfma_f32_16x16x32_bf16(Bt[n][k], At[m][k], acc[ai][bj][m][n], 0, 0, 0); __builtin_amdgcn_s_setprio(0); } while (0)
; #define PG8_WAIT_V(n) asm volatile("s_waitcnt vmcnt(" #n ")" ::: "memory")
; #define PG8_WAIT_L(n) asm volatile("s_waitcnt lgkmcnt(" #n ")" ::: "memory")
; #define PG8_BAR __builtin_amdgcn_s_barrier()
; template <class Epi, class Sched, bool ALIGN_EPI = false, bool SP2 = false>
; __device__ __forceinline__ void gemm_phase(PG8_LAS unsigned char* lds, const Gemm g, const Sched& S, const Epi& E) {
;     ...
;         for (int t = 0; t < nt; t += 2) {
;             const bool last = (t == nt - 2);
;             const char* a1 = cA + (size_t)(t + 1) * kstep;
;             const char* a2 = last ? nA : cA + (size_t)(t + 2) * kstep; const char* b2 = last ? nB : cB + (size_t)(t + 2) * kstep;
;             const char* a3 = a2 + kstep; const char* b3 = b2 + kstep;
;             if constexpr (SP2) {
;             PG8_LDB(B0, 0, 0); PG8_LDB(B1, 0, 1); PG8_SCHED; PG8_LDA(At, 0, 0); PG8_STAGE(PG8_SA(1, 1), a1 + hstep, voffA);
;             PG8_WAIT_V(8); PG8_WAIT_L(0); PG8_BAR; PG8_MMA(0, 0, At, B0); PG8_MMA(0, 1, At, B1); PG8_BAR; PG8_SCHED;
;             PG8_LDA(At, 0, 1); PG8_STAGE(PG8_SB(0, 0), b2, voffB); PG8_STAGE(PG8_SB(0, 1), b2 + hstep, voffB); PG8_STAGE(PG8_SA(0, 0), a2, voffA);
;             PG8_WAIT_V(8); PG8_WAIT_L(0); PG8_BAR; PG8_MMA(1, 0, At, B0); PG8_MMA(1, 1, At, B1); PG8_BAR; PG8_SCHED;
.LBB0_410:
	ds_read_b128 v[166:169], v145
	ds_read_b128 v[170:173], v145 offset:1024
	ds_read_b128 v[174:177], v145 offset:2048
	ds_read_b128 v[178:181], v145 offset:3072
	ds_read_b128 v[182:185], v149
	ds_read_b128 v[186:189], v149 offset:1024
	ds_read_b128 v[190:193], v149 offset:2048
	ds_read_b128 v[194:197], v149 offset:3072
	s_add_u32 s52, s74, 0xfff80080
	s_addc_u32 s53, s75, -1
	s_cmp_eq_u32 s51, 4
	s_cselect_b32 s79, s55, s53
	s_cselect_b32 s78, s54, s52
	s_cselect_b32 s77, s69, s49
	s_cselect_b32 s76, s68, s37
	s_mov_b32 m0, s80
	v_lshl_add_u64 v[230:231], s[74:75], 0, v[160:161]
	ds_read_b128 v[198:201], v164
	ds_read_b128 v[202:205], v164 offset:1024
	ds_read_b128 v[206:209], v164 offset:2048
	ds_read_b128 v[210:213], v164 offset:3072
	ds_read_b128 v[214:217], v164 offset:4096
	ds_read_b128 v[218:221], v164 offset:5120
	ds_read_b128 v[222:225], v164 offset:6144
	ds_read_b128 v[226:229], v164 offset:7168
	global_load_lds_dwordx4 v[230:231], off
	v_lshl_add_u64 v[230:231], s[74:75], 0, v[162:163]
	s_mov_b32 m0, s81
	s_nop 0
	global_load_lds_dwordx4 v[230:231], off
	s_waitcnt vmcnt(8)
	s_waitcnt lgkmcnt(0)
	s_setprio 1
	s_barrier
	v_mfma_f32_16x16x32_bf16 v[124:127], v[166:169], v[198:201], v[124:127]
	v_mfma_f32_16x16x32_bf16 v[120:123], v[174:177], v[198:201], v[120:123]
	v_mfma_f32_16x16x32_bf16 v[116:119], v[166:169], v[206:209], v[116:119]
	v_mfma_f32_16x16x32_bf16 v[108:111], v[174:177], v[206:209], v[108:111]
	v_mfma_f32_16x16x32_bf16 v[100:103], v[166:169], v[214:217], v[100:103]
	v_mfma_f32_16x16x32_bf16 v[92:95], v[174:177], v[214:217], v[92:95]
	v_mfma_f32_16x16x32_bf16 v[84:87], v[166:169], v[222:225], v[84:87]
	v_mfma_f32_16x16x32_bf16 v[76:79], v[174:177], v[222:225], v[76:79]
	v_mfma_f32_16x16x32_bf16 v[124:127], v[170:173], v[202:205], v[124:127]
	v_mfma_f32_16x16x32_bf16 v[120:123], v[178:181], v[202:205], v[120:123]
	v_mfma_f32_16x16x32_bf16 v[116:119], v[170:173], v[210:213], v[116:119]
	v_mfma_f32_16x16x32_bf16 v[108:111], v[178:181], v[210:213], v[108:111]
	v_mfma_f32_16x16x32_bf16 v[100:103], v[170:173], v[218:221], v[100:103]
	v_mfma_f32_16x16x32_bf16 v[92:95], v[178:181], v[218:221], v[92:95]
	v_mfma_f32_16x16x32_bf16 v[84:87], v[170:173], v[226:229], v[84:87]
	v_mfma_f32_16x16x32_bf16 v[76:79], v[178:181], v[226:229], v[76:79]
	v_mfma_f32_16x16x32_bf16 v[112:115], v[182:185], v[198:201], v[112:115]
	v_mfma_f32_16x16x32_bf16 v[104:107], v[190:193], v[198:201], v[104:107]
	v_mfma_f32_16x16x32_bf16 v[96:99], v[182:185], v[206:209], v[96:99]
	v_mfma_f32_16x16x32_bf16 v[88:91], v[190:193], v[206:209], v[88:91]
	v_mfma_f32_16x16x32_bf16 v[80:83], v[182:185], v[214:217], v[80:83]
	v_mfma_f32_16x16x32_bf16 v[72:75], v[190:193], v[214:217], v[72:75]
	v_mfma_f32_16x16x32_bf16 v[68:71], v[182:185], v[222:225], v[68:71]
	v_mfma_f32_16x16x32_bf16 v[64:67], v[190:193], v[222:225], v[64:67]
	v_mfma_f32_16x16x32_bf16 v[112:115], v[186:189], v[202:205], v[112:115]
	v_mfma_f32_16x16x32_bf16 v[104:107], v[194:197], v[202:205], v[104:107]
	v_mfma_f32_16x16x32_bf16 v[96:99], v[186:189], v[210:213], v[96:99]
	v_mfma_f32_16x16x32_bf16 v[88:91], v[194:197], v[210:213], v[88:91]
	v_mfma_f32_16x16x32_bf16 v[80:83], v[186:189], v[218:221], v[80:83]
	v_mfma_f32_16x16x32_bf16 v[72:75], v[194:197], v[218:221], v[72:75]
	s_setprio 2
	s_barrier
	v_mfma_f32_16x16x32_bf16 v[68:71], v[186:189], v[226:229], v[68:71]
	v_mfma_f32_16x16x32_bf16 v[64:67], v[194:197], v[226:229], v[64:67]
	s_setprio 0
	s_mov_b32 m0, s84
	v_lshl_add_u64 v[230:231], s[76:77], 0, v[138:139]
	s_add_u32 s52, s76, 0x80000
	ds_read_b128 v[198:201], v164 offset:16384
	ds_read_b128 v[202:205], v164 offset:17408
	ds_read_b128 v[206:209], v164 offset:18432
	ds_read_b128 v[210:213], v164 offset:19456
	ds_read_b128 v[214:217], v164 offset:20480
	ds_read_b128 v[218:221], v164 offset:21504
	ds_read_b128 v[222:225], v164 offset:22528
	ds_read_b128 v[226:229], v164 offset:23552
	global_load_lds_dwordx4 v[230:231], off
	v_lshl_add_u64 v[232:233], s[76:77], 0, v[142:143]
	s_mov_b32 m0, s85
	s_addc_u32 s53, s77, 0
	global_load_lds_dwordx4 v[232:233], off
	v_lshl_add_u64 v[234:235], s[52:53], 0, v[138:139]
	s_mov_b32 m0, s86
	v_lshl_add_u64 v[236:237], s[78:79], 0, v[140:141]
	global_load_lds_dwordx4 v[234:235], off
	v_lshl_add_u64 v[234:235], s[52:53], 0, v[142:143]
	s_mov_b32 m0, s87
	s_nop 0
	global_load_lds_dwordx4 v[234:235], off
	v_lshl_add_u64 v[234:235], s[78:79], 0, v[136:137]
	s_mov_b32 m0, s10
	s_nop 0
	global_load_lds_dwordx4 v[234:235], off
	s_mov_b32 m0, s11
	s_nop 0
	global_load_lds_dwordx4 v[236:237], off
	s_waitcnt vmcnt(8)
	s_waitcnt lgkmcnt(0)
	s_setprio 1
	s_barrier
; #define PG8_STAGE(bufoff, gbase, voff) do { _Pragma("unroll") for (int _i = 0; _i < 2; ++_i) \
;         __builtin_amdgcn_global_load_lds((const unsigned*)((const char*)(gbase) + (voff)[_i]), (PG8_LAS unsigned*)(lds + (bufoff) + ldsw + _i * 8192), 16, 0, 0); } while (0)
; #define PG8_LDA(dst, b, h) do { _Pragma("unroll") for (int m = 0; m < 4; ++m) _Pragma("unroll") for (int k = 0; k < 2; ++k) dst[m][k] = *(const PG8_LAS bf16x8*)(lds + PG8_SA(b, h) + aoff + m * 2048 + k * 1024); } while (0)
; #define PG8_LDB(dst, b, h) do { _Pragma("unroll") for (int n = 0; n < 2; ++n) _Pragma("unroll") for (int k = 0; k < 2; ++k) dst[n][k] = *(const PG8_LAS bf16x8*)(lds + PG8_SB(b, h) + boff + n * 2048 + k * 1024); } while (0)
; #define PG8_MMA(ai, bj, At, Bt) do { __builtin_amdgcn_s_setprio(1); _Pragma("unroll") for (int m = 0; m < 4; ++m) _Pragma("unroll") for (int n = 0; n < 2; ++n) _Pragma("unroll") for (int k = 0; k < 2; ++k) \
;         acc[ai][bj][m][n] = __builtin_amdgcn_mfma_f32_16x16x32_bf16(Bt[n][k], At[m][k], acc[ai][bj][m][n], 0, 0, 0); __builtin_amdgcn_s_setprio(0); } while (0)
; #define PG8_WAIT_V(n) asm volatile("s_waitcnt vmcnt(" #n ")" ::: "memory")
; #define PG8_WAIT_L(n) asm volatile("s_waitcnt lgkmcnt(" #n ")" ::: "memory")
; #define PG8_BAR __builtin_amdgcn_s_barrier()
; #define PG8_SCHED __builtin_amdgcn_sched_barrier(0)
; template <class Epi, class Sched, bool ALIGN_EPI = false, bool SP2 = false>
; __device__ __forceinline__ void gemm_phase(PG8_LAS unsigned char* lds, const Gemm g, const Sched& S, const Epi& E) {
;     ...
;             PG8_WAIT_V(8); PG8_WAIT_L(0); PG8_BAR; PG8_MMA(1, 0, At, B0); PG8_MMA(1, 1, At, B1); PG8_BAR; PG8_SCHED;
;             PG8_LDB(B0, 1, 0); PG8_LDB(B1, 1, 1); PG8_SCHED; PG8_LDA(At, 1, 0); PG8_STAGE(PG8_SA(0, 1), a2 + hstep, voffA);
;             PG8_WAIT_V(8); PG8_WAIT_L(0); PG8_BAR; PG8_MMA(0, 0, At, B0); PG8_MMA(0, 1, At, B1); PG8_BAR; PG8_SCHED;
	v_mfma_f32_16x16x32_bf16 v[60:63], v[166:169], v[198:201], v[60:63]
	v_mfma_f32_16x16x32_bf16 v[56:59], v[174:177], v[198:201], v[56:59]
	v_mfma_f32_16x16x32_bf16 v[52:55], v[166:169], v[206:209], v[52:55]
	v_mfma_f32_16x16x32_bf16 v[44:47], v[174:177], v[206:209], v[44:47]
	v_mfma_f32_16x16x32_bf16 v[36:39], v[166:169], v[214:217], v[36:39]
	v_mfma_f32_16x16x32_bf16 v[28:31], v[174:177], v[214:217], v[28:31]
	v_mfma_f32_16x16x32_bf16 v[20:23], v[166:169], v[222:225], v[20:23]
	v_mfma_f32_16x16x32_bf16 v[12:15], v[174:177], v[222:225], v[12:15]
	v_mfma_f32_16x16x32_bf16 v[60:63], v[170:173], v[202:205], v[60:63]
	v_mfma_f32_16x16x32_bf16 v[56:59], v[178:181], v[202:205], v[56:59]
	v_mfma_f32_16x16x32_bf16 v[52:55], v[170:173], v[210:213], v[52:55]
	v_mfma_f32_16x16x32_bf16 v[44:47], v[178:181], v[210:213], v[44:47]
	v_mfma_f32_16x16x32_bf16 v[36:39], v[170:173], v[218:221], v[36:39]
	v_mfma_f32_16x16x32_bf16 v[28:31], v[178:181], v[218:221], v[28:31]
	v_mfma_f32_16x16x32_bf16 v[20:23], v[170:173], v[226:229], v[20:23]
	v_mfma_f32_16x16x32_bf16 v[12:15], v[178:181], v[226:229], v[12:15]
	v_mfma_f32_16x16x32_bf16 v[48:51], v[182:185], v[198:201], v[48:51]
	v_mfma_f32_16x16x32_bf16 v[40:43], v[190:193], v[198:201], v[40:43]
	v_mfma_f32_16x16x32_bf16 v[32:35], v[182:185], v[206:209], v[32:35]
	v_mfma_f32_16x16x32_bf16 v[24:27], v[190:193], v[206:209], v[24:27]
	v_mfma_f32_16x16x32_bf16 v[16:19], v[182:185], v[214:217], v[16:19]
	v_mfma_f32_16x16x32_bf16 v[8:11], v[190:193], v[214:217], v[8:11]
	v_mfma_f32_16x16x32_bf16 v[4:7], v[182:185], v[222:225], v[4:7]
	v_mfma_f32_16x16x32_bf16 v[0:3], v[190:193], v[222:225], v[0:3]
	v_mfma_f32_16x16x32_bf16 v[48:51], v[186:189], v[202:205], v[48:51]
	v_mfma_f32_16x16x32_bf16 v[40:43], v[194:197], v[202:205], v[40:43]
	v_mfma_f32_16x16x32_bf16 v[32:35], v[186:189], v[210:213], v[32:35]
	v_mfma_f32_16x16x32_bf16 v[24:27], v[194:197], v[210:213], v[24:27]
	v_mfma_f32_16x16x32_bf16 v[16:19], v[186:189], v[218:221], v[16:19]
	v_mfma_f32_16x16x32_bf16 v[8:11], v[194:197], v[218:221], v[8:11]
	s_setprio 2
	s_barrier
	v_mfma_f32_16x16x32_bf16 v[4:7], v[186:189], v[226:229], v[4:7]
	v_mfma_f32_16x16x32_bf16 v[0:3], v[194:197], v[226:229], v[0:3]
	s_setprio 0
	ds_read_b128 v[166:169], v148
	ds_read_b128 v[170:173], v148 offset:1024
	ds_read_b128 v[174:177], v148 offset:2048
	ds_read_b128 v[178:181], v148 offset:3072
	ds_read_b128 v[182:185], v165
	ds_read_b128 v[186:189], v165 offset:1024
	ds_read_b128 v[190:193], v165 offset:2048
	ds_read_b128 v[194:197], v165 offset:3072
	s_add_u32 s52, s78, 0x80000
	s_addc_u32 s53, s79, 0
	s_mov_b32 m0, s28
	v_lshl_add_u64 v[238:239], s[52:53], 0, v[136:137]
	ds_read_b128 v[198:201], v164 offset:32768
	ds_read_b128 v[202:205], v164 offset:33792
	ds_read_b128 v[206:209], v164 offset:34816
	ds_read_b128 v[210:213], v164 offset:35840
	ds_read_b128 v[214:217], v164 offset:36864
	ds_read_b128 v[218:221], v164 offset:37888
	ds_read_b128 v[222:225], v164 offset:38912
	ds_read_b128 v[226:229], v164 offset:39936
	global_load_lds_dwordx4 v[238:239], off
	v_lshl_add_u64 v[238:239], s[52:53], 0, v[140:141]
	s_mov_b32 m0, s29
	s_nop 0
	global_load_lds_dwordx4 v[238:239], off
	s_waitcnt vmcnt(8)
	s_waitcnt lgkmcnt(0)
	s_setprio 1
	s_barrier
	v_mfma_f32_16x16x32_bf16 v[124:127], v[166:169], v[198:201], v[124:127]
	v_mfma_f32_16x16x32_bf16 v[120:123], v[174:177], v[198:201], v[120:123]
	v_mfma_f32_16x16x32_bf16 v[116:119], v[166:169], v[206:209], v[116:119]
	v_mfma_f32_16x16x32_bf16 v[108:111], v[174:177], v[206:209], v[108:111]
	v_mfma_f32_16x16x32_bf16 v[100:103], v[166:169], v[214:217], v[100:103]
	v_mfma_f32_16x16x32_bf16 v[92:95], v[174:177], v[214:217], v[92:95]
	v_mfma_f32_16x16x32_bf16 v[84:87], v[166:169], v[222:225], v[84:87]
	v_mfma_f32_16x16x32_bf16 v[76:79], v[174:177], v[222:225], v[76:79]
	v_mfma_f32_16x16x32_bf16 v[124:127], v[170:173], v[202:205], v[124:127]
	v_mfma_f32_16x16x32_bf16 v[120:123], v[178:181], v[202:205], v[120:123]
	v_mfma_f32_16x16x32_bf16 v[116:119], v[170:173], v[210:213], v[116:119]
	v_mfma_f32_16x16x32_bf16 v[108:111], v[178:181], v[210:213], v[108:111]
	v_mfma_f32_16x16x32_bf16 v[100:103], v[170:173], v[218:221], v[100:103]
	v_mfma_f32_16x16x32_bf16 v[92:95], v[178:181], v[218:221], v[92:95]
	v_mfma_f32_16x16x32_bf16 v[84:87], v[170:173], v[226:229], v[84:87]
	v_mfma_f32_16x16x32_bf16 v[76:79], v[178:181], v[226:229], v[76:79]
	v_mfma_f32_16x16x32_bf16 v[112:115], v[182:185], v[198:201], v[112:115]
	v_mfma_f32_16x16x32_bf16 v[104:107], v[190:193], v[198:201], v[104:107]
	v_mfma_f32_16x16x32_bf16 v[96:99], v[182:185], v[206:209], v[96:99]
	v_mfma_f32_16x16x32_bf16 v[88:91], v[190:193], v[206:209], v[88:91]
	v_mfma_f32_16x16x32_bf16 v[80:83], v[182:185], v[214:217], v[80:83]
	v_mfma_f32_16x16x32_bf16 v[72:75], v[190:193], v[214:217], v[72:75]
	v_mfma_f32_16x16x32_bf16 v[68:71], v[182:185], v[222:225], v[68:71]
	v_mfma_f32_16x16x32_bf16 v[64:67], v[190:193], v[222:225], v[64:67]
	v_mfma_f32_16x16x32_bf16 v[112:115], v[186:189], v[202:205], v[112:115]
	v_mfma_f32_16x16x32_bf16 v[104:107], v[194:197], v[202:205], v[104:107]
	v_mfma_f32_16x16x32_bf16 v[96:99], v[186:189], v[210:213], v[96:99]
	v_mfma_f32_16x16x32_bf16 v[88:91], v[194:197], v[210:213], v[88:91]
	v_mfma_f32_16x16x32_bf16 v[80:83], v[186:189], v[218:221], v[80:83]
	v_mfma_f32_16x16x32_bf16 v[72:75], v[194:197], v[218:221], v[72:75]
	s_setprio 2
	s_barrier
; #define PG8_STAGE(bufoff, gbase, voff) do { _Pragma("unroll") for (int _i = 0; _i < 2; ++_i) \
;         __builtin_amdgcn_global_load_lds((const unsigned*)((const char*)(gbase) + (voff)[_i]), (PG8_LAS unsigned*)(lds + (bufoff) + ldsw + _i * 8192), 16, 0, 0); } while (0)
; #define PG8_LDA(dst, b, h) do { _Pragma("unroll") for (int m = 0; m < 4; ++m) _Pragma("unroll") for (int k = 0; k < 2; ++k) dst[m][k] = *(const PG8_LAS bf16x8*)(lds + PG8_SA(b, h) + aoff + m * 2048 + k * 1024); } while (0)
; #define PG8_MMA(ai, bj, At, Bt) do { __builtin_amdgcn_s_setprio(1); _Pragma("unroll") for (int m = 0; m < 4; ++m) _Pragma("unroll") for (int n = 0; n < 2; ++n) _Pragma("unroll") for (int k = 0; k < 2; ++k) \
;         acc[ai][bj][m][n] = __builtin_amdgcn_mfma_f32_16x16x32_bf16(Bt[n][k], At[m][k], acc[ai][bj][m][n], 0, 0, 0); __builtin_amdgcn_s_setprio(0); } while (0)
; #define PG8_WAIT_V(n) asm volatile("s_waitcnt vmcnt(" #n ")" ::: "memory")
; #define PG8_WAIT_L(n) asm volatile("s_waitcnt lgkmcnt(" #n ")" ::: "memory")
; #define PG8_BAR __builtin_amdgcn_s_barrier()
; #define PG8_SCHED __builtin_amdgcn_sched_barrier(0)
; template <class Epi, class Sched, bool ALIGN_EPI = false, bool SP2 = false>
; __device__ __forceinline__ void gemm_phase(PG8_LAS unsigned char* lds, const Gemm g, const Sched& S, const Epi& E) {
;     ...
;             PG8_WAIT_V(8); PG8_WAIT_L(0); PG8_BAR; PG8_MMA(0, 0, At, B0); PG8_MMA(0, 1, At, B1); PG8_BAR; PG8_SCHED;
;             PG8_LDA(At, 1, 1); PG8_STAGE(PG8_SB(1, 0), b3, voffB); PG8_STAGE(PG8_SB(1, 1), b3 + hstep, voffB); PG8_STAGE(PG8_SA(1, 0), a3, voffA);
;             PG8_WAIT_V(8); PG8_WAIT_L(0); PG8_BAR; PG8_MMA(1, 0, At, B0); PG8_MMA(1, 1, At, B1); PG8_BAR; PG8_SCHED;
;     ...
;         if constexpr (ALIGN_EPI) { if (wr == 0) PG8_BAR; }
	v_mfma_f32_16x16x32_bf16 v[68:71], v[186:189], v[226:229], v[68:71]
	v_mfma_f32_16x16x32_bf16 v[64:67], v[194:197], v[226:229], v[64:67]
	s_setprio 0
	s_mov_b32 m0, s89
	v_lshl_add_u64 v[230:231], v[230:231], 0, s[12:13]
	ds_read_b128 v[198:201], v164 offset:49152
	ds_read_b128 v[202:205], v164 offset:50176
	ds_read_b128 v[206:209], v164 offset:51200
	ds_read_b128 v[210:213], v164 offset:52224
	ds_read_b128 v[214:217], v164 offset:53248
	ds_read_b128 v[218:221], v164 offset:54272
	ds_read_b128 v[222:225], v164 offset:55296
	ds_read_b128 v[226:229], v164 offset:56320
	global_load_lds_dwordx4 v[230:231], off
	s_add_i32 m0, s89, 0x2000
	s_add_u32 s52, s76, 0x80080
	v_lshl_add_u64 v[230:231], v[232:233], 0, s[12:13]
	s_addc_u32 s53, s77, 0
	s_add_i32 s56, s88, s3
	global_load_lds_dwordx4 v[230:231], off
	v_lshl_add_u64 v[230:231], s[52:53], 0, v[138:139]
	s_mov_b32 m0, s56
	s_nop 0
	global_load_lds_dwordx4 v[230:231], off
	v_lshl_add_u64 v[230:231], s[52:53], 0, v[142:143]
	s_add_i32 m0, s56, 0x2000
	s_nop 0
	global_load_lds_dwordx4 v[230:231], off
	v_lshl_add_u64 v[230:231], v[234:235], 0, s[12:13]
	s_mov_b32 m0, s38
	s_nop 0
	global_load_lds_dwordx4 v[230:231], off
	v_lshl_add_u64 v[230:231], v[236:237], 0, s[12:13]
	s_mov_b32 m0, s39
	s_nop 0
	global_load_lds_dwordx4 v[230:231], off
	s_waitcnt vmcnt(8)
	s_waitcnt lgkmcnt(0)
	s_setprio 1
	s_barrier
	v_mfma_f32_16x16x32_bf16 v[60:63], v[166:169], v[198:201], v[60:63]
	v_mfma_f32_16x16x32_bf16 v[56:59], v[174:177], v[198:201], v[56:59]
	v_mfma_f32_16x16x32_bf16 v[52:55], v[166:169], v[206:209], v[52:55]
	v_mfma_f32_16x16x32_bf16 v[44:47], v[174:177], v[206:209], v[44:47]
	v_mfma_f32_16x16x32_bf16 v[36:39], v[166:169], v[214:217], v[36:39]
	v_mfma_f32_16x16x32_bf16 v[28:31], v[174:177], v[214:217], v[28:31]
	v_mfma_f32_16x16x32_bf16 v[20:23], v[166:169], v[222:225], v[20:23]
	v_mfma_f32_16x16x32_bf16 v[12:15], v[174:177], v[222:225], v[12:15]
	v_mfma_f32_16x16x32_bf16 v[60:63], v[170:173], v[202:205], v[60:63]
	v_mfma_f32_16x16x32_bf16 v[56:59], v[178:181], v[202:205], v[56:59]
	v_mfma_f32_16x16x32_bf16 v[52:55], v[170:173], v[210:213], v[52:55]
	v_mfma_f32_16x16x32_bf16 v[44:47], v[178:181], v[210:213], v[44:47]
	v_mfma_f32_16x16x32_bf16 v[36:39], v[170:173], v[218:221], v[36:39]
	v_mfma_f32_16x16x32_bf16 v[28:31], v[178:181], v[218:221], v[28:31]
	v_mfma_f32_16x16x32_bf16 v[20:23], v[170:173], v[226:229], v[20:23]
	v_mfma_f32_16x16x32_bf16 v[12:15], v[178:181], v[226:229], v[12:15]
	v_mfma_f32_16x16x32_bf16 v[48:51], v[182:185], v[198:201], v[48:51]
	v_mfma_f32_16x16x32_bf16 v[40:43], v[190:193], v[198:201], v[40:43]
	v_mfma_f32_16x16x32_bf16 v[32:35], v[182:185], v[206:209], v[32:35]
	v_mfma_f32_16x16x32_bf16 v[24:27], v[190:193], v[206:209], v[24:27]
	v_mfma_f32_16x16x32_bf16 v[16:19], v[182:185], v[214:217], v[16:19]
	v_mfma_f32_16x16x32_bf16 v[8:11], v[190:193], v[214:217], v[8:11]
	v_mfma_f32_16x16x32_bf16 v[4:7], v[182:185], v[222:225], v[4:7]
	v_mfma_f32_16x16x32_bf16 v[0:3], v[190:193], v[222:225], v[0:3]
	v_mfma_f32_16x16x32_bf16 v[48:51], v[186:189], v[202:205], v[48:51]
	v_mfma_f32_16x16x32_bf16 v[40:43], v[194:197], v[202:205], v[40:43]
	v_mfma_f32_16x16x32_bf16 v[32:35], v[186:189], v[210:213], v[32:35]
	v_mfma_f32_16x16x32_bf16 v[24:27], v[194:197], v[210:213], v[24:27]
	v_mfma_f32_16x16x32_bf16 v[16:19], v[186:189], v[218:221], v[16:19]
	v_mfma_f32_16x16x32_bf16 v[8:11], v[194:197], v[218:221], v[8:11]
	s_setprio 2
	s_barrier
	v_mfma_f32_16x16x32_bf16 v[4:7], v[186:189], v[226:229], v[4:7]
	v_mfma_f32_16x16x32_bf16 v[0:3], v[194:197], v[226:229], v[0:3]
	s_setprio 0
	s_add_i32 s51, s51, 2
	s_add_u32 s74, s74, 0x100
	s_addc_u32 s75, s75, 0
	s_add_u32 s37, s37, 0x100
	s_addc_u32 s49, s49, 0
	s_cmp_gt_u32 s51, 5
	s_cbranch_scc0 .LBB0_410
	s_and_b64 vcc, exec, s[14:15]
	s_cbranch_vccz .LBB0_413
	s_barrier

; #define PG8_STAGE(bufoff, gbase, voff) do { _Pragma("unroll") for (int _i = 0; _i < 2; ++_i) \
;         __builtin_amdgcn_global_load_lds((const unsigned*)((const char*)(gbase) + (voff)[_i]), (PG8_LAS unsigned*)(lds + (bufoff) + ldsw + _i * 8192), 16, 0, 0); } while (0)
; #define PG8_LDA(dst, b, h) do { _Pragma("unroll") for (int m = 0; m < 4; ++m) _Pragma("unroll") for (int k = 0; k < 2; ++k) dst[m][k] = *(const PG8_LAS bf16x8*)(lds + PG8_SA(b, h) + aoff + m * 2048 + k * 1024); } while (0)
; #define PG8_LDB(dst, b, h) do { _Pragma("unroll") for (int n = 0; n < 2; ++n) _Pragma("unroll") for (int k = 0; k < 2; ++k) dst[n][k] = *(const PG8_LAS bf16x8*)(lds + PG8_SB(b, h) + boff + n * 2048 + k * 1024); } while (0)
; #define PG8_MMA(ai, bj, At, Bt) do { __builtin_amdgcn_s_setprio(1); _Pragma("unroll") for (int m = 0; m < 4; ++m) _Pragma("unroll") for (int n = 0; n < 2; ++n) _Pragma("unroll") for (int k = 0; k < 2; ++k) \
;         acc[ai][bj][m][n] = __builtin_amdgcn_mfma_f32_16x16x32_bf16(Bt[n][k], At[m][k], acc[ai][bj][m][n], 0, 0, 0); __builtin_amdgcn_s_setprio(0); } while (0)
; #define PG8_WAIT_V(n) asm volatile("s_waitcnt vmcnt(" #n ")" ::: "memory")
; #define PG8_WAIT_L(n) asm volatile("s_waitcnt lgkmcnt(" #n ")" ::: "memory")
; #define PG8_BAR __builtin_amdgcn_s_barrier()
; template <class Epi, class Sched, bool ALIGN_EPI = false, bool SP2 = false>
; __device__ __forceinline__ void gemm_phase(PG8_LAS unsigned char* lds, const Gemm g, const Sched& S, const Epi& E) {
;     ...
;         for (int t = 0; t < nt; t += 2) {
;             const bool last = (t == nt - 2);
;             const char* a1 = cA + (size_t)(t + 1) * kstep;
;             const char* a2 = last ? nA : cA + (size_t)(t + 2) * kstep; const char* b2 = last ? nB : cB + (size_t)(t + 2) * kstep;
;             const char* a3 = a2 + kstep; const char* b3 = b2 + kstep;
;             if constexpr (SP2) {
;             PG8_LDB(B0, 0, 0); PG8_LDB(B1, 0, 1); PG8_SCHED; PG8_LDA(At, 0, 0); PG8_STAGE(PG8_SA(1, 1), a1 + hstep, voffA);
;             PG8_WAIT_V(8); PG8_WAIT_L(0); PG8_BAR; PG8_MMA(0, 0, At, B0); PG8_MMA(0, 1, At, B1); PG8_BAR; PG8_SCHED;
;             PG8_LDA(At, 0, 1); PG8_STAGE(PG8_SB(0, 0), b2, voffB); PG8_STAGE(PG8_SB(0, 1), b2 + hstep, voffB); PG8_STAGE(PG8_SA(0, 0), a2, voffA);
;             PG8_WAIT_V(8); PG8_WAIT_L(0); PG8_BAR; PG8_MMA(1, 0, At, B0); PG8_MMA(1, 1, At, B1); PG8_BAR; PG8_SCHED;
.LBB0_545:
	ds_read_b128 v[112:115], v174
	ds_read_b128 v[116:119], v174 offset:1024
	ds_read_b128 v[120:123], v174 offset:2048
	ds_read_b128 v[124:127], v174 offset:3072
	ds_read_b128 v[164:167], v175
	ds_read_b128 v[168:171], v175 offset:1024
	ds_read_b128 v[178:181], v175 offset:2048
	ds_read_b128 v[182:185], v175 offset:3072
	s_add_u32 s52, s68, 0xfff80080
	s_addc_u32 s53, s69, -1
	s_cmp_eq_u32 s88, 28
	s_cselect_b32 s73, s41, s53
	s_cselect_b32 s72, s84, s52
	s_cselect_b32 s71, s37, s87
	s_cselect_b32 s70, s85, s86
	v_lshl_add_u64 v[218:219], s[68:69], 0, v[156:157]
	s_add_i32 m0, s39, 0xc000
	ds_read_b128 v[186:189], v176
	ds_read_b128 v[190:193], v176 offset:1024
	ds_read_b128 v[194:197], v176 offset:2048
	ds_read_b128 v[198:201], v176 offset:3072
	ds_read_b128 v[202:205], v176 offset:4096
	ds_read_b128 v[206:209], v176 offset:5120
	ds_read_b128 v[210:213], v176 offset:6144
	ds_read_b128 v[214:217], v176 offset:7168
	global_load_lds_dwordx4 v[218:219], off
	v_lshl_add_u64 v[218:219], s[68:69], 0, v[158:159]
	s_add_i32 m0, s39, 0xe000
	s_nop 0
	global_load_lds_dwordx4 v[218:219], off
	s_waitcnt vmcnt(8)
	s_waitcnt lgkmcnt(0)
	s_setprio 1
	s_barrier
	v_mfma_f32_16x16x32_bf16 v[140:143], v[112:115], v[186:189], v[140:143]
	v_mfma_f32_16x16x32_bf16 v[136:139], v[120:123], v[186:189], v[136:139]
	v_mfma_f32_16x16x32_bf16 v[108:111], v[112:115], v[194:197], v[108:111]
	v_mfma_f32_16x16x32_bf16 v[104:107], v[120:123], v[194:197], v[104:107]
	v_mfma_f32_16x16x32_bf16 v[92:95], v[112:115], v[202:205], v[92:95]
	v_mfma_f32_16x16x32_bf16 v[88:91], v[120:123], v[202:205], v[88:91]
	v_mfma_f32_16x16x32_bf16 v[76:79], v[112:115], v[210:213], v[76:79]
	v_mfma_f32_16x16x32_bf16 v[72:75], v[120:123], v[210:213], v[72:75]
	v_mfma_f32_16x16x32_bf16 v[140:143], v[116:119], v[190:193], v[140:143]
	v_mfma_f32_16x16x32_bf16 v[136:139], v[124:127], v[190:193], v[136:139]
	v_mfma_f32_16x16x32_bf16 v[108:111], v[116:119], v[198:201], v[108:111]
	v_mfma_f32_16x16x32_bf16 v[104:107], v[124:127], v[198:201], v[104:107]
	v_mfma_f32_16x16x32_bf16 v[92:95], v[116:119], v[206:209], v[92:95]
	v_mfma_f32_16x16x32_bf16 v[88:91], v[124:127], v[206:209], v[88:91]
	v_mfma_f32_16x16x32_bf16 v[76:79], v[116:119], v[214:217], v[76:79]
	v_mfma_f32_16x16x32_bf16 v[72:75], v[124:127], v[214:217], v[72:75]
	v_mfma_f32_16x16x32_bf16 v[132:135], v[164:167], v[186:189], v[132:135]
	v_mfma_f32_16x16x32_bf16 v[128:131], v[178:181], v[186:189], v[128:131]
	v_mfma_f32_16x16x32_bf16 v[100:103], v[164:167], v[194:197], v[100:103]
	v_mfma_f32_16x16x32_bf16 v[96:99], v[178:181], v[194:197], v[96:99]
	v_mfma_f32_16x16x32_bf16 v[84:87], v[164:167], v[202:205], v[84:87]
	v_mfma_f32_16x16x32_bf16 v[80:83], v[178:181], v[202:205], v[80:83]
	v_mfma_f32_16x16x32_bf16 v[68:71], v[164:167], v[210:213], v[68:71]
	v_mfma_f32_16x16x32_bf16 v[64:67], v[178:181], v[210:213], v[64:67]
	v_mfma_f32_16x16x32_bf16 v[132:135], v[168:171], v[190:193], v[132:135]
	v_mfma_f32_16x16x32_bf16 v[128:131], v[182:185], v[190:193], v[128:131]
	v_mfma_f32_16x16x32_bf16 v[100:103], v[168:171], v[198:201], v[100:103]
	v_mfma_f32_16x16x32_bf16 v[96:99], v[182:185], v[198:201], v[96:99]
	v_mfma_f32_16x16x32_bf16 v[84:87], v[168:171], v[206:209], v[84:87]
	v_mfma_f32_16x16x32_bf16 v[80:83], v[182:185], v[206:209], v[80:83]
	s_setprio 2
	s_barrier
	v_mfma_f32_16x16x32_bf16 v[68:71], v[168:171], v[214:217], v[68:71]
	v_mfma_f32_16x16x32_bf16 v[64:67], v[182:185], v[214:217], v[64:67]
	s_setprio 0
	s_add_i32 s52, s81, s29
	v_lshl_add_u64 v[218:219], s[70:71], 0, v[152:153]
	s_mov_b32 m0, s52
	ds_read_b128 v[186:189], v176 offset:16384
	ds_read_b128 v[190:193], v176 offset:17408
	ds_read_b128 v[194:197], v176 offset:18432
	ds_read_b128 v[198:201], v176 offset:19456
	ds_read_b128 v[202:205], v176 offset:20480
	ds_read_b128 v[206:209], v176 offset:21504
	ds_read_b128 v[210:213], v176 offset:22528
	ds_read_b128 v[214:217], v176 offset:23552
	global_load_lds_dwordx4 v[218:219], off
	s_add_i32 m0, s52, 0x2000
	s_add_u32 s52, s70, 0x80000
	v_lshl_add_u64 v[220:221], s[70:71], 0, v[148:149]
	s_addc_u32 s53, s71, 0
	s_add_i32 s56, s82, s29
	global_load_lds_dwordx4 v[220:221], off
	v_lshl_add_u64 v[222:223], s[52:53], 0, v[152:153]
	s_mov_b32 m0, s56
	v_lshl_add_u64 v[224:225], s[72:73], 0, v[150:151]
	global_load_lds_dwordx4 v[222:223], off
	v_lshl_add_u64 v[222:223], s[52:53], 0, v[148:149]
	s_add_i32 m0, s56, 0x2000
	s_nop 0
	global_load_lds_dwordx4 v[222:223], off
	v_lshl_add_u64 v[222:223], s[72:73], 0, v[154:155]
	s_mov_b32 m0, s39
	s_nop 0
	global_load_lds_dwordx4 v[222:223], off
	s_mov_b32 m0, s55
	s_nop 0
	global_load_lds_dwordx4 v[224:225], off
	s_waitcnt vmcnt(8)
	s_waitcnt lgkmcnt(0)
	s_setprio 1
	s_barrier
; #define PG8_STAGE(bufoff, gbase, voff) do { _Pragma("unroll") for (int _i = 0; _i < 2; ++_i) \
;         __builtin_amdgcn_global_load_lds((const unsigned*)((const char*)(gbase) + (voff)[_i]), (PG8_LAS unsigned*)(lds + (bufoff) + ldsw + _i * 8192), 16, 0, 0); } while (0)
; #define PG8_LDA(dst, b, h) do { _Pragma("unroll") for (int m = 0; m < 4; ++m) _Pragma("unroll") for (int k = 0; k < 2; ++k) dst[m][k] = *(const PG8_LAS bf16x8*)(lds + PG8_SA(b, h) + aoff + m * 2048 + k * 1024); } while (0)
; #define PG8_LDB(dst, b, h) do { _Pragma("unroll") for (int n = 0; n < 2; ++n) _Pragma("unroll") for (int k = 0; k < 2; ++k) dst[n][k] = *(const PG8_LAS bf16x8*)(lds + PG8_SB(b, h) + boff + n * 2048 + k * 1024); } while (0)
; #define PG8_MMA(ai, bj, At, Bt) do { __builtin_amdgcn_s_setprio(1); _Pragma("unroll") for (int m = 0; m < 4; ++m) _Pragma("unroll") for (int n = 0; n < 2; ++n) _Pragma("unroll") for (int k = 0; k < 2; ++k) \
;         acc[ai][bj][m][n] = __builtin_amdgcn_mfma_f32_16x16x32_bf16(Bt[n][k], At[m][k], acc[ai][bj][m][n], 0, 0, 0); __builtin_amdgcn_s_setprio(0); } while (0)
; #define PG8_WAIT_V(n) asm volatile("s_waitcnt vmcnt(" #n ")" ::: "memory")
; #define PG8_WAIT_L(n) asm volatile("s_waitcnt lgkmcnt(" #n ")" ::: "memory")
; #define PG8_BAR __builtin_amdgcn_s_barrier()
; #define PG8_SCHED __builtin_amdgcn_sched_barrier(0)
; template <class Epi, class Sched, bool ALIGN_EPI = false, bool SP2 = false>
; __device__ __forceinline__ void gemm_phase(PG8_LAS unsigned char* lds, const Gemm g, const Sched& S, const Epi& E) {
;     ...
;             PG8_WAIT_V(8); PG8_WAIT_L(0); PG8_BAR; PG8_MMA(1, 0, At, B0); PG8_MMA(1, 1, At, B1); PG8_BAR; PG8_SCHED;
;             PG8_LDB(B0, 1, 0); PG8_LDB(B1, 1, 1); PG8_SCHED; PG8_LDA(At, 1, 0); PG8_STAGE(PG8_SA(0, 1), a2 + hstep, voffA);
;             PG8_WAIT_V(8); PG8_WAIT_L(0); PG8_BAR; PG8_MMA(0, 0, At, B0); PG8_MMA(0, 1, At, B1); PG8_BAR; PG8_SCHED;
	v_mfma_f32_16x16x32_bf16 v[60:63], v[112:115], v[186:189], v[60:63]
	v_mfma_f32_16x16x32_bf16 v[56:59], v[120:123], v[186:189], v[56:59]
	v_mfma_f32_16x16x32_bf16 v[44:47], v[112:115], v[194:197], v[44:47]
	v_mfma_f32_16x16x32_bf16 v[40:43], v[120:123], v[194:197], v[40:43]
	v_mfma_f32_16x16x32_bf16 v[28:31], v[112:115], v[202:205], v[28:31]
	v_mfma_f32_16x16x32_bf16 v[24:27], v[120:123], v[202:205], v[24:27]
	v_mfma_f32_16x16x32_bf16 v[12:15], v[112:115], v[210:213], v[12:15]
	v_mfma_f32_16x16x32_bf16 v[8:11], v[120:123], v[210:213], v[8:11]
	v_mfma_f32_16x16x32_bf16 v[60:63], v[116:119], v[190:193], v[60:63]
	v_mfma_f32_16x16x32_bf16 v[56:59], v[124:127], v[190:193], v[56:59]
	v_mfma_f32_16x16x32_bf16 v[44:47], v[116:119], v[198:201], v[44:47]
	v_mfma_f32_16x16x32_bf16 v[40:43], v[124:127], v[198:201], v[40:43]
	v_mfma_f32_16x16x32_bf16 v[28:31], v[116:119], v[206:209], v[28:31]
	v_mfma_f32_16x16x32_bf16 v[24:27], v[124:127], v[206:209], v[24:27]
	v_mfma_f32_16x16x32_bf16 v[12:15], v[116:119], v[214:217], v[12:15]
	v_mfma_f32_16x16x32_bf16 v[8:11], v[124:127], v[214:217], v[8:11]
	v_mfma_f32_16x16x32_bf16 v[52:55], v[164:167], v[186:189], v[52:55]
	v_mfma_f32_16x16x32_bf16 v[48:51], v[178:181], v[186:189], v[48:51]
	v_mfma_f32_16x16x32_bf16 v[36:39], v[164:167], v[194:197], v[36:39]
	v_mfma_f32_16x16x32_bf16 v[32:35], v[178:181], v[194:197], v[32:35]
	v_mfma_f32_16x16x32_bf16 v[20:23], v[164:167], v[202:205], v[20:23]
	v_mfma_f32_16x16x32_bf16 v[16:19], v[178:181], v[202:205], v[16:19]
	v_mfma_f32_16x16x32_bf16 v[4:7], v[164:167], v[210:213], v[4:7]
	v_mfma_f32_16x16x32_bf16 v[0:3], v[178:181], v[210:213], v[0:3]
	v_mfma_f32_16x16x32_bf16 v[52:55], v[168:171], v[190:193], v[52:55]
	v_mfma_f32_16x16x32_bf16 v[48:51], v[182:185], v[190:193], v[48:51]
	v_mfma_f32_16x16x32_bf16 v[36:39], v[168:171], v[198:201], v[36:39]
	v_mfma_f32_16x16x32_bf16 v[32:35], v[182:185], v[198:201], v[32:35]
	v_mfma_f32_16x16x32_bf16 v[20:23], v[168:171], v[206:209], v[20:23]
	v_mfma_f32_16x16x32_bf16 v[16:19], v[182:185], v[206:209], v[16:19]
	s_setprio 2
	s_barrier
	v_mfma_f32_16x16x32_bf16 v[4:7], v[168:171], v[214:217], v[4:7]
	v_mfma_f32_16x16x32_bf16 v[0:3], v[182:185], v[214:217], v[0:3]
	s_setprio 0
	s_add_i32 s56, 0, 0x18000
	s_add_i32 s57, 0, 0x1c000
	v_add_u32_e32 v124, s56, v172
	v_add_u32_e32 v177, s57, v172
	ds_read_b128 v[112:115], v124
	ds_read_b128 v[116:119], v124 offset:1024
	ds_read_b128 v[120:123], v124 offset:2048
	ds_read_b128 v[124:127], v124 offset:3072
	ds_read_b128 v[164:167], v177
	ds_read_b128 v[168:171], v177 offset:1024
	ds_read_b128 v[178:181], v177 offset:2048
	ds_read_b128 v[182:185], v177 offset:3072
	s_add_u32 s52, s72, 0x80000
	s_addc_u32 s53, s73, 0
	s_mov_b32 m0, s74
	v_lshl_add_u64 v[226:227], s[52:53], 0, v[154:155]
	ds_read_b128 v[186:189], v176 offset:32768
	ds_read_b128 v[190:193], v176 offset:33792
	ds_read_b128 v[194:197], v176 offset:34816
	ds_read_b128 v[198:201], v176 offset:35840
	ds_read_b128 v[202:205], v176 offset:36864
	ds_read_b128 v[206:209], v176 offset:37888
	ds_read_b128 v[210:213], v176 offset:38912
	ds_read_b128 v[214:217], v176 offset:39936
	global_load_lds_dwordx4 v[226:227], off
	v_lshl_add_u64 v[226:227], s[52:53], 0, v[150:151]
	s_mov_b32 m0, s75
	s_nop 0
	global_load_lds_dwordx4 v[226:227], off
	s_waitcnt vmcnt(8)
	s_waitcnt lgkmcnt(0)
	s_setprio 1
	s_barrier
	v_mfma_f32_16x16x32_bf16 v[140:143], v[112:115], v[186:189], v[140:143]
	v_mfma_f32_16x16x32_bf16 v[136:139], v[120:123], v[186:189], v[136:139]
	v_mfma_f32_16x16x32_bf16 v[108:111], v[112:115], v[194:197], v[108:111]
	v_mfma_f32_16x16x32_bf16 v[104:107], v[120:123], v[194:197], v[104:107]
	v_mfma_f32_16x16x32_bf16 v[92:95], v[112:115], v[202:205], v[92:95]
	v_mfma_f32_16x16x32_bf16 v[88:91], v[120:123], v[202:205], v[88:91]
	v_mfma_f32_16x16x32_bf16 v[76:79], v[112:115], v[210:213], v[76:79]
	v_mfma_f32_16x16x32_bf16 v[72:75], v[120:123], v[210:213], v[72:75]
	v_mfma_f32_16x16x32_bf16 v[140:143], v[116:119], v[190:193], v[140:143]
	v_mfma_f32_16x16x32_bf16 v[136:139], v[124:127], v[190:193], v[136:139]
	v_mfma_f32_16x16x32_bf16 v[108:111], v[116:119], v[198:201], v[108:111]
	v_mfma_f32_16x16x32_bf16 v[104:107], v[124:127], v[198:201], v[104:107]
	v_mfma_f32_16x16x32_bf16 v[92:95], v[116:119], v[206:209], v[92:95]
	v_mfma_f32_16x16x32_bf16 v[88:91], v[124:127], v[206:209], v[88:91]
	v_mfma_f32_16x16x32_bf16 v[76:79], v[116:119], v[214:217], v[76:79]
	v_mfma_f32_16x16x32_bf16 v[72:75], v[124:127], v[214:217], v[72:75]
	v_mfma_f32_16x16x32_bf16 v[132:135], v[164:167], v[186:189], v[132:135]
	v_mfma_f32_16x16x32_bf16 v[128:131], v[178:181], v[186:189], v[128:131]
	v_mfma_f32_16x16x32_bf16 v[100:103], v[164:167], v[194:197], v[100:103]
	v_mfma_f32_16x16x32_bf16 v[96:99], v[178:181], v[194:197], v[96:99]
	v_mfma_f32_16x16x32_bf16 v[84:87], v[164:167], v[202:205], v[84:87]
	v_mfma_f32_16x16x32_bf16 v[80:83], v[178:181], v[202:205], v[80:83]
	v_mfma_f32_16x16x32_bf16 v[68:71], v[164:167], v[210:213], v[68:71]
	v_mfma_f32_16x16x32_bf16 v[64:67], v[178:181], v[210:213], v[64:67]
	v_mfma_f32_16x16x32_bf16 v[132:135], v[168:171], v[190:193], v[132:135]
	v_mfma_f32_16x16x32_bf16 v[128:131], v[182:185], v[190:193], v[128:131]
	v_mfma_f32_16x16x32_bf16 v[100:103], v[168:171], v[198:201], v[100:103]
	v_mfma_f32_16x16x32_bf16 v[96:99], v[182:185], v[198:201], v[96:99]
	v_mfma_f32_16x16x32_bf16 v[84:87], v[168:171], v[206:209], v[84:87]
	v_mfma_f32_16x16x32_bf16 v[80:83], v[182:185], v[206:209], v[80:83]
	s_setprio 2
	s_barrier
; #define PG8_STAGE(bufoff, gbase, voff) do { _Pragma("unroll") for (int _i = 0; _i < 2; ++_i) \
;         __builtin_amdgcn_global_load_lds((const unsigned*)((const char*)(gbase) + (voff)[_i]), (PG8_LAS unsigned*)(lds + (bufoff) + ldsw + _i * 8192), 16, 0, 0); } while (0)
; #define PG8_LDA(dst, b, h) do { _Pragma("unroll") for (int m = 0; m < 4; ++m) _Pragma("unroll") for (int k = 0; k < 2; ++k) dst[m][k] = *(const PG8_LAS bf16x8*)(lds + PG8_SA(b, h) + aoff + m * 2048 + k * 1024); } while (0)
; #define PG8_MMA(ai, bj, At, Bt) do { __builtin_amdgcn_s_setprio(1); _Pragma("unroll") for (int m = 0; m < 4; ++m) _Pragma("unroll") for (int n = 0; n < 2; ++n) _Pragma("unroll") for (int k = 0; k < 2; ++k) \
;         acc[ai][bj][m][n] = __builtin_amdgcn_mfma_f32_16x16x32_bf16(Bt[n][k], At[m][k], acc[ai][bj][m][n], 0, 0, 0); __builtin_amdgcn_s_setprio(0); } while (0)
; #define PG8_WAIT_V(n) asm volatile("s_waitcnt vmcnt(" #n ")" ::: "memory")
; #define PG8_WAIT_L(n) asm volatile("s_waitcnt lgkmcnt(" #n ")" ::: "memory")
; #define PG8_BAR __builtin_amdgcn_s_barrier()
; #define PG8_SCHED __builtin_amdgcn_sched_barrier(0)
; template <class Epi, class Sched, bool ALIGN_EPI = false, bool SP2 = false>
; __device__ __forceinline__ void gemm_phase(PG8_LAS unsigned char* lds, const Gemm g, const Sched& S, const Epi& E) {
;     ...
;             PG8_WAIT_V(8); PG8_WAIT_L(0); PG8_BAR; PG8_MMA(0, 0, At, B0); PG8_MMA(0, 1, At, B1); PG8_BAR; PG8_SCHED;
;             PG8_LDA(At, 1, 1); PG8_STAGE(PG8_SB(1, 0), b3, voffB); PG8_STAGE(PG8_SB(1, 1), b3 + hstep, voffB); PG8_STAGE(PG8_SA(1, 0), a3, voffA);
;             PG8_WAIT_V(8); PG8_WAIT_L(0); PG8_BAR; PG8_MMA(1, 0, At, B0); PG8_MMA(1, 1, At, B1); PG8_BAR; PG8_SCHED;
;     ...
;         if constexpr (ALIGN_EPI) { if (wr == 0) PG8_BAR; }
	v_mfma_f32_16x16x32_bf16 v[68:71], v[168:171], v[214:217], v[68:71]
	v_mfma_f32_16x16x32_bf16 v[64:67], v[182:185], v[214:217], v[64:67]
	s_setprio 0
	s_add_i32 s52, s56, s29
	v_lshl_add_u64 v[218:219], v[218:219], 0, s[12:13]
	s_mov_b32 m0, s52
	ds_read_b128 v[186:189], v176 offset:49152
	ds_read_b128 v[190:193], v176 offset:50176
	ds_read_b128 v[194:197], v176 offset:51200
	ds_read_b128 v[198:201], v176 offset:52224
	ds_read_b128 v[202:205], v176 offset:53248
	ds_read_b128 v[206:209], v176 offset:54272
	ds_read_b128 v[210:213], v176 offset:55296
	ds_read_b128 v[214:217], v176 offset:56320
	global_load_lds_dwordx4 v[218:219], off
	s_add_i32 m0, s52, 0x2000
	s_add_u32 s52, s70, 0x80080
	v_lshl_add_u64 v[218:219], v[220:221], 0, s[12:13]
	s_addc_u32 s53, s71, 0
	s_add_i32 s56, s57, s29
	global_load_lds_dwordx4 v[218:219], off
	v_lshl_add_u64 v[218:219], s[52:53], 0, v[152:153]
	s_mov_b32 m0, s56
	s_nop 0
	global_load_lds_dwordx4 v[218:219], off
	v_lshl_add_u64 v[218:219], s[52:53], 0, v[148:149]
	s_add_i32 m0, s56, 0x2000
	s_nop 0
	global_load_lds_dwordx4 v[218:219], off
	v_lshl_add_u64 v[218:219], v[222:223], 0, s[12:13]
	s_mov_b32 m0, s77
	s_nop 0
	global_load_lds_dwordx4 v[218:219], off
	v_lshl_add_u64 v[218:219], v[224:225], 0, s[12:13]
	s_mov_b32 m0, s78
	s_nop 0
	global_load_lds_dwordx4 v[218:219], off
	s_waitcnt vmcnt(8)
	s_waitcnt lgkmcnt(0)
	s_setprio 1
	s_barrier
	v_mfma_f32_16x16x32_bf16 v[60:63], v[112:115], v[186:189], v[60:63]
	v_mfma_f32_16x16x32_bf16 v[56:59], v[120:123], v[186:189], v[56:59]
	v_mfma_f32_16x16x32_bf16 v[44:47], v[112:115], v[194:197], v[44:47]
	v_mfma_f32_16x16x32_bf16 v[40:43], v[120:123], v[194:197], v[40:43]
	v_mfma_f32_16x16x32_bf16 v[28:31], v[112:115], v[202:205], v[28:31]
	v_mfma_f32_16x16x32_bf16 v[24:27], v[120:123], v[202:205], v[24:27]
	v_mfma_f32_16x16x32_bf16 v[12:15], v[112:115], v[210:213], v[12:15]
	v_mfma_f32_16x16x32_bf16 v[8:11], v[120:123], v[210:213], v[8:11]
	v_mfma_f32_16x16x32_bf16 v[60:63], v[116:119], v[190:193], v[60:63]
	v_mfma_f32_16x16x32_bf16 v[56:59], v[124:127], v[190:193], v[56:59]
	v_mfma_f32_16x16x32_bf16 v[44:47], v[116:119], v[198:201], v[44:47]
	v_mfma_f32_16x16x32_bf16 v[40:43], v[124:127], v[198:201], v[40:43]
	v_mfma_f32_16x16x32_bf16 v[28:31], v[116:119], v[206:209], v[28:31]
	v_mfma_f32_16x16x32_bf16 v[24:27], v[124:127], v[206:209], v[24:27]
	v_mfma_f32_16x16x32_bf16 v[12:15], v[116:119], v[214:217], v[12:15]
	v_mfma_f32_16x16x32_bf16 v[8:11], v[124:127], v[214:217], v[8:11]
	v_mfma_f32_16x16x32_bf16 v[52:55], v[164:167], v[186:189], v[52:55]
	v_mfma_f32_16x16x32_bf16 v[48:51], v[178:181], v[186:189], v[48:51]
	v_mfma_f32_16x16x32_bf16 v[36:39], v[164:167], v[194:197], v[36:39]
	v_mfma_f32_16x16x32_bf16 v[32:35], v[178:181], v[194:197], v[32:35]
	v_mfma_f32_16x16x32_bf16 v[20:23], v[164:167], v[202:205], v[20:23]
	v_mfma_f32_16x16x32_bf16 v[16:19], v[178:181], v[202:205], v[16:19]
	v_mfma_f32_16x16x32_bf16 v[4:7], v[164:167], v[210:213], v[4:7]
	v_mfma_f32_16x16x32_bf16 v[0:3], v[178:181], v[210:213], v[0:3]
	v_mfma_f32_16x16x32_bf16 v[52:55], v[168:171], v[190:193], v[52:55]
	v_mfma_f32_16x16x32_bf16 v[48:51], v[182:185], v[190:193], v[48:51]
	v_mfma_f32_16x16x32_bf16 v[36:39], v[168:171], v[198:201], v[36:39]
	v_mfma_f32_16x16x32_bf16 v[32:35], v[182:185], v[198:201], v[32:35]
	v_mfma_f32_16x16x32_bf16 v[20:23], v[168:171], v[206:209], v[20:23]
	v_mfma_f32_16x16x32_bf16 v[16:19], v[182:185], v[206:209], v[16:19]
	s_setprio 2
	s_barrier
	v_mfma_f32_16x16x32_bf16 v[4:7], v[168:171], v[214:217], v[4:7]
	v_mfma_f32_16x16x32_bf16 v[0:3], v[182:185], v[214:217], v[0:3]
	s_setprio 0
	s_add_i32 s88, s88, 2
	s_add_u32 s68, s68, 0x100
	s_addc_u32 s69, s69, 0
	s_add_u32 s86, s86, 0x100
	s_addc_u32 s87, s87, 0
	s_cmp_gt_u32 s88, 29
	s_cbranch_scc0 .LBB0_545
	s_and_b64 vcc, exec, s[14:15]
	s_cbranch_vccz .LBB0_548
	s_barrier

; #define PG8_STAGE(bufoff, gbase, voff) do { _Pragma("unroll") for (int _i = 0; _i < 2; ++_i) \
;         __builtin_amdgcn_global_load_lds((const unsigned*)((const char*)(gbase) + (voff)[_i]), (PG8_LAS unsigned*)(lds + (bufoff) + ldsw + _i * 8192), 16, 0, 0); } while (0)
; #define PG8_LDA(dst, b, h) do { _Pragma("unroll") for (int m = 0; m < 4; ++m) _Pragma("unroll") for (int k = 0; k < 2; ++k) dst[m][k] = *(const PG8_LAS bf16x8*)(lds + PG8_SA(b, h) + aoff + m * 2048 + k * 1024); } while (0)
; #define PG8_LDB(dst, b, h) do { _Pragma("unroll") for (int n = 0; n < 2; ++n) _Pragma("unroll") for (int k = 0; k < 2; ++k) dst[n][k] = *(const PG8_LAS bf16x8*)(lds + PG8_SB(b, h) + boff + n * 2048 + k * 1024); } while (0)
; #define PG8_MMA(ai, bj, At, Bt) do { __builtin_amdgcn_s_setprio(1); _Pragma("unroll") for (int m = 0; m < 4; ++m) _Pragma("unroll") for (int n = 0; n < 2; ++n) _Pragma("unroll") for (int k = 0; k < 2; ++k) \
;         acc[ai][bj][m][n] = __builtin_amdgcn_mfma_f32_16x16x32_bf16(Bt[n][k], At[m][k], acc[ai][bj][m][n], 0, 0, 0); __builtin_amdgcn_s_setprio(0); } while (0)
; #define PG8_WAIT_V(n) asm volatile("s_waitcnt vmcnt(" #n ")" ::: "memory")
; #define PG8_WAIT_L(n) asm volatile("s_waitcnt lgkmcnt(" #n ")" ::: "memory")
; #define PG8_BAR __builtin_amdgcn_s_barrier()
; template <class Epi, class Sched, bool ALIGN_EPI = false, bool SP2 = false>
; __device__ __forceinline__ void gemm_phase(PG8_LAS unsigned char* lds, const Gemm g, const Sched& S, const Epi& E) {
;     ...
;         for (int t = 0; t < nt; t += 2) {
;             const bool last = (t == nt - 2);
;             const char* a1 = cA + (size_t)(t + 1) * kstep;
;             const char* a2 = last ? nA : cA + (size_t)(t + 2) * kstep; const char* b2 = last ? nB : cB + (size_t)(t + 2) * kstep;
;             const char* a3 = a2 + kstep; const char* b3 = b2 + kstep;
;             if constexpr (SP2) {
;             PG8_LDB(B0, 0, 0); PG8_LDB(B1, 0, 1); PG8_SCHED; PG8_LDA(At, 0, 0); PG8_STAGE(PG8_SA(1, 1), a1 + hstep, voffA);
;             PG8_WAIT_V(8); PG8_WAIT_L(0); PG8_BAR; PG8_MMA(0, 0, At, B0); PG8_MMA(0, 1, At, B1); PG8_BAR; PG8_SCHED;
;             PG8_LDA(At, 0, 1); PG8_STAGE(PG8_SB(0, 0), b2, voffB); PG8_STAGE(PG8_SB(0, 1), b2 + hstep, voffB); PG8_STAGE(PG8_SA(0, 0), a2, voffA);
;             PG8_WAIT_V(8); PG8_WAIT_L(0); PG8_BAR; PG8_MMA(1, 0, At, B0); PG8_MMA(1, 1, At, B1); PG8_BAR; PG8_SCHED;
.LBB0_624:
	ds_read_b128 v[128:131], v214
	ds_read_b128 v[132:135], v214 offset:1024
	ds_read_b128 v[158:161], v214 offset:2048
	ds_read_b128 v[162:165], v214 offset:3072
	ds_read_b128 v[166:169], v215
	ds_read_b128 v[170:173], v215 offset:1024
	ds_read_b128 v[174:177], v215 offset:2048
	ds_read_b128 v[178:181], v215 offset:3072
	s_add_u32 s52, s74, 0xffe00080
	s_addc_u32 s53, s75, -1
	s_cmpk_eq_i32 vcc_hi, 0x7c
	s_cselect_b32 s79, s51, s53
	s_cselect_b32 s78, s71, s52
	s_cselect_b32 s77, s49, vcc_lo
	s_cselect_b32 s76, s73, s93
	v_lshl_add_u64 v[226:227], s[74:75], 0, v[150:151]
	s_add_i32 m0, s83, 0xc000
	ds_read_b128 v[182:185], v216
	ds_read_b128 v[186:189], v216 offset:1024
	ds_read_b128 v[190:193], v216 offset:2048
	ds_read_b128 v[194:197], v216 offset:3072
	ds_read_b128 v[198:201], v216 offset:4096
	ds_read_b128 v[202:205], v216 offset:5120
	ds_read_b128 v[218:221], v216 offset:6144
	ds_read_b128 v[222:225], v216 offset:7168
	global_load_lds_dwordx4 v[226:227], off
	v_lshl_add_u64 v[226:227], s[74:75], 0, v[152:153]
	s_add_i32 m0, s83, 0xe000
	s_nop 0
	global_load_lds_dwordx4 v[226:227], off
	s_waitcnt vmcnt(8)
	s_waitcnt lgkmcnt(0)
	s_setprio 1
	s_barrier
	v_mfma_f32_16x16x32_bf16 v[124:127], v[128:131], v[182:185], v[124:127]
	v_mfma_f32_16x16x32_bf16 v[120:123], v[158:161], v[182:185], v[120:123]
	v_mfma_f32_16x16x32_bf16 v[116:119], v[128:131], v[190:193], v[116:119]
	v_mfma_f32_16x16x32_bf16 v[112:115], v[158:161], v[190:193], v[112:115]
	v_mfma_f32_16x16x32_bf16 v[108:111], v[128:131], v[198:201], v[108:111]
	v_mfma_f32_16x16x32_bf16 v[104:107], v[158:161], v[198:201], v[104:107]
	v_mfma_f32_16x16x32_bf16 v[100:103], v[128:131], v[218:221], v[100:103]
	v_mfma_f32_16x16x32_bf16 v[96:99], v[158:161], v[218:221], v[96:99]
	v_mfma_f32_16x16x32_bf16 v[124:127], v[132:135], v[186:189], v[124:127]
	v_mfma_f32_16x16x32_bf16 v[120:123], v[162:165], v[186:189], v[120:123]
	v_mfma_f32_16x16x32_bf16 v[116:119], v[132:135], v[194:197], v[116:119]
	v_mfma_f32_16x16x32_bf16 v[112:115], v[162:165], v[194:197], v[112:115]
	v_mfma_f32_16x16x32_bf16 v[108:111], v[132:135], v[202:205], v[108:111]
	v_mfma_f32_16x16x32_bf16 v[104:107], v[162:165], v[202:205], v[104:107]
	v_mfma_f32_16x16x32_bf16 v[100:103], v[132:135], v[222:225], v[100:103]
	v_mfma_f32_16x16x32_bf16 v[96:99], v[162:165], v[222:225], v[96:99]
	v_mfma_f32_16x16x32_bf16 v[60:63], v[166:169], v[182:185], v[60:63]
	v_mfma_f32_16x16x32_bf16 v[56:59], v[174:177], v[182:185], v[56:59]
	v_mfma_f32_16x16x32_bf16 v[52:55], v[166:169], v[190:193], v[52:55]
	v_mfma_f32_16x16x32_bf16 v[48:51], v[174:177], v[190:193], v[48:51]
	v_mfma_f32_16x16x32_bf16 v[44:47], v[166:169], v[198:201], v[44:47]
	v_mfma_f32_16x16x32_bf16 v[40:43], v[174:177], v[198:201], v[40:43]
	v_mfma_f32_16x16x32_bf16 v[36:39], v[166:169], v[218:221], v[36:39]
	v_mfma_f32_16x16x32_bf16 v[32:35], v[174:177], v[218:221], v[32:35]
	v_mfma_f32_16x16x32_bf16 v[60:63], v[170:173], v[186:189], v[60:63]
	v_mfma_f32_16x16x32_bf16 v[56:59], v[178:181], v[186:189], v[56:59]
	v_mfma_f32_16x16x32_bf16 v[52:55], v[170:173], v[194:197], v[52:55]
	v_mfma_f32_16x16x32_bf16 v[48:51], v[178:181], v[194:197], v[48:51]
	v_mfma_f32_16x16x32_bf16 v[44:47], v[170:173], v[202:205], v[44:47]
	v_mfma_f32_16x16x32_bf16 v[40:43], v[178:181], v[202:205], v[40:43]
	s_setprio 2
	s_barrier
	v_mfma_f32_16x16x32_bf16 v[36:39], v[170:173], v[222:225], v[36:39]
	v_mfma_f32_16x16x32_bf16 v[32:35], v[178:181], v[222:225], v[32:35]
	s_setprio 0
	s_add_i32 s52, s33, s82
	v_lshl_add_u64 v[226:227], s[76:77], 0, v[138:139]
	s_mov_b32 m0, s52
	ds_read_b128 v[182:185], v216 offset:16384
	ds_read_b128 v[186:189], v216 offset:17408
	ds_read_b128 v[190:193], v216 offset:18432
	ds_read_b128 v[194:197], v216 offset:19456
	ds_read_b128 v[198:201], v216 offset:20480
	ds_read_b128 v[202:205], v216 offset:21504
	ds_read_b128 v[218:221], v216 offset:22528
	ds_read_b128 v[222:225], v216 offset:23552
	global_load_lds_dwordx4 v[226:227], off
	s_add_i32 m0, s52, 0x2000
	s_add_u32 s52, s76, 0x200000
	v_lshl_add_u64 v[228:229], s[76:77], 0, v[142:143]
	s_addc_u32 s53, s77, 0
	s_add_i32 s56, s92, s82
	global_load_lds_dwordx4 v[228:229], off
	v_lshl_add_u64 v[230:231], s[52:53], 0, v[138:139]
	s_mov_b32 m0, s56
	v_lshl_add_u64 v[232:233], s[78:79], 0, v[140:141]
	global_load_lds_dwordx4 v[230:231], off
	v_lshl_add_u64 v[230:231], s[52:53], 0, v[142:143]
	s_add_i32 m0, s56, 0x2000
	s_nop 0
	global_load_lds_dwordx4 v[230:231], off
	v_lshl_add_u64 v[230:231], s[78:79], 0, v[136:137]
	s_mov_b32 m0, s83
	s_nop 0
	global_load_lds_dwordx4 v[230:231], off
	s_mov_b32 m0, s84
	s_nop 0
	global_load_lds_dwordx4 v[232:233], off
	s_waitcnt vmcnt(8)
	s_waitcnt lgkmcnt(0)
	s_setprio 1
	s_barrier
; #define PG8_STAGE(bufoff, gbase, voff) do { _Pragma("unroll") for (int _i = 0; _i < 2; ++_i) \
;         __builtin_amdgcn_global_load_lds((const unsigned*)((const char*)(gbase) + (voff)[_i]), (PG8_LAS unsigned*)(lds + (bufoff) + ldsw + _i * 8192), 16, 0, 0); } while (0)
; #define PG8_LDA(dst, b, h) do { _Pragma("unroll") for (int m = 0; m < 4; ++m) _Pragma("unroll") for (int k = 0; k < 2; ++k) dst[m][k] = *(const PG8_LAS bf16x8*)(lds + PG8_SA(b, h) + aoff + m * 2048 + k * 1024); } while (0)
; #define PG8_LDB(dst, b, h) do { _Pragma("unroll") for (int n = 0; n < 2; ++n) _Pragma("unroll") for (int k = 0; k < 2; ++k) dst[n][k] = *(const PG8_LAS bf16x8*)(lds + PG8_SB(b, h) + boff + n * 2048 + k * 1024); } while (0)
; #define PG8_MMA(ai, bj, At, Bt) do { __builtin_amdgcn_s_setprio(1); _Pragma("unroll") for (int m = 0; m < 4; ++m) _Pragma("unroll") for (int n = 0; n < 2; ++n) _Pragma("unroll") for (int k = 0; k < 2; ++k) \
;         acc[ai][bj][m][n] = __builtin_amdgcn_mfma_f32_16x16x32_bf16(Bt[n][k], At[m][k], acc[ai][bj][m][n], 0, 0, 0); __builtin_amdgcn_s_setprio(0); } while (0)
; #define PG8_WAIT_V(n) asm volatile("s_waitcnt vmcnt(" #n ")" ::: "memory")
; #define PG8_WAIT_L(n) asm volatile("s_waitcnt lgkmcnt(" #n ")" ::: "memory")
; #define PG8_BAR __builtin_amdgcn_s_barrier()
; #define PG8_SCHED __builtin_amdgcn_sched_barrier(0)
; template <class Epi, class Sched, bool ALIGN_EPI = false, bool SP2 = false>
; __device__ __forceinline__ void gemm_phase(PG8_LAS unsigned char* lds, const Gemm g, const Sched& S, const Epi& E) {
;     ...
;             PG8_WAIT_V(8); PG8_WAIT_L(0); PG8_BAR; PG8_MMA(1, 0, At, B0); PG8_MMA(1, 1, At, B1); PG8_BAR; PG8_SCHED;
;             PG8_LDB(B0, 1, 0); PG8_LDB(B1, 1, 1); PG8_SCHED; PG8_LDA(At, 1, 0); PG8_STAGE(PG8_SA(0, 1), a2 + hstep, voffA);
;             PG8_WAIT_V(8); PG8_WAIT_L(0); PG8_BAR; PG8_MMA(0, 0, At, B0); PG8_MMA(0, 1, At, B1); PG8_BAR; PG8_SCHED;
	v_mfma_f32_16x16x32_bf16 v[92:95], v[128:131], v[182:185], v[92:95]
	v_mfma_f32_16x16x32_bf16 v[88:91], v[158:161], v[182:185], v[88:91]
	v_mfma_f32_16x16x32_bf16 v[84:87], v[128:131], v[190:193], v[84:87]
	v_mfma_f32_16x16x32_bf16 v[80:83], v[158:161], v[190:193], v[80:83]
	v_mfma_f32_16x16x32_bf16 v[76:79], v[128:131], v[198:201], v[76:79]
	v_mfma_f32_16x16x32_bf16 v[72:75], v[158:161], v[198:201], v[72:75]
	v_mfma_f32_16x16x32_bf16 v[68:71], v[128:131], v[218:221], v[68:71]
	v_mfma_f32_16x16x32_bf16 v[64:67], v[158:161], v[218:221], v[64:67]
	v_mfma_f32_16x16x32_bf16 v[92:95], v[132:135], v[186:189], v[92:95]
	v_mfma_f32_16x16x32_bf16 v[88:91], v[162:165], v[186:189], v[88:91]
	v_mfma_f32_16x16x32_bf16 v[84:87], v[132:135], v[194:197], v[84:87]
	v_mfma_f32_16x16x32_bf16 v[80:83], v[162:165], v[194:197], v[80:83]
	v_mfma_f32_16x16x32_bf16 v[76:79], v[132:135], v[202:205], v[76:79]
	v_mfma_f32_16x16x32_bf16 v[72:75], v[162:165], v[202:205], v[72:75]
	v_mfma_f32_16x16x32_bf16 v[68:71], v[132:135], v[222:225], v[68:71]
	v_mfma_f32_16x16x32_bf16 v[64:67], v[162:165], v[222:225], v[64:67]
	v_mfma_f32_16x16x32_bf16 v[28:31], v[166:169], v[182:185], v[28:31]
	v_mfma_f32_16x16x32_bf16 v[24:27], v[174:177], v[182:185], v[24:27]
	v_mfma_f32_16x16x32_bf16 v[20:23], v[166:169], v[190:193], v[20:23]
	v_mfma_f32_16x16x32_bf16 v[16:19], v[174:177], v[190:193], v[16:19]
	v_mfma_f32_16x16x32_bf16 v[12:15], v[166:169], v[198:201], v[12:15]
	v_mfma_f32_16x16x32_bf16 v[8:11], v[174:177], v[198:201], v[8:11]
	v_mfma_f32_16x16x32_bf16 v[4:7], v[166:169], v[218:221], v[4:7]
	v_mfma_f32_16x16x32_bf16 v[0:3], v[174:177], v[218:221], v[0:3]
	v_mfma_f32_16x16x32_bf16 v[28:31], v[170:173], v[186:189], v[28:31]
	v_mfma_f32_16x16x32_bf16 v[24:27], v[178:181], v[186:189], v[24:27]
	v_mfma_f32_16x16x32_bf16 v[20:23], v[170:173], v[194:197], v[20:23]
	v_mfma_f32_16x16x32_bf16 v[16:19], v[178:181], v[194:197], v[16:19]
	v_mfma_f32_16x16x32_bf16 v[12:15], v[170:173], v[202:205], v[12:15]
	v_mfma_f32_16x16x32_bf16 v[8:11], v[178:181], v[202:205], v[8:11]
	s_setprio 2
	s_barrier
	v_mfma_f32_16x16x32_bf16 v[4:7], v[170:173], v[222:225], v[4:7]
	v_mfma_f32_16x16x32_bf16 v[0:3], v[178:181], v[222:225], v[0:3]
	s_setprio 0
	s_add_i32 s56, 0, 0x18000
	s_add_i32 s57, 0, 0x1c000
	v_add_u32_e32 v162, s56, v212
	v_add_u32_e32 v178, s57, v212
	ds_read_b128 v[128:131], v162
	ds_read_b128 v[132:135], v162 offset:1024
	ds_read_b128 v[158:161], v162 offset:2048
	ds_read_b128 v[162:165], v162 offset:3072
	ds_read_b128 v[166:169], v178
	ds_read_b128 v[170:173], v178 offset:1024
	ds_read_b128 v[174:177], v178 offset:2048
	ds_read_b128 v[178:181], v178 offset:3072
	s_add_u32 s52, s78, 0x200000
	s_addc_u32 s53, s79, 0
	s_mov_b32 m0, s85
	v_lshl_add_u64 v[234:235], s[52:53], 0, v[136:137]
	ds_read_b128 v[182:185], v216 offset:32768
	ds_read_b128 v[186:189], v216 offset:33792
	ds_read_b128 v[190:193], v216 offset:34816
	ds_read_b128 v[194:197], v216 offset:35840
	ds_read_b128 v[198:201], v216 offset:36864
	ds_read_b128 v[202:205], v216 offset:37888
	ds_read_b128 v[218:221], v216 offset:38912
	ds_read_b128 v[222:225], v216 offset:39936
	global_load_lds_dwordx4 v[234:235], off
	v_lshl_add_u64 v[234:235], s[52:53], 0, v[140:141]
	s_mov_b32 m0, s86
	s_nop 0
	global_load_lds_dwordx4 v[234:235], off
	s_waitcnt vmcnt(8)
	s_waitcnt lgkmcnt(0)
	s_setprio 1
	s_barrier
	v_mfma_f32_16x16x32_bf16 v[124:127], v[128:131], v[182:185], v[124:127]
	v_mfma_f32_16x16x32_bf16 v[120:123], v[158:161], v[182:185], v[120:123]
	v_mfma_f32_16x16x32_bf16 v[116:119], v[128:131], v[190:193], v[116:119]
	v_mfma_f32_16x16x32_bf16 v[112:115], v[158:161], v[190:193], v[112:115]
	v_mfma_f32_16x16x32_bf16 v[108:111], v[128:131], v[198:201], v[108:111]
	v_mfma_f32_16x16x32_bf16 v[104:107], v[158:161], v[198:201], v[104:107]
	v_mfma_f32_16x16x32_bf16 v[100:103], v[128:131], v[218:221], v[100:103]
	v_mfma_f32_16x16x32_bf16 v[96:99], v[158:161], v[218:221], v[96:99]
	v_mfma_f32_16x16x32_bf16 v[124:127], v[132:135], v[186:189], v[124:127]
	v_mfma_f32_16x16x32_bf16 v[120:123], v[162:165], v[186:189], v[120:123]
	v_mfma_f32_16x16x32_bf16 v[116:119], v[132:135], v[194:197], v[116:119]
	v_mfma_f32_16x16x32_bf16 v[112:115], v[162:165], v[194:197], v[112:115]
	v_mfma_f32_16x16x32_bf16 v[108:111], v[132:135], v[202:205], v[108:111]
	v_mfma_f32_16x16x32_bf16 v[104:107], v[162:165], v[202:205], v[104:107]
	v_mfma_f32_16x16x32_bf16 v[100:103], v[132:135], v[222:225], v[100:103]
	v_mfma_f32_16x16x32_bf16 v[96:99], v[162:165], v[222:225], v[96:99]
	v_mfma_f32_16x16x32_bf16 v[60:63], v[166:169], v[182:185], v[60:63]
	v_mfma_f32_16x16x32_bf16 v[56:59], v[174:177], v[182:185], v[56:59]
	v_mfma_f32_16x16x32_bf16 v[52:55], v[166:169], v[190:193], v[52:55]
	v_mfma_f32_16x16x32_bf16 v[48:51], v[174:177], v[190:193], v[48:51]
	v_mfma_f32_16x16x32_bf16 v[44:47], v[166:169], v[198:201], v[44:47]
	v_mfma_f32_16x16x32_bf16 v[40:43], v[174:177], v[198:201], v[40:43]
	v_mfma_f32_16x16x32_bf16 v[36:39], v[166:169], v[218:221], v[36:39]
	v_mfma_f32_16x16x32_bf16 v[32:35], v[174:177], v[218:221], v[32:35]
	v_mfma_f32_16x16x32_bf16 v[60:63], v[170:173], v[186:189], v[60:63]
	v_mfma_f32_16x16x32_bf16 v[56:59], v[178:181], v[186:189], v[56:59]
	v_mfma_f32_16x16x32_bf16 v[52:55], v[170:173], v[194:197], v[52:55]
	v_mfma_f32_16x16x32_bf16 v[48:51], v[178:181], v[194:197], v[48:51]
	v_mfma_f32_16x16x32_bf16 v[44:47], v[170:173], v[202:205], v[44:47]
	v_mfma_f32_16x16x32_bf16 v[40:43], v[178:181], v[202:205], v[40:43]
	s_setprio 2
	s_barrier
; #define PG8_STAGE(bufoff, gbase, voff) do { _Pragma("unroll") for (int _i = 0; _i < 2; ++_i) \
;         __builtin_amdgcn_global_load_lds((const unsigned*)((const char*)(gbase) + (voff)[_i]), (PG8_LAS unsigned*)(lds + (bufoff) + ldsw + _i * 8192), 16, 0, 0); } while (0)
; #define PG8_LDA(dst, b, h) do { _Pragma("unroll") for (int m = 0; m < 4; ++m) _Pragma("unroll") for (int k = 0; k < 2; ++k) dst[m][k] = *(const PG8_LAS bf16x8*)(lds + PG8_SA(b, h) + aoff + m * 2048 + k * 1024); } while (0)
; #define PG8_MMA(ai, bj, At, Bt) do { __builtin_amdgcn_s_setprio(1); _Pragma("unroll") for (int m = 0; m < 4; ++m) _Pragma("unroll") for (int n = 0; n < 2; ++n) _Pragma("unroll") for (int k = 0; k < 2; ++k) \
;         acc[ai][bj][m][n] = __builtin_amdgcn_mfma_f32_16x16x32_bf16(Bt[n][k], At[m][k], acc[ai][bj][m][n], 0, 0, 0); __builtin_amdgcn_s_setprio(0); } while (0)
; #define PG8_WAIT_V(n) asm volatile("s_waitcnt vmcnt(" #n ")" ::: "memory")
; #define PG8_WAIT_L(n) asm volatile("s_waitcnt lgkmcnt(" #n ")" ::: "memory")
; #define PG8_BAR __builtin_amdgcn_s_barrier()
; #define PG8_SCHED __builtin_amdgcn_sched_barrier(0)
; template <class Epi, class Sched, bool ALIGN_EPI = false, bool SP2 = false>
; __device__ __forceinline__ void gemm_phase(PG8_LAS unsigned char* lds, const Gemm g, const Sched& S, const Epi& E) {
;     ...
;             PG8_WAIT_V(8); PG8_WAIT_L(0); PG8_BAR; PG8_MMA(0, 0, At, B0); PG8_MMA(0, 1, At, B1); PG8_BAR; PG8_SCHED;
;             PG8_LDA(At, 1, 1); PG8_STAGE(PG8_SB(1, 0), b3, voffB); PG8_STAGE(PG8_SB(1, 1), b3 + hstep, voffB); PG8_STAGE(PG8_SA(1, 0), a3, voffA);
;             PG8_WAIT_V(8); PG8_WAIT_L(0); PG8_BAR; PG8_MMA(1, 0, At, B0); PG8_MMA(1, 1, At, B1); PG8_BAR; PG8_SCHED;
;     ...
;         if constexpr (ALIGN_EPI) { if (wr == 0) PG8_BAR; }
	v_mfma_f32_16x16x32_bf16 v[36:39], v[170:173], v[222:225], v[36:39]
	v_mfma_f32_16x16x32_bf16 v[32:35], v[178:181], v[222:225], v[32:35]
	s_setprio 0
	s_add_i32 s52, s56, s82
	v_lshl_add_u64 v[226:227], v[226:227], 0, s[36:37]
	s_mov_b32 m0, s52
	ds_read_b128 v[182:185], v216 offset:49152
	ds_read_b128 v[186:189], v216 offset:50176
	ds_read_b128 v[190:193], v216 offset:51200
	ds_read_b128 v[194:197], v216 offset:52224
	ds_read_b128 v[198:201], v216 offset:53248
	ds_read_b128 v[202:205], v216 offset:54272
	ds_read_b128 v[218:221], v216 offset:55296
	ds_read_b128 v[222:225], v216 offset:56320
	global_load_lds_dwordx4 v[226:227], off
	s_add_i32 m0, s52, 0x2000
	s_add_u32 s52, s76, 0x200080
	v_lshl_add_u64 v[226:227], v[228:229], 0, s[36:37]
	s_addc_u32 s53, s77, 0
	s_add_i32 s56, s57, s82
	global_load_lds_dwordx4 v[226:227], off
	v_lshl_add_u64 v[226:227], s[52:53], 0, v[138:139]
	s_mov_b32 m0, s56
	s_nop 0
	global_load_lds_dwordx4 v[226:227], off
	v_lshl_add_u64 v[226:227], s[52:53], 0, v[142:143]
	s_add_i32 m0, s56, 0x2000
	s_nop 0
	global_load_lds_dwordx4 v[226:227], off
	v_lshl_add_u64 v[226:227], v[230:231], 0, s[36:37]
	s_mov_b32 m0, s94
	s_nop 0
	global_load_lds_dwordx4 v[226:227], off
	v_lshl_add_u64 v[226:227], v[232:233], 0, s[36:37]
	s_mov_b32 m0, s95
	s_nop 0
	global_load_lds_dwordx4 v[226:227], off
	s_waitcnt vmcnt(8)
	s_waitcnt lgkmcnt(0)
	s_setprio 1
	s_barrier
	v_mfma_f32_16x16x32_bf16 v[92:95], v[128:131], v[182:185], v[92:95]
	v_mfma_f32_16x16x32_bf16 v[88:91], v[158:161], v[182:185], v[88:91]
	v_mfma_f32_16x16x32_bf16 v[84:87], v[128:131], v[190:193], v[84:87]
	v_mfma_f32_16x16x32_bf16 v[80:83], v[158:161], v[190:193], v[80:83]
	v_mfma_f32_16x16x32_bf16 v[76:79], v[128:131], v[198:201], v[76:79]
	v_mfma_f32_16x16x32_bf16 v[72:75], v[158:161], v[198:201], v[72:75]
	v_mfma_f32_16x16x32_bf16 v[68:71], v[128:131], v[218:221], v[68:71]
	v_mfma_f32_16x16x32_bf16 v[64:67], v[158:161], v[218:221], v[64:67]
	v_mfma_f32_16x16x32_bf16 v[92:95], v[132:135], v[186:189], v[92:95]
	v_mfma_f32_16x16x32_bf16 v[88:91], v[162:165], v[186:189], v[88:91]
	v_mfma_f32_16x16x32_bf16 v[84:87], v[132:135], v[194:197], v[84:87]
	v_mfma_f32_16x16x32_bf16 v[80:83], v[162:165], v[194:197], v[80:83]
	v_mfma_f32_16x16x32_bf16 v[76:79], v[132:135], v[202:205], v[76:79]
	v_mfma_f32_16x16x32_bf16 v[72:75], v[162:165], v[202:205], v[72:75]
	v_mfma_f32_16x16x32_bf16 v[68:71], v[132:135], v[222:225], v[68:71]
	v_mfma_f32_16x16x32_bf16 v[64:67], v[162:165], v[222:225], v[64:67]
	v_mfma_f32_16x16x32_bf16 v[28:31], v[166:169], v[182:185], v[28:31]
	v_mfma_f32_16x16x32_bf16 v[24:27], v[174:177], v[182:185], v[24:27]
	v_mfma_f32_16x16x32_bf16 v[20:23], v[166:169], v[190:193], v[20:23]
	v_mfma_f32_16x16x32_bf16 v[16:19], v[174:177], v[190:193], v[16:19]
	v_mfma_f32_16x16x32_bf16 v[12:15], v[166:169], v[198:201], v[12:15]
	v_mfma_f32_16x16x32_bf16 v[8:11], v[174:177], v[198:201], v[8:11]
	v_mfma_f32_16x16x32_bf16 v[4:7], v[166:169], v[218:221], v[4:7]
	v_mfma_f32_16x16x32_bf16 v[0:3], v[174:177], v[218:221], v[0:3]
	v_mfma_f32_16x16x32_bf16 v[28:31], v[170:173], v[186:189], v[28:31]
	v_mfma_f32_16x16x32_bf16 v[24:27], v[178:181], v[186:189], v[24:27]
	v_mfma_f32_16x16x32_bf16 v[20:23], v[170:173], v[194:197], v[20:23]
	v_mfma_f32_16x16x32_bf16 v[16:19], v[178:181], v[194:197], v[16:19]
	v_mfma_f32_16x16x32_bf16 v[12:15], v[170:173], v[202:205], v[12:15]
	v_mfma_f32_16x16x32_bf16 v[8:11], v[178:181], v[202:205], v[8:11]
	s_setprio 2
	s_barrier
	v_mfma_f32_16x16x32_bf16 v[4:7], v[170:173], v[222:225], v[4:7]
	v_mfma_f32_16x16x32_bf16 v[0:3], v[178:181], v[222:225], v[0:3]
	s_setprio 0
	s_add_i32 vcc_hi, vcc_hi, 2
	s_add_u32 s74, s74, 0x100
	s_addc_u32 s75, s75, 0
	s_add_u32 s93, s93, 0x100
	s_addc_u32 vcc_lo, vcc_lo, 0
	s_cmpk_gt_u32 vcc_hi, 0x7d
	s_cbranch_scc0 .LBB0_624
	s_and_b64 vcc, exec, s[40:41]
	s_cbranch_vccz .LBB0_627
	s_barrier

; #define PG8_STAGE(bufoff, gbase, voff) do { _Pragma("unroll") for (int _i = 0; _i < 2; ++_i) \
;         __builtin_amdgcn_global_load_lds((const unsigned*)((const char*)(gbase) + (voff)[_i]), (PG8_LAS unsigned*)(lds + (bufoff) + ldsw + _i * 8192), 16, 0, 0); } while (0)
; #define PG8_LDA(dst, b, h) do { _Pragma("unroll") for (int m = 0; m < 4; ++m) _Pragma("unroll") for (int k = 0; k < 2; ++k) dst[m][k] = *(const PG8_LAS bf16x8*)(lds + PG8_SA(b, h) + aoff + m * 2048 + k * 1024); } while (0)
; #define PG8_LDB(dst, b, h) do { _Pragma("unroll") for (int n = 0; n < 2; ++n) _Pragma("unroll") for (int k = 0; k < 2; ++k) dst[n][k] = *(const PG8_LAS bf16x8*)(lds + PG8_SB(b, h) + boff + n * 2048 + k * 1024); } while (0)
; #define PG8_MMA(ai, bj, At, Bt) do { __builtin_amdgcn_s_setprio(1); _Pragma("unroll") for (int m = 0; m < 4; ++m) _Pragma("unroll") for (int n = 0; n < 2; ++n) _Pragma("unroll") for (int k = 0; k < 2; ++k) \
;         acc[ai][bj][m][n] = __builtin_amdgcn_mfma_f32_16x16x32_bf16(Bt[n][k], At[m][k], acc[ai][bj][m][n], 0, 0, 0); __builtin_amdgcn_s_setprio(0); } while (0)
; #define PG8_WAIT_V(n) asm volatile("s_waitcnt vmcnt(" #n ")" ::: "memory")
; #define PG8_WAIT_L(n) asm volatile("s_waitcnt lgkmcnt(" #n ")" ::: "memory")
; #define PG8_BAR __builtin_amdgcn_s_barrier()
; template <class Epi, class Sched, bool ALIGN_EPI = false, bool SP2 = false>
; __device__ __forceinline__ void gemm_phase(PG8_LAS unsigned char* lds, const Gemm g, const Sched& S, const Epi& E) {
;     ...
;         for (int t = 0; t < nt; t += 2) {
;             const bool last = (t == nt - 2);
;             const char* a1 = cA + (size_t)(t + 1) * kstep;
;             const char* a2 = last ? nA : cA + (size_t)(t + 2) * kstep; const char* b2 = last ? nB : cB + (size_t)(t + 2) * kstep;
;             const char* a3 = a2 + kstep; const char* b3 = b2 + kstep;
;             if constexpr (SP2) {
;             PG8_LDB(B0, 0, 0); PG8_LDB(B1, 0, 1); PG8_SCHED; PG8_LDA(At, 0, 0); PG8_STAGE(PG8_SA(1, 1), a1 + hstep, voffA);
;             PG8_WAIT_V(8); PG8_WAIT_L(0); PG8_BAR; PG8_MMA(0, 0, At, B0); PG8_MMA(0, 1, At, B1); PG8_BAR; PG8_SCHED;
;             PG8_LDA(At, 0, 1); PG8_STAGE(PG8_SB(0, 0), b2, voffB); PG8_STAGE(PG8_SB(0, 1), b2 + hstep, voffB); PG8_STAGE(PG8_SA(0, 0), a2, voffA);
;             PG8_WAIT_V(8); PG8_WAIT_L(0); PG8_BAR; PG8_MMA(1, 0, At, B0); PG8_MMA(1, 1, At, B1); PG8_BAR; PG8_SCHED;
.LBB0_660:
	ds_read_b128 v[166:169], v145
	ds_read_b128 v[170:173], v145 offset:1024
	ds_read_b128 v[174:177], v145 offset:2048
	ds_read_b128 v[178:181], v145 offset:3072
	ds_read_b128 v[182:185], v149
	ds_read_b128 v[186:189], v149 offset:1024
	ds_read_b128 v[190:193], v149 offset:2048
	ds_read_b128 v[194:197], v149 offset:3072
	s_add_u32 s52, s72, 0xffe00080
	s_addc_u32 s53, s73, -1
	s_cmp_eq_u32 s49, 28
	s_cselect_b32 s77, s51, s53
	s_cselect_b32 s76, s50, s52
	s_cselect_b32 s75, s55, s41
	s_cselect_b32 s74, s54, s37
	s_mov_b32 m0, s82
	v_lshl_add_u64 v[230:231], s[72:73], 0, v[160:161]
	ds_read_b128 v[198:201], v164
	ds_read_b128 v[202:205], v164 offset:1024
	ds_read_b128 v[206:209], v164 offset:2048
	ds_read_b128 v[210:213], v164 offset:3072
	ds_read_b128 v[214:217], v164 offset:4096
	ds_read_b128 v[218:221], v164 offset:5120
	ds_read_b128 v[222:225], v164 offset:6144
	ds_read_b128 v[226:229], v164 offset:7168
	global_load_lds_dwordx4 v[230:231], off
	v_lshl_add_u64 v[230:231], s[72:73], 0, v[162:163]
	s_mov_b32 m0, s83
	s_nop 0
	global_load_lds_dwordx4 v[230:231], off
	s_waitcnt vmcnt(8)
	s_waitcnt lgkmcnt(0)
	s_setprio 1
	s_barrier
	v_mfma_f32_16x16x32_bf16 v[124:127], v[166:169], v[198:201], v[124:127]
	v_mfma_f32_16x16x32_bf16 v[120:123], v[174:177], v[198:201], v[120:123]
	v_mfma_f32_16x16x32_bf16 v[116:119], v[166:169], v[206:209], v[116:119]
	v_mfma_f32_16x16x32_bf16 v[108:111], v[174:177], v[206:209], v[108:111]
	v_mfma_f32_16x16x32_bf16 v[100:103], v[166:169], v[214:217], v[100:103]
	v_mfma_f32_16x16x32_bf16 v[92:95], v[174:177], v[214:217], v[92:95]
	v_mfma_f32_16x16x32_bf16 v[84:87], v[166:169], v[222:225], v[84:87]
	v_mfma_f32_16x16x32_bf16 v[76:79], v[174:177], v[222:225], v[76:79]
	v_mfma_f32_16x16x32_bf16 v[124:127], v[170:173], v[202:205], v[124:127]
	v_mfma_f32_16x16x32_bf16 v[120:123], v[178:181], v[202:205], v[120:123]
	v_mfma_f32_16x16x32_bf16 v[116:119], v[170:173], v[210:213], v[116:119]
	v_mfma_f32_16x16x32_bf16 v[108:111], v[178:181], v[210:213], v[108:111]
	v_mfma_f32_16x16x32_bf16 v[100:103], v[170:173], v[218:221], v[100:103]
	v_mfma_f32_16x16x32_bf16 v[92:95], v[178:181], v[218:221], v[92:95]
	v_mfma_f32_16x16x32_bf16 v[84:87], v[170:173], v[226:229], v[84:87]
	v_mfma_f32_16x16x32_bf16 v[76:79], v[178:181], v[226:229], v[76:79]
	v_mfma_f32_16x16x32_bf16 v[112:115], v[182:185], v[198:201], v[112:115]
	v_mfma_f32_16x16x32_bf16 v[104:107], v[190:193], v[198:201], v[104:107]
	v_mfma_f32_16x16x32_bf16 v[96:99], v[182:185], v[206:209], v[96:99]
	v_mfma_f32_16x16x32_bf16 v[88:91], v[190:193], v[206:209], v[88:91]
	v_mfma_f32_16x16x32_bf16 v[80:83], v[182:185], v[214:217], v[80:83]
	v_mfma_f32_16x16x32_bf16 v[72:75], v[190:193], v[214:217], v[72:75]
	v_mfma_f32_16x16x32_bf16 v[68:71], v[182:185], v[222:225], v[68:71]
	v_mfma_f32_16x16x32_bf16 v[64:67], v[190:193], v[222:225], v[64:67]
	v_mfma_f32_16x16x32_bf16 v[112:115], v[186:189], v[202:205], v[112:115]
	v_mfma_f32_16x16x32_bf16 v[104:107], v[194:197], v[202:205], v[104:107]
	v_mfma_f32_16x16x32_bf16 v[96:99], v[186:189], v[210:213], v[96:99]
	v_mfma_f32_16x16x32_bf16 v[88:91], v[194:197], v[210:213], v[88:91]
	v_mfma_f32_16x16x32_bf16 v[80:83], v[186:189], v[218:221], v[80:83]
	v_mfma_f32_16x16x32_bf16 v[72:75], v[194:197], v[218:221], v[72:75]
	s_setprio 2
	s_barrier
	v_mfma_f32_16x16x32_bf16 v[68:71], v[186:189], v[226:229], v[68:71]
	v_mfma_f32_16x16x32_bf16 v[64:67], v[194:197], v[226:229], v[64:67]
	s_setprio 0
	s_mov_b32 m0, s84
	v_lshl_add_u64 v[230:231], s[74:75], 0, v[138:139]
	s_add_u32 s52, s74, 0x200000
	ds_read_b128 v[198:201], v164 offset:16384
	ds_read_b128 v[202:205], v164 offset:17408
	ds_read_b128 v[206:209], v164 offset:18432
	ds_read_b128 v[210:213], v164 offset:19456
	ds_read_b128 v[214:217], v164 offset:20480
	ds_read_b128 v[218:221], v164 offset:21504
	ds_read_b128 v[222:225], v164 offset:22528
	ds_read_b128 v[226:229], v164 offset:23552
	global_load_lds_dwordx4 v[230:231], off
	v_lshl_add_u64 v[232:233], s[74:75], 0, v[142:143]
	s_mov_b32 m0, s85
	s_addc_u32 s53, s75, 0
	global_load_lds_dwordx4 v[232:233], off
	v_lshl_add_u64 v[234:235], s[52:53], 0, v[138:139]
	s_mov_b32 m0, s86
	v_lshl_add_u64 v[236:237], s[76:77], 0, v[140:141]
	global_load_lds_dwordx4 v[234:235], off
	v_lshl_add_u64 v[234:235], s[52:53], 0, v[142:143]
	s_mov_b32 m0, s87
	s_nop 0
	global_load_lds_dwordx4 v[234:235], off
	v_lshl_add_u64 v[234:235], s[76:77], 0, v[136:137]
	s_mov_b32 m0, s28
	s_nop 0
	global_load_lds_dwordx4 v[234:235], off
	s_mov_b32 m0, s29
	s_nop 0
	global_load_lds_dwordx4 v[236:237], off
	s_waitcnt vmcnt(8)
	s_waitcnt lgkmcnt(0)
	s_setprio 1
	s_barrier
; #define PG8_STAGE(bufoff, gbase, voff) do { _Pragma("unroll") for (int _i = 0; _i < 2; ++_i) \
;         __builtin_amdgcn_global_load_lds((const unsigned*)((const char*)(gbase) + (voff)[_i]), (PG8_LAS unsigned*)(lds + (bufoff) + ldsw + _i * 8192), 16, 0, 0); } while (0)
; #define PG8_LDA(dst, b, h) do { _Pragma("unroll") for (int m = 0; m < 4; ++m) _Pragma("unroll") for (int k = 0; k < 2; ++k) dst[m][k] = *(const PG8_LAS bf16x8*)(lds + PG8_SA(b, h) + aoff + m * 2048 + k * 1024); } while (0)
; #define PG8_LDB(dst, b, h) do { _Pragma("unroll") for (int n = 0; n < 2; ++n) _Pragma("unroll") for (int k = 0; k < 2; ++k) dst[n][k] = *(const PG8_LAS bf16x8*)(lds + PG8_SB(b, h) + boff + n * 2048 + k * 1024); } while (0)
; #define PG8_MMA(ai, bj, At, Bt) do { __builtin_amdgcn_s_setprio(1); _Pragma("unroll") for (int m = 0; m < 4; ++m) _Pragma("unroll") for (int n = 0; n < 2; ++n) _Pragma("unroll") for (int k = 0; k < 2; ++k) \
;         acc[ai][bj][m][n] = __builtin_amdgcn_mfma_f32_16x16x32_bf16(Bt[n][k], At[m][k], acc[ai][bj][m][n], 0, 0, 0); __builtin_amdgcn_s_setprio(0); } while (0)
; #define PG8_WAIT_V(n) asm volatile("s_waitcnt vmcnt(" #n ")" ::: "memory")
; #define PG8_WAIT_L(n) asm volatile("s_waitcnt lgkmcnt(" #n ")" ::: "memory")
; #define PG8_BAR __builtin_amdgcn_s_barrier()
; #define PG8_SCHED __builtin_amdgcn_sched_barrier(0)
; template <class Epi, class Sched, bool ALIGN_EPI = false, bool SP2 = false>
; __device__ __forceinline__ void gemm_phase(PG8_LAS unsigned char* lds, const Gemm g, const Sched& S, const Epi& E) {
;     ...
;             PG8_WAIT_V(8); PG8_WAIT_L(0); PG8_BAR; PG8_MMA(1, 0, At, B0); PG8_MMA(1, 1, At, B1); PG8_BAR; PG8_SCHED;
;             PG8_LDB(B0, 1, 0); PG8_LDB(B1, 1, 1); PG8_SCHED; PG8_LDA(At, 1, 0); PG8_STAGE(PG8_SA(0, 1), a2 + hstep, voffA);
;             PG8_WAIT_V(8); PG8_WAIT_L(0); PG8_BAR; PG8_MMA(0, 0, At, B0); PG8_MMA(0, 1, At, B1); PG8_BAR; PG8_SCHED;
	v_mfma_f32_16x16x32_bf16 v[60:63], v[166:169], v[198:201], v[60:63]
	v_mfma_f32_16x16x32_bf16 v[56:59], v[174:177], v[198:201], v[56:59]
	v_mfma_f32_16x16x32_bf16 v[52:55], v[166:169], v[206:209], v[52:55]
	v_mfma_f32_16x16x32_bf16 v[44:47], v[174:177], v[206:209], v[44:47]
	v_mfma_f32_16x16x32_bf16 v[36:39], v[166:169], v[214:217], v[36:39]
	v_mfma_f32_16x16x32_bf16 v[28:31], v[174:177], v[214:217], v[28:31]
	v_mfma_f32_16x16x32_bf16 v[20:23], v[166:169], v[222:225], v[20:23]
	v_mfma_f32_16x16x32_bf16 v[12:15], v[174:177], v[222:225], v[12:15]
	v_mfma_f32_16x16x32_bf16 v[60:63], v[170:173], v[202:205], v[60:63]
	v_mfma_f32_16x16x32_bf16 v[56:59], v[178:181], v[202:205], v[56:59]
	v_mfma_f32_16x16x32_bf16 v[52:55], v[170:173], v[210:213], v[52:55]
	v_mfma_f32_16x16x32_bf16 v[44:47], v[178:181], v[210:213], v[44:47]
	v_mfma_f32_16x16x32_bf16 v[36:39], v[170:173], v[218:221], v[36:39]
	v_mfma_f32_16x16x32_bf16 v[28:31], v[178:181], v[218:221], v[28:31]
	v_mfma_f32_16x16x32_bf16 v[20:23], v[170:173], v[226:229], v[20:23]
	v_mfma_f32_16x16x32_bf16 v[12:15], v[178:181], v[226:229], v[12:15]
	v_mfma_f32_16x16x32_bf16 v[48:51], v[182:185], v[198:201], v[48:51]
	v_mfma_f32_16x16x32_bf16 v[40:43], v[190:193], v[198:201], v[40:43]
	v_mfma_f32_16x16x32_bf16 v[32:35], v[182:185], v[206:209], v[32:35]
	v_mfma_f32_16x16x32_bf16 v[24:27], v[190:193], v[206:209], v[24:27]
	v_mfma_f32_16x16x32_bf16 v[16:19], v[182:185], v[214:217], v[16:19]
	v_mfma_f32_16x16x32_bf16 v[8:11], v[190:193], v[214:217], v[8:11]
	v_mfma_f32_16x16x32_bf16 v[4:7], v[182:185], v[222:225], v[4:7]
	v_mfma_f32_16x16x32_bf16 v[0:3], v[190:193], v[222:225], v[0:3]
	v_mfma_f32_16x16x32_bf16 v[48:51], v[186:189], v[202:205], v[48:51]
	v_mfma_f32_16x16x32_bf16 v[40:43], v[194:197], v[202:205], v[40:43]
	v_mfma_f32_16x16x32_bf16 v[32:35], v[186:189], v[210:213], v[32:35]
	v_mfma_f32_16x16x32_bf16 v[24:27], v[194:197], v[210:213], v[24:27]
	v_mfma_f32_16x16x32_bf16 v[16:19], v[186:189], v[218:221], v[16:19]
	v_mfma_f32_16x16x32_bf16 v[8:11], v[194:197], v[218:221], v[8:11]
	s_setprio 2
	s_barrier
	v_mfma_f32_16x16x32_bf16 v[4:7], v[186:189], v[226:229], v[4:7]
	v_mfma_f32_16x16x32_bf16 v[0:3], v[194:197], v[226:229], v[0:3]
	s_setprio 0
	ds_read_b128 v[166:169], v148
	ds_read_b128 v[170:173], v148 offset:1024
	ds_read_b128 v[174:177], v148 offset:2048
	ds_read_b128 v[178:181], v148 offset:3072
	ds_read_b128 v[182:185], v165
	ds_read_b128 v[186:189], v165 offset:1024
	ds_read_b128 v[190:193], v165 offset:2048
	ds_read_b128 v[194:197], v165 offset:3072
	s_add_u32 s52, s76, 0x200000
	s_addc_u32 s53, s77, 0
	s_mov_b32 m0, s33
	v_lshl_add_u64 v[238:239], s[52:53], 0, v[136:137]
	ds_read_b128 v[198:201], v164 offset:32768
	ds_read_b128 v[202:205], v164 offset:33792
	ds_read_b128 v[206:209], v164 offset:34816
	ds_read_b128 v[210:213], v164 offset:35840
	ds_read_b128 v[214:217], v164 offset:36864
	ds_read_b128 v[218:221], v164 offset:37888
	ds_read_b128 v[222:225], v164 offset:38912
	ds_read_b128 v[226:229], v164 offset:39936
	global_load_lds_dwordx4 v[238:239], off
	v_lshl_add_u64 v[238:239], s[52:53], 0, v[140:141]
	s_mov_b32 m0, s38
	s_nop 0
	global_load_lds_dwordx4 v[238:239], off
	s_waitcnt vmcnt(8)
	s_waitcnt lgkmcnt(0)
	s_setprio 1
	s_barrier
	v_mfma_f32_16x16x32_bf16 v[124:127], v[166:169], v[198:201], v[124:127]
	v_mfma_f32_16x16x32_bf16 v[120:123], v[174:177], v[198:201], v[120:123]
	v_mfma_f32_16x16x32_bf16 v[116:119], v[166:169], v[206:209], v[116:119]
	v_mfma_f32_16x16x32_bf16 v[108:111], v[174:177], v[206:209], v[108:111]
	v_mfma_f32_16x16x32_bf16 v[100:103], v[166:169], v[214:217], v[100:103]
	v_mfma_f32_16x16x32_bf16 v[92:95], v[174:177], v[214:217], v[92:95]
	v_mfma_f32_16x16x32_bf16 v[84:87], v[166:169], v[222:225], v[84:87]
	v_mfma_f32_16x16x32_bf16 v[76:79], v[174:177], v[222:225], v[76:79]
	v_mfma_f32_16x16x32_bf16 v[124:127], v[170:173], v[202:205], v[124:127]
	v_mfma_f32_16x16x32_bf16 v[120:123], v[178:181], v[202:205], v[120:123]
	v_mfma_f32_16x16x32_bf16 v[116:119], v[170:173], v[210:213], v[116:119]
	v_mfma_f32_16x16x32_bf16 v[108:111], v[178:181], v[210:213], v[108:111]
	v_mfma_f32_16x16x32_bf16 v[100:103], v[170:173], v[218:221], v[100:103]
	v_mfma_f32_16x16x32_bf16 v[92:95], v[178:181], v[218:221], v[92:95]
	v_mfma_f32_16x16x32_bf16 v[84:87], v[170:173], v[226:229], v[84:87]
	v_mfma_f32_16x16x32_bf16 v[76:79], v[178:181], v[226:229], v[76:79]
	v_mfma_f32_16x16x32_bf16 v[112:115], v[182:185], v[198:201], v[112:115]
	v_mfma_f32_16x16x32_bf16 v[104:107], v[190:193], v[198:201], v[104:107]
	v_mfma_f32_16x16x32_bf16 v[96:99], v[182:185], v[206:209], v[96:99]
	v_mfma_f32_16x16x32_bf16 v[88:91], v[190:193], v[206:209], v[88:91]
	v_mfma_f32_16x16x32_bf16 v[80:83], v[182:185], v[214:217], v[80:83]
	v_mfma_f32_16x16x32_bf16 v[72:75], v[190:193], v[214:217], v[72:75]
	v_mfma_f32_16x16x32_bf16 v[68:71], v[182:185], v[222:225], v[68:71]
	v_mfma_f32_16x16x32_bf16 v[64:67], v[190:193], v[222:225], v[64:67]
	v_mfma_f32_16x16x32_bf16 v[112:115], v[186:189], v[202:205], v[112:115]
	v_mfma_f32_16x16x32_bf16 v[104:107], v[194:197], v[202:205], v[104:107]
	v_mfma_f32_16x16x32_bf16 v[96:99], v[186:189], v[210:213], v[96:99]
	v_mfma_f32_16x16x32_bf16 v[88:91], v[194:197], v[210:213], v[88:91]
	v_mfma_f32_16x16x32_bf16 v[80:83], v[186:189], v[218:221], v[80:83]
	v_mfma_f32_16x16x32_bf16 v[72:75], v[194:197], v[218:221], v[72:75]
	s_setprio 2
	s_barrier
; #define PG8_STAGE(bufoff, gbase, voff) do { _Pragma("unroll") for (int _i = 0; _i < 2; ++_i) \
;         __builtin_amdgcn_global_load_lds((const unsigned*)((const char*)(gbase) + (voff)[_i]), (PG8_LAS unsigned*)(lds + (bufoff) + ldsw + _i * 8192), 16, 0, 0); } while (0)
; #define PG8_LDA(dst, b, h) do { _Pragma("unroll") for (int m = 0; m < 4; ++m) _Pragma("unroll") for (int k = 0; k < 2; ++k) dst[m][k] = *(const PG8_LAS bf16x8*)(lds + PG8_SA(b, h) + aoff + m * 2048 + k * 1024); } while (0)
; #define PG8_MMA(ai, bj, At, Bt) do { __builtin_amdgcn_s_setprio(1); _Pragma("unroll") for (int m = 0; m < 4; ++m) _Pragma("unroll") for (int n = 0; n < 2; ++n) _Pragma("unroll") for (int k = 0; k < 2; ++k) \
;         acc[ai][bj][m][n] = __builtin_amdgcn_mfma_f32_16x16x32_bf16(Bt[n][k], At[m][k], acc[ai][bj][m][n], 0, 0, 0); __builtin_amdgcn_s_setprio(0); } while (0)
; #define PG8_WAIT_V(n) asm volatile("s_waitcnt vmcnt(" #n ")" ::: "memory")
; #define PG8_WAIT_L(n) asm volatile("s_waitcnt lgkmcnt(" #n ")" ::: "memory")
; #define PG8_BAR __builtin_amdgcn_s_barrier()
; #define PG8_SCHED __builtin_amdgcn_sched_barrier(0)
; template <class Epi, class Sched, bool ALIGN_EPI = false, bool SP2 = false>
; __device__ __forceinline__ void gemm_phase(PG8_LAS unsigned char* lds, const Gemm g, const Sched& S, const Epi& E) {
;     ...
;             PG8_WAIT_V(8); PG8_WAIT_L(0); PG8_BAR; PG8_MMA(0, 0, At, B0); PG8_MMA(0, 1, At, B1); PG8_BAR; PG8_SCHED;
;             PG8_LDA(At, 1, 1); PG8_STAGE(PG8_SB(1, 0), b3, voffB); PG8_STAGE(PG8_SB(1, 1), b3 + hstep, voffB); PG8_STAGE(PG8_SA(1, 0), a3, voffA);
;             PG8_WAIT_V(8); PG8_WAIT_L(0); PG8_BAR; PG8_MMA(1, 0, At, B0); PG8_MMA(1, 1, At, B1); PG8_BAR; PG8_SCHED;
;     ...
;         if constexpr (ALIGN_EPI) { if (wr == 0) PG8_BAR; }
	v_mfma_f32_16x16x32_bf16 v[68:71], v[186:189], v[226:229], v[68:71]
	v_mfma_f32_16x16x32_bf16 v[64:67], v[194:197], v[226:229], v[64:67]
	s_setprio 0
	s_mov_b32 m0, s89
	v_lshl_add_u64 v[230:231], v[230:231], 0, s[12:13]
	ds_read_b128 v[198:201], v164 offset:49152
	ds_read_b128 v[202:205], v164 offset:50176
	ds_read_b128 v[206:209], v164 offset:51200
	ds_read_b128 v[210:213], v164 offset:52224
	ds_read_b128 v[214:217], v164 offset:53248
	ds_read_b128 v[218:221], v164 offset:54272
	ds_read_b128 v[222:225], v164 offset:55296
	ds_read_b128 v[226:229], v164 offset:56320
	global_load_lds_dwordx4 v[230:231], off
	s_add_i32 m0, s89, 0x2000
	s_add_u32 s52, s74, 0x200080
	v_lshl_add_u64 v[230:231], v[232:233], 0, s[12:13]
	s_addc_u32 s53, s75, 0
	s_add_i32 s56, s88, s3
	global_load_lds_dwordx4 v[230:231], off
	v_lshl_add_u64 v[230:231], s[52:53], 0, v[138:139]
	s_mov_b32 m0, s56
	s_nop 0
	global_load_lds_dwordx4 v[230:231], off
	v_lshl_add_u64 v[230:231], s[52:53], 0, v[142:143]
	s_add_i32 m0, s56, 0x2000
	s_nop 0
	global_load_lds_dwordx4 v[230:231], off
	v_lshl_add_u64 v[230:231], v[234:235], 0, s[12:13]
	s_mov_b32 m0, s71
	s_nop 0
	global_load_lds_dwordx4 v[230:231], off
	v_lshl_add_u64 v[230:231], v[236:237], 0, s[12:13]
	s_mov_b32 m0, s78
	s_nop 0
	global_load_lds_dwordx4 v[230:231], off
	s_waitcnt vmcnt(8)
	s_waitcnt lgkmcnt(0)
	s_setprio 1
	s_barrier
	v_mfma_f32_16x16x32_bf16 v[60:63], v[166:169], v[198:201], v[60:63]
	v_mfma_f32_16x16x32_bf16 v[56:59], v[174:177], v[198:201], v[56:59]
	v_mfma_f32_16x16x32_bf16 v[52:55], v[166:169], v[206:209], v[52:55]
	v_mfma_f32_16x16x32_bf16 v[44:47], v[174:177], v[206:209], v[44:47]
	v_mfma_f32_16x16x32_bf16 v[36:39], v[166:169], v[214:217], v[36:39]
	v_mfma_f32_16x16x32_bf16 v[28:31], v[174:177], v[214:217], v[28:31]
	v_mfma_f32_16x16x32_bf16 v[20:23], v[166:169], v[222:225], v[20:23]
	v_mfma_f32_16x16x32_bf16 v[12:15], v[174:177], v[222:225], v[12:15]
	v_mfma_f32_16x16x32_bf16 v[60:63], v[170:173], v[202:205], v[60:63]
	v_mfma_f32_16x16x32_bf16 v[56:59], v[178:181], v[202:205], v[56:59]
	v_mfma_f32_16x16x32_bf16 v[52:55], v[170:173], v[210:213], v[52:55]
	v_mfma_f32_16x16x32_bf16 v[44:47], v[178:181], v[210:213], v[44:47]
	v_mfma_f32_16x16x32_bf16 v[36:39], v[170:173], v[218:221], v[36:39]
	v_mfma_f32_16x16x32_bf16 v[28:31], v[178:181], v[218:221], v[28:31]
	v_mfma_f32_16x16x32_bf16 v[20:23], v[170:173], v[226:229], v[20:23]
	v_mfma_f32_16x16x32_bf16 v[12:15], v[178:181], v[226:229], v[12:15]
	v_mfma_f32_16x16x32_bf16 v[48:51], v[182:185], v[198:201], v[48:51]
	v_mfma_f32_16x16x32_bf16 v[40:43], v[190:193], v[198:201], v[40:43]
	v_mfma_f32_16x16x32_bf16 v[32:35], v[182:185], v[206:209], v[32:35]
	v_mfma_f32_16x16x32_bf16 v[24:27], v[190:193], v[206:209], v[24:27]
	v_mfma_f32_16x16x32_bf16 v[16:19], v[182:185], v[214:217], v[16:19]
	v_mfma_f32_16x16x32_bf16 v[8:11], v[190:193], v[214:217], v[8:11]
	v_mfma_f32_16x16x32_bf16 v[4:7], v[182:185], v[222:225], v[4:7]
	v_mfma_f32_16x16x32_bf16 v[0:3], v[190:193], v[222:225], v[0:3]
	v_mfma_f32_16x16x32_bf16 v[48:51], v[186:189], v[202:205], v[48:51]
	v_mfma_f32_16x16x32_bf16 v[40:43], v[194:197], v[202:205], v[40:43]
	v_mfma_f32_16x16x32_bf16 v[32:35], v[186:189], v[210:213], v[32:35]
	v_mfma_f32_16x16x32_bf16 v[24:27], v[194:197], v[210:213], v[24:27]
	v_mfma_f32_16x16x32_bf16 v[16:19], v[186:189], v[218:221], v[16:19]
	v_mfma_f32_16x16x32_bf16 v[8:11], v[194:197], v[218:221], v[8:11]
	s_setprio 2
	s_barrier
	v_mfma_f32_16x16x32_bf16 v[4:7], v[186:189], v[226:229], v[4:7]
	v_mfma_f32_16x16x32_bf16 v[0:3], v[194:197], v[226:229], v[0:3]
	s_setprio 0
	s_add_i32 s49, s49, 2
	s_add_u32 s72, s72, 0x100
	s_addc_u32 s73, s73, 0
	s_add_u32 s37, s37, 0x100
	s_addc_u32 s41, s41, 0
	s_cmp_gt_u32 s49, 29
	s_cbranch_scc0 .LBB0_660
	s_and_b64 vcc, exec, s[14:15]
	s_cbranch_vccz .LBB0_663
	s_barrier

; #define PG8_STAGE(bufoff, gbase, voff) do { _Pragma("unroll") for (int _i = 0; _i < 2; ++_i) \
;         __builtin_amdgcn_global_load_lds((const unsigned*)((const char*)(gbase) + (voff)[_i]), (PG8_LAS unsigned*)(lds + (bufoff) + ldsw + _i * 8192), 16, 0, 0); } while (0)
; #define PG8_LDA(dst, b, h) do { _Pragma("unroll") for (int m = 0; m < 4; ++m) _Pragma("unroll") for (int k = 0; k < 2; ++k) dst[m][k] = *(const PG8_LAS bf16x8*)(lds + PG8_SA(b, h) + aoff + m * 2048 + k * 1024); } while (0)
; #define PG8_LDB(dst, b, h) do { _Pragma("unroll") for (int n = 0; n < 2; ++n) _Pragma("unroll") for (int k = 0; k < 2; ++k) dst[n][k] = *(const PG8_LAS bf16x8*)(lds + PG8_SB(b, h) + boff + n * 2048 + k * 1024); } while (0)
; #define PG8_MMA(ai, bj, At, Bt) do { __builtin_amdgcn_s_setprio(1); _Pragma("unroll") for (int m = 0; m < 4; ++m) _Pragma("unroll") for (int n = 0; n < 2; ++n) _Pragma("unroll") for (int k = 0; k < 2; ++k) \
;         acc[ai][bj][m][n] = __builtin_amdgcn_mfma_f32_16x16x32_bf16(Bt[n][k], At[m][k], acc[ai][bj][m][n], 0, 0, 0); __builtin_amdgcn_s_setprio(0); } while (0)
; #define PG8_WAIT_V(n) asm volatile("s_waitcnt vmcnt(" #n ")" ::: "memory")
; #define PG8_WAIT_L(n) asm volatile("s_waitcnt lgkmcnt(" #n ")" ::: "memory")
; #define PG8_BAR __builtin_amdgcn_s_barrier()
; template <class Epi, class Sched, bool ALIGN_EPI = false, bool SP2 = false>
; __device__ __forceinline__ void gemm_phase(PG8_LAS unsigned char* lds, const Gemm g, const Sched& S, const Epi& E) {
;     ...
;         for (int t = 0; t < nt; t += 2) {
;             const bool last = (t == nt - 2);
;             const char* a1 = cA + (size_t)(t + 1) * kstep;
;             const char* a2 = last ? nA : cA + (size_t)(t + 2) * kstep; const char* b2 = last ? nB : cB + (size_t)(t + 2) * kstep;
;             const char* a3 = a2 + kstep; const char* b3 = b2 + kstep;
;             if constexpr (SP2) {
;             PG8_LDB(B0, 0, 0); PG8_LDB(B1, 0, 1); PG8_SCHED; PG8_LDA(At, 0, 0); PG8_STAGE(PG8_SA(1, 1), a1 + hstep, voffA);
;             PG8_WAIT_V(8); PG8_WAIT_L(0); PG8_BAR; PG8_MMA(0, 0, At, B0); PG8_MMA(0, 1, At, B1); PG8_BAR; PG8_SCHED;
;             PG8_LDA(At, 0, 1); PG8_STAGE(PG8_SB(0, 0), b2, voffB); PG8_STAGE(PG8_SB(0, 1), b2 + hstep, voffB); PG8_STAGE(PG8_SA(0, 0), a2, voffA);
;             PG8_WAIT_V(8); PG8_WAIT_L(0); PG8_BAR; PG8_MMA(1, 0, At, B0); PG8_MMA(1, 1, At, B1); PG8_BAR; PG8_SCHED;
.LBB0_809:
	ds_read_b128 v[128:131], v180
	ds_read_b128 v[132:135], v180 offset:1024
	ds_read_b128 v[136:139], v180 offset:2048
	ds_read_b128 v[140:143], v180 offset:3072
	ds_read_b128 v[160:163], v181
	ds_read_b128 v[164:167], v181 offset:1024
	ds_read_b128 v[184:187], v181 offset:2048
	ds_read_b128 v[188:191], v181 offset:3072
	s_add_u32 s52, s72, 0xfff80080
	s_addc_u32 s53, s73, -1
	s_cmp_eq_u32 s92, 28
	s_cselect_b32 s77, s5, s53
	s_cselect_b32 s76, s49, s52
	s_cselect_b32 s75, s45, s91
	s_cselect_b32 s74, s89, s90
	v_lshl_add_u64 v[168:169], s[72:73], 0, v[154:155]
	s_add_i32 m0, s71, 0xc000
	ds_read_b128 v[192:195], v182
	ds_read_b128 v[196:199], v182 offset:1024
	ds_read_b128 v[200:203], v182 offset:2048
	ds_read_b128 v[204:207], v182 offset:3072
	ds_read_b128 v[208:211], v182 offset:4096
	ds_read_b128 v[212:215], v182 offset:5120
	ds_read_b128 v[216:219], v182 offset:6144
	ds_read_b128 v[220:223], v182 offset:7168
	global_load_lds_dwordx4 v[168:169], off
	v_lshl_add_u64 v[168:169], s[72:73], 0, v[156:157]
	s_add_i32 m0, s71, 0xe000
	s_nop 0
	global_load_lds_dwordx4 v[168:169], off
	s_waitcnt vmcnt(8)
	s_waitcnt lgkmcnt(0)
	s_setprio 1
	s_barrier
	v_mfma_f32_16x16x32_bf16 v[124:127], v[128:131], v[192:195], v[124:127]
	v_mfma_f32_16x16x32_bf16 v[120:123], v[136:139], v[192:195], v[120:123]
	v_mfma_f32_16x16x32_bf16 v[108:111], v[128:131], v[200:203], v[108:111]
	v_mfma_f32_16x16x32_bf16 v[104:107], v[136:139], v[200:203], v[104:107]
	v_mfma_f32_16x16x32_bf16 v[92:95], v[128:131], v[208:211], v[92:95]
	v_mfma_f32_16x16x32_bf16 v[88:91], v[136:139], v[208:211], v[88:91]
	v_mfma_f32_16x16x32_bf16 v[76:79], v[128:131], v[216:219], v[76:79]
	v_mfma_f32_16x16x32_bf16 v[72:75], v[136:139], v[216:219], v[72:75]
	v_mfma_f32_16x16x32_bf16 v[124:127], v[132:135], v[196:199], v[124:127]
	v_mfma_f32_16x16x32_bf16 v[120:123], v[140:143], v[196:199], v[120:123]
	v_mfma_f32_16x16x32_bf16 v[108:111], v[132:135], v[204:207], v[108:111]
	v_mfma_f32_16x16x32_bf16 v[104:107], v[140:143], v[204:207], v[104:107]
	v_mfma_f32_16x16x32_bf16 v[92:95], v[132:135], v[212:215], v[92:95]
	v_mfma_f32_16x16x32_bf16 v[88:91], v[140:143], v[212:215], v[88:91]
	v_mfma_f32_16x16x32_bf16 v[76:79], v[132:135], v[220:223], v[76:79]
	v_mfma_f32_16x16x32_bf16 v[72:75], v[140:143], v[220:223], v[72:75]
	v_mfma_f32_16x16x32_bf16 v[116:119], v[160:163], v[192:195], v[116:119]
	v_mfma_f32_16x16x32_bf16 v[112:115], v[184:187], v[192:195], v[112:115]
	v_mfma_f32_16x16x32_bf16 v[100:103], v[160:163], v[200:203], v[100:103]
	v_mfma_f32_16x16x32_bf16 v[96:99], v[184:187], v[200:203], v[96:99]
	v_mfma_f32_16x16x32_bf16 v[84:87], v[160:163], v[208:211], v[84:87]
	v_mfma_f32_16x16x32_bf16 v[80:83], v[184:187], v[208:211], v[80:83]
	v_mfma_f32_16x16x32_bf16 v[68:71], v[160:163], v[216:219], v[68:71]
	v_mfma_f32_16x16x32_bf16 v[64:67], v[184:187], v[216:219], v[64:67]
	v_mfma_f32_16x16x32_bf16 v[116:119], v[164:167], v[196:199], v[116:119]
	v_mfma_f32_16x16x32_bf16 v[112:115], v[188:191], v[196:199], v[112:115]
	v_mfma_f32_16x16x32_bf16 v[100:103], v[164:167], v[204:207], v[100:103]
	v_mfma_f32_16x16x32_bf16 v[96:99], v[188:191], v[204:207], v[96:99]
	v_mfma_f32_16x16x32_bf16 v[84:87], v[164:167], v[212:215], v[84:87]
	v_mfma_f32_16x16x32_bf16 v[80:83], v[188:191], v[212:215], v[80:83]
	s_setprio 2
	s_barrier
	v_mfma_f32_16x16x32_bf16 v[68:71], v[164:167], v[220:223], v[68:71]
	v_mfma_f32_16x16x32_bf16 v[64:67], v[188:191], v[220:223], v[64:67]
	s_setprio 0
	s_add_i32 s52, s83, s78
	v_lshl_add_u64 v[168:169], s[74:75], 0, v[148:149]
	s_mov_b32 m0, s52
	ds_read_b128 v[192:195], v182 offset:16384
	ds_read_b128 v[196:199], v182 offset:17408
	ds_read_b128 v[200:203], v182 offset:18432
	ds_read_b128 v[204:207], v182 offset:19456
	ds_read_b128 v[208:211], v182 offset:20480
	ds_read_b128 v[212:215], v182 offset:21504
	ds_read_b128 v[216:219], v182 offset:22528
	ds_read_b128 v[220:223], v182 offset:23552
	global_load_lds_dwordx4 v[168:169], off
	s_add_i32 m0, s52, 0x2000
	s_add_u32 s52, s74, 0x80000
	v_lshl_add_u64 v[224:225], s[74:75], 0, v[152:153]
	s_addc_u32 s53, s75, 0
	s_add_i32 s56, s84, s78
	global_load_lds_dwordx4 v[224:225], off
	v_lshl_add_u64 v[226:227], s[52:53], 0, v[148:149]
	s_mov_b32 m0, s56
	v_lshl_add_u64 v[228:229], s[76:77], 0, v[150:151]
	global_load_lds_dwordx4 v[226:227], off
	v_lshl_add_u64 v[226:227], s[52:53], 0, v[152:153]
	s_add_i32 m0, s56, 0x2000
	s_nop 0
	global_load_lds_dwordx4 v[226:227], off
	v_lshl_add_u64 v[226:227], s[76:77], 0, v[144:145]
	s_mov_b32 m0, s71
	s_nop 0
	global_load_lds_dwordx4 v[226:227], off
	s_mov_b32 m0, s79
	s_nop 0
	global_load_lds_dwordx4 v[228:229], off
	s_waitcnt vmcnt(8)
	s_waitcnt lgkmcnt(0)
	s_setprio 1
	s_barrier
; #define PG8_STAGE(bufoff, gbase, voff) do { _Pragma("unroll") for (int _i = 0; _i < 2; ++_i) \
;         __builtin_amdgcn_global_load_lds((const unsigned*)((const char*)(gbase) + (voff)[_i]), (PG8_LAS unsigned*)(lds + (bufoff) + ldsw + _i * 8192), 16, 0, 0); } while (0)
; #define PG8_LDA(dst, b, h) do { _Pragma("unroll") for (int m = 0; m < 4; ++m) _Pragma("unroll") for (int k = 0; k < 2; ++k) dst[m][k] = *(const PG8_LAS bf16x8*)(lds + PG8_SA(b, h) + aoff + m * 2048 + k * 1024); } while (0)
; #define PG8_LDB(dst, b, h) do { _Pragma("unroll") for (int n = 0; n < 2; ++n) _Pragma("unroll") for (int k = 0; k < 2; ++k) dst[n][k] = *(const PG8_LAS bf16x8*)(lds + PG8_SB(b, h) + boff + n * 2048 + k * 1024); } while (0)
; #define PG8_MMA(ai, bj, At, Bt) do { __builtin_amdgcn_s_setprio(1); _Pragma("unroll") for (int m = 0; m < 4; ++m) _Pragma("unroll") for (int n = 0; n < 2; ++n) _Pragma("unroll") for (int k = 0; k < 2; ++k) \
;         acc[ai][bj][m][n] = __builtin_amdgcn_mfma_f32_16x16x32_bf16(Bt[n][k], At[m][k], acc[ai][bj][m][n], 0, 0, 0); __builtin_amdgcn_s_setprio(0); } while (0)
; #define PG8_WAIT_V(n) asm volatile("s_waitcnt vmcnt(" #n ")" ::: "memory")
; #define PG8_WAIT_L(n) asm volatile("s_waitcnt lgkmcnt(" #n ")" ::: "memory")
; #define PG8_BAR __builtin_amdgcn_s_barrier()
; #define PG8_SCHED __builtin_amdgcn_sched_barrier(0)
; template <class Epi, class Sched, bool ALIGN_EPI = false, bool SP2 = false>
; __device__ __forceinline__ void gemm_phase(PG8_LAS unsigned char* lds, const Gemm g, const Sched& S, const Epi& E) {
;     ...
;             PG8_WAIT_V(8); PG8_WAIT_L(0); PG8_BAR; PG8_MMA(1, 0, At, B0); PG8_MMA(1, 1, At, B1); PG8_BAR; PG8_SCHED;
;             PG8_LDB(B0, 1, 0); PG8_LDB(B1, 1, 1); PG8_SCHED; PG8_LDA(At, 1, 0); PG8_STAGE(PG8_SA(0, 1), a2 + hstep, voffA);
;             PG8_WAIT_V(8); PG8_WAIT_L(0); PG8_BAR; PG8_MMA(0, 0, At, B0); PG8_MMA(0, 1, At, B1); PG8_BAR; PG8_SCHED;
	v_mfma_f32_16x16x32_bf16 v[60:63], v[128:131], v[192:195], v[60:63]
	v_mfma_f32_16x16x32_bf16 v[56:59], v[136:139], v[192:195], v[56:59]
	v_mfma_f32_16x16x32_bf16 v[44:47], v[128:131], v[200:203], v[44:47]
	v_mfma_f32_16x16x32_bf16 v[40:43], v[136:139], v[200:203], v[40:43]
	v_mfma_f32_16x16x32_bf16 v[28:31], v[128:131], v[208:211], v[28:31]
	v_mfma_f32_16x16x32_bf16 v[24:27], v[136:139], v[208:211], v[24:27]
	v_mfma_f32_16x16x32_bf16 v[12:15], v[128:131], v[216:219], v[12:15]
	v_mfma_f32_16x16x32_bf16 v[8:11], v[136:139], v[216:219], v[8:11]
	v_mfma_f32_16x16x32_bf16 v[60:63], v[132:135], v[196:199], v[60:63]
	v_mfma_f32_16x16x32_bf16 v[56:59], v[140:143], v[196:199], v[56:59]
	v_mfma_f32_16x16x32_bf16 v[44:47], v[132:135], v[204:207], v[44:47]
	v_mfma_f32_16x16x32_bf16 v[40:43], v[140:143], v[204:207], v[40:43]
	v_mfma_f32_16x16x32_bf16 v[28:31], v[132:135], v[212:215], v[28:31]
	v_mfma_f32_16x16x32_bf16 v[24:27], v[140:143], v[212:215], v[24:27]
	v_mfma_f32_16x16x32_bf16 v[12:15], v[132:135], v[220:223], v[12:15]
	v_mfma_f32_16x16x32_bf16 v[8:11], v[140:143], v[220:223], v[8:11]
	v_mfma_f32_16x16x32_bf16 v[52:55], v[160:163], v[192:195], v[52:55]
	v_mfma_f32_16x16x32_bf16 v[48:51], v[184:187], v[192:195], v[48:51]
	v_mfma_f32_16x16x32_bf16 v[36:39], v[160:163], v[200:203], v[36:39]
	v_mfma_f32_16x16x32_bf16 v[32:35], v[184:187], v[200:203], v[32:35]
	v_mfma_f32_16x16x32_bf16 v[20:23], v[160:163], v[208:211], v[20:23]
	v_mfma_f32_16x16x32_bf16 v[16:19], v[184:187], v[208:211], v[16:19]
	v_mfma_f32_16x16x32_bf16 v[4:7], v[160:163], v[216:219], v[4:7]
	v_mfma_f32_16x16x32_bf16 v[0:3], v[184:187], v[216:219], v[0:3]
	v_mfma_f32_16x16x32_bf16 v[52:55], v[164:167], v[196:199], v[52:55]
	v_mfma_f32_16x16x32_bf16 v[48:51], v[188:191], v[196:199], v[48:51]
	v_mfma_f32_16x16x32_bf16 v[36:39], v[164:167], v[204:207], v[36:39]
	v_mfma_f32_16x16x32_bf16 v[32:35], v[188:191], v[204:207], v[32:35]
	v_mfma_f32_16x16x32_bf16 v[20:23], v[164:167], v[212:215], v[20:23]
	v_mfma_f32_16x16x32_bf16 v[16:19], v[188:191], v[212:215], v[16:19]
	s_setprio 2
	s_barrier
	v_mfma_f32_16x16x32_bf16 v[4:7], v[164:167], v[220:223], v[4:7]
	v_mfma_f32_16x16x32_bf16 v[0:3], v[188:191], v[220:223], v[0:3]
	s_setprio 0
	s_add_i32 s56, 0, 0x18000
	s_add_i32 s57, 0, 0x1c000
	v_add_u32_e32 v140, s56, v171
	v_add_u32_e32 v188, s57, v171
	ds_read_b128 v[128:131], v140
	ds_read_b128 v[132:135], v140 offset:1024
	ds_read_b128 v[136:139], v140 offset:2048
	ds_read_b128 v[140:143], v140 offset:3072
	ds_read_b128 v[160:163], v188
	ds_read_b128 v[164:167], v188 offset:1024
	ds_read_b128 v[184:187], v188 offset:2048
	ds_read_b128 v[188:191], v188 offset:3072
	s_add_u32 s52, s76, 0x80000
	s_addc_u32 s53, s77, 0
	s_mov_b32 m0, s80
	v_lshl_add_u64 v[230:231], s[52:53], 0, v[144:145]
	ds_read_b128 v[192:195], v182 offset:32768
	ds_read_b128 v[196:199], v182 offset:33792
	ds_read_b128 v[200:203], v182 offset:34816
	ds_read_b128 v[204:207], v182 offset:35840
	ds_read_b128 v[208:211], v182 offset:36864
	ds_read_b128 v[212:215], v182 offset:37888
	ds_read_b128 v[216:219], v182 offset:38912
	ds_read_b128 v[220:223], v182 offset:39936
	global_load_lds_dwordx4 v[230:231], off
	v_lshl_add_u64 v[230:231], s[52:53], 0, v[150:151]
	s_mov_b32 m0, s81
	s_nop 0
	global_load_lds_dwordx4 v[230:231], off
	s_waitcnt vmcnt(8)
	s_waitcnt lgkmcnt(0)
	s_setprio 1
	s_barrier
	v_mfma_f32_16x16x32_bf16 v[124:127], v[128:131], v[192:195], v[124:127]
	v_mfma_f32_16x16x32_bf16 v[120:123], v[136:139], v[192:195], v[120:123]
	v_mfma_f32_16x16x32_bf16 v[108:111], v[128:131], v[200:203], v[108:111]
	v_mfma_f32_16x16x32_bf16 v[104:107], v[136:139], v[200:203], v[104:107]
	v_mfma_f32_16x16x32_bf16 v[92:95], v[128:131], v[208:211], v[92:95]
	v_mfma_f32_16x16x32_bf16 v[88:91], v[136:139], v[208:211], v[88:91]
	v_mfma_f32_16x16x32_bf16 v[76:79], v[128:131], v[216:219], v[76:79]
	v_mfma_f32_16x16x32_bf16 v[72:75], v[136:139], v[216:219], v[72:75]
	v_mfma_f32_16x16x32_bf16 v[124:127], v[132:135], v[196:199], v[124:127]
	v_mfma_f32_16x16x32_bf16 v[120:123], v[140:143], v[196:199], v[120:123]
	v_mfma_f32_16x16x32_bf16 v[108:111], v[132:135], v[204:207], v[108:111]
	v_mfma_f32_16x16x32_bf16 v[104:107], v[140:143], v[204:207], v[104:107]
	v_mfma_f32_16x16x32_bf16 v[92:95], v[132:135], v[212:215], v[92:95]
	v_mfma_f32_16x16x32_bf16 v[88:91], v[140:143], v[212:215], v[88:91]
	v_mfma_f32_16x16x32_bf16 v[76:79], v[132:135], v[220:223], v[76:79]
	v_mfma_f32_16x16x32_bf16 v[72:75], v[140:143], v[220:223], v[72:75]
	v_mfma_f32_16x16x32_bf16 v[116:119], v[160:163], v[192:195], v[116:119]
	v_mfma_f32_16x16x32_bf16 v[112:115], v[184:187], v[192:195], v[112:115]
	v_mfma_f32_16x16x32_bf16 v[100:103], v[160:163], v[200:203], v[100:103]
	v_mfma_f32_16x16x32_bf16 v[96:99], v[184:187], v[200:203], v[96:99]
	v_mfma_f32_16x16x32_bf16 v[84:87], v[160:163], v[208:211], v[84:87]
	v_mfma_f32_16x16x32_bf16 v[80:83], v[184:187], v[208:211], v[80:83]
	v_mfma_f32_16x16x32_bf16 v[68:71], v[160:163], v[216:219], v[68:71]
	v_mfma_f32_16x16x32_bf16 v[64:67], v[184:187], v[216:219], v[64:67]
	v_mfma_f32_16x16x32_bf16 v[116:119], v[164:167], v[196:199], v[116:119]
	v_mfma_f32_16x16x32_bf16 v[112:115], v[188:191], v[196:199], v[112:115]
	v_mfma_f32_16x16x32_bf16 v[100:103], v[164:167], v[204:207], v[100:103]
	v_mfma_f32_16x16x32_bf16 v[96:99], v[188:191], v[204:207], v[96:99]
	v_mfma_f32_16x16x32_bf16 v[84:87], v[164:167], v[212:215], v[84:87]
	v_mfma_f32_16x16x32_bf16 v[80:83], v[188:191], v[212:215], v[80:83]
	s_setprio 2
	s_barrier
; #define PG8_STAGE(bufoff, gbase, voff) do { _Pragma("unroll") for (int _i = 0; _i < 2; ++_i) \
;         __builtin_amdgcn_global_load_lds((const unsigned*)((const char*)(gbase) + (voff)[_i]), (PG8_LAS unsigned*)(lds + (bufoff) + ldsw + _i * 8192), 16, 0, 0); } while (0)
; #define PG8_LDA(dst, b, h) do { _Pragma("unroll") for (int m = 0; m < 4; ++m) _Pragma("unroll") for (int k = 0; k < 2; ++k) dst[m][k] = *(const PG8_LAS bf16x8*)(lds + PG8_SA(b, h) + aoff + m * 2048 + k * 1024); } while (0)
; #define PG8_MMA(ai, bj, At, Bt) do { __builtin_amdgcn_s_setprio(1); _Pragma("unroll") for (int m = 0; m < 4; ++m) _Pragma("unroll") for (int n = 0; n < 2; ++n) _Pragma("unroll") for (int k = 0; k < 2; ++k) \
;         acc[ai][bj][m][n] = __builtin_amdgcn_mfma_f32_16x16x32_bf16(Bt[n][k], At[m][k], acc[ai][bj][m][n], 0, 0, 0); __builtin_amdgcn_s_setprio(0); } while (0)
; #define PG8_WAIT_V(n) asm volatile("s_waitcnt vmcnt(" #n ")" ::: "memory")
; #define PG8_WAIT_L(n) asm volatile("s_waitcnt lgkmcnt(" #n ")" ::: "memory")
; #define PG8_BAR __builtin_amdgcn_s_barrier()
; #define PG8_SCHED __builtin_amdgcn_sched_barrier(0)
; template <class Epi, class Sched, bool ALIGN_EPI = false, bool SP2 = false>
; __device__ __forceinline__ void gemm_phase(PG8_LAS unsigned char* lds, const Gemm g, const Sched& S, const Epi& E) {
;     ...
;             PG8_WAIT_V(8); PG8_WAIT_L(0); PG8_BAR; PG8_MMA(0, 0, At, B0); PG8_MMA(0, 1, At, B1); PG8_BAR; PG8_SCHED;
;             PG8_LDA(At, 1, 1); PG8_STAGE(PG8_SB(1, 0), b3, voffB); PG8_STAGE(PG8_SB(1, 1), b3 + hstep, voffB); PG8_STAGE(PG8_SA(1, 0), a3, voffA);
;             PG8_WAIT_V(8); PG8_WAIT_L(0); PG8_BAR; PG8_MMA(1, 0, At, B0); PG8_MMA(1, 1, At, B1); PG8_BAR; PG8_SCHED;
;     ...
;         if constexpr (ALIGN_EPI) { if (wr == 0) PG8_BAR; }
	v_mfma_f32_16x16x32_bf16 v[68:71], v[164:167], v[220:223], v[68:71]
	v_mfma_f32_16x16x32_bf16 v[64:67], v[188:191], v[220:223], v[64:67]
	s_setprio 0
	s_add_i32 s52, s56, s78
	v_lshl_add_u64 v[168:169], v[168:169], 0, s[40:41]
	s_mov_b32 m0, s52
	ds_read_b128 v[192:195], v182 offset:49152
	ds_read_b128 v[196:199], v182 offset:50176
	ds_read_b128 v[200:203], v182 offset:51200
	ds_read_b128 v[204:207], v182 offset:52224
	ds_read_b128 v[208:211], v182 offset:53248
	ds_read_b128 v[212:215], v182 offset:54272
	ds_read_b128 v[216:219], v182 offset:55296
	ds_read_b128 v[220:223], v182 offset:56320
	global_load_lds_dwordx4 v[168:169], off
	s_add_i32 m0, s52, 0x2000
	s_add_u32 s52, s74, 0x80080
	v_lshl_add_u64 v[168:169], v[224:225], 0, s[40:41]
	s_addc_u32 s53, s75, 0
	s_add_i32 s56, s57, s78
	global_load_lds_dwordx4 v[168:169], off
	v_lshl_add_u64 v[168:169], s[52:53], 0, v[148:149]
	s_mov_b32 m0, s56
	s_nop 0
	global_load_lds_dwordx4 v[168:169], off
	v_lshl_add_u64 v[168:169], s[52:53], 0, v[152:153]
	s_add_i32 m0, s56, 0x2000
	s_nop 0
	global_load_lds_dwordx4 v[168:169], off
	v_lshl_add_u64 v[168:169], v[226:227], 0, s[40:41]
	s_mov_b32 m0, s3
	s_nop 0
	global_load_lds_dwordx4 v[168:169], off
	v_lshl_add_u64 v[168:169], v[228:229], 0, s[40:41]
	s_mov_b32 m0, s28
	s_nop 0
	global_load_lds_dwordx4 v[168:169], off
	s_waitcnt vmcnt(8)
	s_waitcnt lgkmcnt(0)
	s_setprio 1
	s_barrier
	v_mfma_f32_16x16x32_bf16 v[60:63], v[128:131], v[192:195], v[60:63]
	v_mfma_f32_16x16x32_bf16 v[56:59], v[136:139], v[192:195], v[56:59]
	v_mfma_f32_16x16x32_bf16 v[44:47], v[128:131], v[200:203], v[44:47]
	v_mfma_f32_16x16x32_bf16 v[40:43], v[136:139], v[200:203], v[40:43]
	v_mfma_f32_16x16x32_bf16 v[28:31], v[128:131], v[208:211], v[28:31]
	v_mfma_f32_16x16x32_bf16 v[24:27], v[136:139], v[208:211], v[24:27]
	v_mfma_f32_16x16x32_bf16 v[12:15], v[128:131], v[216:219], v[12:15]
	v_mfma_f32_16x16x32_bf16 v[8:11], v[136:139], v[216:219], v[8:11]
	v_mfma_f32_16x16x32_bf16 v[60:63], v[132:135], v[196:199], v[60:63]
	v_mfma_f32_16x16x32_bf16 v[56:59], v[140:143], v[196:199], v[56:59]
	v_mfma_f32_16x16x32_bf16 v[44:47], v[132:135], v[204:207], v[44:47]
	v_mfma_f32_16x16x32_bf16 v[40:43], v[140:143], v[204:207], v[40:43]
	v_mfma_f32_16x16x32_bf16 v[28:31], v[132:135], v[212:215], v[28:31]
	v_mfma_f32_16x16x32_bf16 v[24:27], v[140:143], v[212:215], v[24:27]
	v_mfma_f32_16x16x32_bf16 v[12:15], v[132:135], v[220:223], v[12:15]
	v_mfma_f32_16x16x32_bf16 v[8:11], v[140:143], v[220:223], v[8:11]
	v_mfma_f32_16x16x32_bf16 v[52:55], v[160:163], v[192:195], v[52:55]
	v_mfma_f32_16x16x32_bf16 v[48:51], v[184:187], v[192:195], v[48:51]
	v_mfma_f32_16x16x32_bf16 v[36:39], v[160:163], v[200:203], v[36:39]
	v_mfma_f32_16x16x32_bf16 v[32:35], v[184:187], v[200:203], v[32:35]
	v_mfma_f32_16x16x32_bf16 v[20:23], v[160:163], v[208:211], v[20:23]
	v_mfma_f32_16x16x32_bf16 v[16:19], v[184:187], v[208:211], v[16:19]
	v_mfma_f32_16x16x32_bf16 v[4:7], v[160:163], v[216:219], v[4:7]
	v_mfma_f32_16x16x32_bf16 v[0:3], v[184:187], v[216:219], v[0:3]
	v_mfma_f32_16x16x32_bf16 v[52:55], v[164:167], v[196:199], v[52:55]
	v_mfma_f32_16x16x32_bf16 v[48:51], v[188:191], v[196:199], v[48:51]
	v_mfma_f32_16x16x32_bf16 v[36:39], v[164:167], v[204:207], v[36:39]
	v_mfma_f32_16x16x32_bf16 v[32:35], v[188:191], v[204:207], v[32:35]
	v_mfma_f32_16x16x32_bf16 v[20:23], v[164:167], v[212:215], v[20:23]
	v_mfma_f32_16x16x32_bf16 v[16:19], v[188:191], v[212:215], v[16:19]
	s_setprio 2
	s_barrier
	v_mfma_f32_16x16x32_bf16 v[4:7], v[164:167], v[220:223], v[4:7]
	v_mfma_f32_16x16x32_bf16 v[0:3], v[188:191], v[220:223], v[0:3]
	s_setprio 0
	s_add_i32 s92, s92, 2
	s_add_u32 s72, s72, 0x100
	s_addc_u32 s73, s73, 0
	s_add_u32 s90, s90, 0x100
	s_addc_u32 s91, s91, 0
	s_cmp_gt_u32 s92, 29
	s_cbranch_scc0 .LBB0_809
	s_and_b64 vcc, exec, s[42:43]
	s_cbranch_vccz .LBB0_812
	s_barrier

; #define PG8_STAGE(bufoff, gbase, voff) do { _Pragma("unroll") for (int _i = 0; _i < 2; ++_i) \
;         __builtin_amdgcn_global_load_lds((const unsigned*)((const char*)(gbase) + (voff)[_i]), (PG8_LAS unsigned*)(lds + (bufoff) + ldsw + _i * 8192), 16, 0, 0); } while (0)
; #define PG8_LDA(dst, b, h) do { _Pragma("unroll") for (int m = 0; m < 4; ++m) _Pragma("unroll") for (int k = 0; k < 2; ++k) dst[m][k] = *(const PG8_LAS bf16x8*)(lds + PG8_SA(b, h) + aoff + m * 2048 + k * 1024); } while (0)
; #define PG8_LDB(dst, b, h) do { _Pragma("unroll") for (int n = 0; n < 2; ++n) _Pragma("unroll") for (int k = 0; k < 2; ++k) dst[n][k] = *(const PG8_LAS bf16x8*)(lds + PG8_SB(b, h) + boff + n * 2048 + k * 1024); } while (0)
; #define PG8_MMA(ai, bj, At, Bt) do { __builtin_amdgcn_s_setprio(1); _Pragma("unroll") for (int m = 0; m < 4; ++m) _Pragma("unroll") for (int n = 0; n < 2; ++n) _Pragma("unroll") for (int k = 0; k < 2; ++k) \
;         acc[ai][bj][m][n] = __builtin_amdgcn_mfma_f32_16x16x32_bf16(Bt[n][k], At[m][k], acc[ai][bj][m][n], 0, 0, 0); __builtin_amdgcn_s_setprio(0); } while (0)
; #define PG8_WAIT_V(n) asm volatile("s_waitcnt vmcnt(" #n ")" ::: "memory")
; #define PG8_WAIT_L(n) asm volatile("s_waitcnt lgkmcnt(" #n ")" ::: "memory")
; #define PG8_BAR __builtin_amdgcn_s_barrier()
; template <class Epi, class Sched, bool ALIGN_EPI = false, bool SP2 = false>
; __device__ __forceinline__ void gemm_phase(PG8_LAS unsigned char* lds, const Gemm g, const Sched& S, const Epi& E) {
;     ...
;         for (int t = 0; t < nt; t += 2) {
;             const bool last = (t == nt - 2);
;             const char* a1 = cA + (size_t)(t + 1) * kstep;
;             const char* a2 = last ? nA : cA + (size_t)(t + 2) * kstep; const char* b2 = last ? nB : cB + (size_t)(t + 2) * kstep;
;             const char* a3 = a2 + kstep; const char* b3 = b2 + kstep;
;             if constexpr (SP2) {
;             PG8_LDB(B0, 0, 0); PG8_LDB(B1, 0, 1); PG8_SCHED; PG8_LDA(At, 0, 0); PG8_STAGE(PG8_SA(1, 1), a1 + hstep, voffA);
;             PG8_WAIT_V(8); PG8_WAIT_L(0); PG8_BAR; PG8_MMA(0, 0, At, B0); PG8_MMA(0, 1, At, B1); PG8_BAR; PG8_SCHED;
;             PG8_LDA(At, 0, 1); PG8_STAGE(PG8_SB(0, 0), b2, voffB); PG8_STAGE(PG8_SB(0, 1), b2 + hstep, voffB); PG8_STAGE(PG8_SA(0, 0), a2, voffA);
;             PG8_WAIT_V(8); PG8_WAIT_L(0); PG8_BAR; PG8_MMA(1, 0, At, B0); PG8_MMA(1, 1, At, B1); PG8_BAR; PG8_SCHED;
.LBB0_1051:
	ds_read_b128 v[128:131], v205
	ds_read_b128 v[132:135], v205 offset:1024
	ds_read_b128 v[154:157], v205 offset:2048
	ds_read_b128 v[158:161], v205 offset:3072
	ds_read_b128 v[162:165], v206
	ds_read_b128 v[166:169], v206 offset:1024
	ds_read_b128 v[170:173], v206 offset:2048
	ds_read_b128 v[174:177], v206 offset:3072
	s_add_u32 s54, s52, 0xfff80080
	s_addc_u32 s55, s53, -1
	s_cmp_eq_u32 s77, 28
	s_cselect_b32 s57, s43, s55
	s_cselect_b32 s56, s49, s54
	s_cselect_b32 s55, s37, s76
	s_cselect_b32 s54, s51, s75
	v_lshl_add_u64 v[218:219], s[52:53], 0, v[144:145]
	s_add_i32 m0, s61, 0xc000
	ds_read_b128 v[178:181], v207
	ds_read_b128 v[182:185], v207 offset:1024
	ds_read_b128 v[186:189], v207 offset:2048
	ds_read_b128 v[190:193], v207 offset:3072
	ds_read_b128 v[194:197], v207 offset:4096
	ds_read_b128 v[198:201], v207 offset:5120
	ds_read_b128 v[210:213], v207 offset:6144
	ds_read_b128 v[214:217], v207 offset:7168
	global_load_lds_dwordx4 v[218:219], off
	v_lshl_add_u64 v[218:219], s[52:53], 0, v[148:149]
	s_add_i32 m0, s61, 0xe000
	s_nop 0
	global_load_lds_dwordx4 v[218:219], off
	s_waitcnt vmcnt(8)
	s_waitcnt lgkmcnt(0)
	s_setprio 1
	s_barrier
	v_mfma_f32_16x16x32_bf16 v[124:127], v[128:131], v[178:181], v[124:127]
	v_mfma_f32_16x16x32_bf16 v[120:123], v[154:157], v[178:181], v[120:123]
	v_mfma_f32_16x16x32_bf16 v[116:119], v[128:131], v[186:189], v[116:119]
	v_mfma_f32_16x16x32_bf16 v[112:115], v[154:157], v[186:189], v[112:115]
	v_mfma_f32_16x16x32_bf16 v[108:111], v[128:131], v[194:197], v[108:111]
	v_mfma_f32_16x16x32_bf16 v[104:107], v[154:157], v[194:197], v[104:107]
	v_mfma_f32_16x16x32_bf16 v[100:103], v[128:131], v[210:213], v[100:103]
	v_mfma_f32_16x16x32_bf16 v[96:99], v[154:157], v[210:213], v[96:99]
	v_mfma_f32_16x16x32_bf16 v[124:127], v[132:135], v[182:185], v[124:127]
	v_mfma_f32_16x16x32_bf16 v[120:123], v[158:161], v[182:185], v[120:123]
	v_mfma_f32_16x16x32_bf16 v[116:119], v[132:135], v[190:193], v[116:119]
	v_mfma_f32_16x16x32_bf16 v[112:115], v[158:161], v[190:193], v[112:115]
	v_mfma_f32_16x16x32_bf16 v[108:111], v[132:135], v[198:201], v[108:111]
	v_mfma_f32_16x16x32_bf16 v[104:107], v[158:161], v[198:201], v[104:107]
	v_mfma_f32_16x16x32_bf16 v[100:103], v[132:135], v[214:217], v[100:103]
	v_mfma_f32_16x16x32_bf16 v[96:99], v[158:161], v[214:217], v[96:99]
	v_mfma_f32_16x16x32_bf16 v[60:63], v[162:165], v[178:181], v[60:63]
	v_mfma_f32_16x16x32_bf16 v[56:59], v[170:173], v[178:181], v[56:59]
	v_mfma_f32_16x16x32_bf16 v[52:55], v[162:165], v[186:189], v[52:55]
	v_mfma_f32_16x16x32_bf16 v[48:51], v[170:173], v[186:189], v[48:51]
	v_mfma_f32_16x16x32_bf16 v[44:47], v[162:165], v[194:197], v[44:47]
	v_mfma_f32_16x16x32_bf16 v[40:43], v[170:173], v[194:197], v[40:43]
	v_mfma_f32_16x16x32_bf16 v[36:39], v[162:165], v[210:213], v[36:39]
	v_mfma_f32_16x16x32_bf16 v[32:35], v[170:173], v[210:213], v[32:35]
	v_mfma_f32_16x16x32_bf16 v[60:63], v[166:169], v[182:185], v[60:63]
	v_mfma_f32_16x16x32_bf16 v[56:59], v[174:177], v[182:185], v[56:59]
	v_mfma_f32_16x16x32_bf16 v[52:55], v[166:169], v[190:193], v[52:55]
	v_mfma_f32_16x16x32_bf16 v[48:51], v[174:177], v[190:193], v[48:51]
	v_mfma_f32_16x16x32_bf16 v[44:47], v[166:169], v[198:201], v[44:47]
	v_mfma_f32_16x16x32_bf16 v[40:43], v[174:177], v[198:201], v[40:43]
	s_setprio 2
	s_barrier
	v_mfma_f32_16x16x32_bf16 v[36:39], v[166:169], v[214:217], v[36:39]
	v_mfma_f32_16x16x32_bf16 v[32:35], v[174:177], v[214:217], v[32:35]
	s_setprio 0
	s_add_i32 s78, s33, s60
	v_lshl_add_u64 v[218:219], s[54:55], 0, v[138:139]
	s_mov_b32 m0, s78
	ds_read_b128 v[178:181], v207 offset:16384
	ds_read_b128 v[182:185], v207 offset:17408
	ds_read_b128 v[186:189], v207 offset:18432
	ds_read_b128 v[190:193], v207 offset:19456
	ds_read_b128 v[194:197], v207 offset:20480
	ds_read_b128 v[198:201], v207 offset:21504
	ds_read_b128 v[210:213], v207 offset:22528
	ds_read_b128 v[214:217], v207 offset:23552
	global_load_lds_dwordx4 v[218:219], off
	s_add_i32 m0, s78, 0x2000
	s_add_u32 s78, s54, 0x80000
	v_lshl_add_u64 v[220:221], s[54:55], 0, v[142:143]
	s_addc_u32 s79, s55, 0
	s_add_i32 s80, s74, s60
	global_load_lds_dwordx4 v[220:221], off
	v_lshl_add_u64 v[222:223], s[78:79], 0, v[138:139]
	s_mov_b32 m0, s80
	v_lshl_add_u64 v[224:225], s[56:57], 0, v[140:141]
	global_load_lds_dwordx4 v[222:223], off
	v_lshl_add_u64 v[222:223], s[78:79], 0, v[142:143]
	s_add_i32 m0, s80, 0x2000
	s_nop 0
	global_load_lds_dwordx4 v[222:223], off
	v_lshl_add_u64 v[222:223], s[56:57], 0, v[136:137]
	s_mov_b32 m0, s61
	s_nop 0
	global_load_lds_dwordx4 v[222:223], off
	s_mov_b32 m0, s62
	s_nop 0
	global_load_lds_dwordx4 v[224:225], off
	s_waitcnt vmcnt(8)
	s_waitcnt lgkmcnt(0)
	s_setprio 1
	s_barrier
; #define PG8_STAGE(bufoff, gbase, voff) do { _Pragma("unroll") for (int _i = 0; _i < 2; ++_i) \
;         __builtin_amdgcn_global_load_lds((const unsigned*)((const char*)(gbase) + (voff)[_i]), (PG8_LAS unsigned*)(lds + (bufoff) + ldsw + _i * 8192), 16, 0, 0); } while (0)
; #define PG8_LDA(dst, b, h) do { _Pragma("unroll") for (int m = 0; m < 4; ++m) _Pragma("unroll") for (int k = 0; k < 2; ++k) dst[m][k] = *(const PG8_LAS bf16x8*)(lds + PG8_SA(b, h) + aoff + m * 2048 + k * 1024); } while (0)
; #define PG8_LDB(dst, b, h) do { _Pragma("unroll") for (int n = 0; n < 2; ++n) _Pragma("unroll") for (int k = 0; k < 2; ++k) dst[n][k] = *(const PG8_LAS bf16x8*)(lds + PG8_SB(b, h) + boff + n * 2048 + k * 1024); } while (0)
; #define PG8_MMA(ai, bj, At, Bt) do { __builtin_amdgcn_s_setprio(1); _Pragma("unroll") for (int m = 0; m < 4; ++m) _Pragma("unroll") for (int n = 0; n < 2; ++n) _Pragma("unroll") for (int k = 0; k < 2; ++k) \
;         acc[ai][bj][m][n] = __builtin_amdgcn_mfma_f32_16x16x32_bf16(Bt[n][k], At[m][k], acc[ai][bj][m][n], 0, 0, 0); __builtin_amdgcn_s_setprio(0); } while (0)
; #define PG8_WAIT_V(n) asm volatile("s_waitcnt vmcnt(" #n ")" ::: "memory")
; template <class Epi, class Sched, bool ALIGN_EPI = false, bool SP2 = false>
; __device__ __forceinline__ void gemm_phase(PG8_LAS unsigned char* lds, const Gemm g, const Sched& S, const Epi& E) {
;     ...
;             PG8_LDB(B0, 0, 0); PG8_LDB(B1, 0, 1); PG8_SCHED; PG8_LDA(At, 0, 0); PG8_STAGE(PG8_SA(1, 1), a1 + hstep, voffA);
;             PG8_WAIT_V(8); PG8_WAIT_L(0); PG8_BAR; PG8_MMA(0, 0, At, B0); PG8_MMA(0, 1, At, B1); PG8_BAR; PG8_SCHED;
;             PG8_LDA(At, 0, 1); PG8_STAGE(PG8_SB(0, 0), b2, voffB); PG8_STAGE(PG8_SB(0, 1), b2 + hstep, voffB); PG8_STAGE(PG8_SA(0, 0), a2, voffA);
;             PG8_WAIT_V(8); PG8_WAIT_L(0); PG8_BAR; PG8_MMA(1, 0, At, B0); PG8_MMA(1, 1, At, B1); PG8_BAR; PG8_SCHED;
;             PG8_LDB(B0, 1, 0); PG8_LDB(B1, 1, 1); PG8_SCHED; PG8_LDA(At, 1, 0); PG8_STAGE(PG8_SA(0, 1), a2 + hstep, voffA);
;             PG8_WAIT_V(8); PG8_WAIT_L(0); PG8_BAR; PG8_MMA(0, 0, At, B0); PG8_MMA(0, 1, At, B1); PG8_BAR; PG8_SCHED;
;             PG8_LDA(At, 1, 1); PG8_STAGE(PG8_SB(1, 0), b3, voffB); PG8_STAGE(PG8_SB(1, 1), b3 + hstep, voffB); PG8_STAGE(PG8_SA(1, 0), a3, voffA);
;             PG8_WAIT_V(8); PG8_WAIT_L(0); PG8_BAR; PG8_MMA(1, 0, At, B0); PG8_MMA(1, 1, At, B1); PG8_BAR; PG8_SCHED;
	v_mfma_f32_16x16x32_bf16 v[92:95], v[128:131], v[178:181], v[92:95]
	v_mfma_f32_16x16x32_bf16 v[88:91], v[154:157], v[178:181], v[88:91]
	v_mfma_f32_16x16x32_bf16 v[84:87], v[128:131], v[186:189], v[84:87]
	v_mfma_f32_16x16x32_bf16 v[80:83], v[154:157], v[186:189], v[80:83]
	v_mfma_f32_16x16x32_bf16 v[76:79], v[128:131], v[194:197], v[76:79]
	v_mfma_f32_16x16x32_bf16 v[72:75], v[154:157], v[194:197], v[72:75]
	v_mfma_f32_16x16x32_bf16 v[68:71], v[128:131], v[210:213], v[68:71]
	v_mfma_f32_16x16x32_bf16 v[64:67], v[154:157], v[210:213], v[64:67]
	v_mfma_f32_16x16x32_bf16 v[92:95], v[132:135], v[182:185], v[92:95]
	v_mfma_f32_16x16x32_bf16 v[88:91], v[158:161], v[182:185], v[88:91]
	v_mfma_f32_16x16x32_bf16 v[84:87], v[132:135], v[190:193], v[84:87]
	v_mfma_f32_16x16x32_bf16 v[80:83], v[158:161], v[190:193], v[80:83]
	v_mfma_f32_16x16x32_bf16 v[76:79], v[132:135], v[198:201], v[76:79]
	v_mfma_f32_16x16x32_bf16 v[72:75], v[158:161], v[198:201], v[72:75]
	v_mfma_f32_16x16x32_bf16 v[68:71], v[132:135], v[214:217], v[68:71]
	v_mfma_f32_16x16x32_bf16 v[64:67], v[158:161], v[214:217], v[64:67]
	v_mfma_f32_16x16x32_bf16 v[28:31], v[162:165], v[178:181], v[28:31]
	v_mfma_f32_16x16x32_bf16 v[24:27], v[170:173], v[178:181], v[24:27]
	v_mfma_f32_16x16x32_bf16 v[20:23], v[162:165], v[186:189], v[20:23]
	v_mfma_f32_16x16x32_bf16 v[16:19], v[170:173], v[186:189], v[16:19]
	v_mfma_f32_16x16x32_bf16 v[12:15], v[162:165], v[194:197], v[12:15]
	v_mfma_f32_16x16x32_bf16 v[8:11], v[170:173], v[194:197], v[8:11]
	v_mfma_f32_16x16x32_bf16 v[4:7], v[162:165], v[210:213], v[4:7]
	v_mfma_f32_16x16x32_bf16 v[0:3], v[170:173], v[210:213], v[0:3]
	v_mfma_f32_16x16x32_bf16 v[28:31], v[166:169], v[182:185], v[28:31]
	v_mfma_f32_16x16x32_bf16 v[24:27], v[174:177], v[182:185], v[24:27]
	v_mfma_f32_16x16x32_bf16 v[20:23], v[166:169], v[190:193], v[20:23]
	v_mfma_f32_16x16x32_bf16 v[16:19], v[174:177], v[190:193], v[16:19]
	v_mfma_f32_16x16x32_bf16 v[12:15], v[166:169], v[198:201], v[12:15]
	v_mfma_f32_16x16x32_bf16 v[8:11], v[174:177], v[198:201], v[8:11]
	s_setprio 2
	s_barrier
	v_mfma_f32_16x16x32_bf16 v[4:7], v[166:169], v[214:217], v[4:7]
	v_mfma_f32_16x16x32_bf16 v[0:3], v[174:177], v[214:217], v[0:3]
	s_setprio 0
	s_add_i32 s78, 0, 0x18000
	s_add_i32 s79, 0, 0x1c000
	v_add_u32_e32 v158, s78, v203
	v_add_u32_e32 v174, s79, v203
	ds_read_b128 v[128:131], v158
	ds_read_b128 v[132:135], v158 offset:1024
	ds_read_b128 v[154:157], v158 offset:2048
	ds_read_b128 v[158:161], v158 offset:3072
	ds_read_b128 v[162:165], v174
	ds_read_b128 v[166:169], v174 offset:1024
	ds_read_b128 v[170:173], v174 offset:2048
	ds_read_b128 v[174:177], v174 offset:3072
	s_add_u32 s56, s56, 0x80000
	s_addc_u32 s57, s57, 0
	s_mov_b32 m0, s63
	v_lshl_add_u64 v[226:227], s[56:57], 0, v[136:137]
	ds_read_b128 v[178:181], v207 offset:32768
	ds_read_b128 v[182:185], v207 offset:33792
	ds_read_b128 v[186:189], v207 offset:34816
	ds_read_b128 v[190:193], v207 offset:35840
	ds_read_b128 v[194:197], v207 offset:36864
	ds_read_b128 v[198:201], v207 offset:37888
	ds_read_b128 v[210:213], v207 offset:38912
	ds_read_b128 v[214:217], v207 offset:39936
	global_load_lds_dwordx4 v[226:227], off
	v_lshl_add_u64 v[226:227], s[56:57], 0, v[140:141]
	s_mov_b32 m0, s64
	s_nop 0
	global_load_lds_dwordx4 v[226:227], off
	s_waitcnt vmcnt(8)
	s_waitcnt lgkmcnt(0)
	s_setprio 1
	s_barrier
	v_mfma_f32_16x16x32_bf16 v[124:127], v[128:131], v[178:181], v[124:127]
	v_mfma_f32_16x16x32_bf16 v[120:123], v[154:157], v[178:181], v[120:123]
	v_mfma_f32_16x16x32_bf16 v[116:119], v[128:131], v[186:189], v[116:119]
	v_mfma_f32_16x16x32_bf16 v[112:115], v[154:157], v[186:189], v[112:115]
	v_mfma_f32_16x16x32_bf16 v[108:111], v[128:131], v[194:197], v[108:111]
	v_mfma_f32_16x16x32_bf16 v[104:107], v[154:157], v[194:197], v[104:107]
	v_mfma_f32_16x16x32_bf16 v[100:103], v[128:131], v[210:213], v[100:103]
	v_mfma_f32_16x16x32_bf16 v[96:99], v[154:157], v[210:213], v[96:99]
	v_mfma_f32_16x16x32_bf16 v[124:127], v[132:135], v[182:185], v[124:127]
	v_mfma_f32_16x16x32_bf16 v[120:123], v[158:161], v[182:185], v[120:123]
	v_mfma_f32_16x16x32_bf16 v[116:119], v[132:135], v[190:193], v[116:119]
	v_mfma_f32_16x16x32_bf16 v[112:115], v[158:161], v[190:193], v[112:115]
	v_mfma_f32_16x16x32_bf16 v[108:111], v[132:135], v[198:201], v[108:111]
	v_mfma_f32_16x16x32_bf16 v[104:107], v[158:161], v[198:201], v[104:107]
	v_mfma_f32_16x16x32_bf16 v[100:103], v[132:135], v[214:217], v[100:103]
	v_mfma_f32_16x16x32_bf16 v[96:99], v[158:161], v[214:217], v[96:99]
	v_mfma_f32_16x16x32_bf16 v[60:63], v[162:165], v[178:181], v[60:63]
	v_mfma_f32_16x16x32_bf16 v[56:59], v[170:173], v[178:181], v[56:59]
	v_mfma_f32_16x16x32_bf16 v[52:55], v[162:165], v[186:189], v[52:55]
	v_mfma_f32_16x16x32_bf16 v[48:51], v[170:173], v[186:189], v[48:51]
	v_mfma_f32_16x16x32_bf16 v[44:47], v[162:165], v[194:197], v[44:47]
	v_mfma_f32_16x16x32_bf16 v[40:43], v[170:173], v[194:197], v[40:43]
	v_mfma_f32_16x16x32_bf16 v[36:39], v[162:165], v[210:213], v[36:39]
	v_mfma_f32_16x16x32_bf16 v[32:35], v[170:173], v[210:213], v[32:35]
	v_mfma_f32_16x16x32_bf16 v[60:63], v[166:169], v[182:185], v[60:63]
	v_mfma_f32_16x16x32_bf16 v[56:59], v[174:177], v[182:185], v[56:59]
	v_mfma_f32_16x16x32_bf16 v[52:55], v[166:169], v[190:193], v[52:55]
	v_mfma_f32_16x16x32_bf16 v[48:51], v[174:177], v[190:193], v[48:51]
	v_mfma_f32_16x16x32_bf16 v[44:47], v[166:169], v[198:201], v[44:47]
	v_mfma_f32_16x16x32_bf16 v[40:43], v[174:177], v[198:201], v[40:43]
	s_setprio 2
	s_barrier
; #define PG8_STAGE(bufoff, gbase, voff) do { _Pragma("unroll") for (int _i = 0; _i < 2; ++_i) \
;         __builtin_amdgcn_global_load_lds((const unsigned*)((const char*)(gbase) + (voff)[_i]), (PG8_LAS unsigned*)(lds + (bufoff) + ldsw + _i * 8192), 16, 0, 0); } while (0)
; #define PG8_LDA(dst, b, h) do { _Pragma("unroll") for (int m = 0; m < 4; ++m) _Pragma("unroll") for (int k = 0; k < 2; ++k) dst[m][k] = *(const PG8_LAS bf16x8*)(lds + PG8_SA(b, h) + aoff + m * 2048 + k * 1024); } while (0)
; #define PG8_MMA(ai, bj, At, Bt) do { __builtin_amdgcn_s_setprio(1); _Pragma("unroll") for (int m = 0; m < 4; ++m) _Pragma("unroll") for (int n = 0; n < 2; ++n) _Pragma("unroll") for (int k = 0; k < 2; ++k) \
;         acc[ai][bj][m][n] = __builtin_amdgcn_mfma_f32_16x16x32_bf16(Bt[n][k], At[m][k], acc[ai][bj][m][n], 0, 0, 0); __builtin_amdgcn_s_setprio(0); } while (0)
; #define PG8_WAIT_V(n) asm volatile("s_waitcnt vmcnt(" #n ")" ::: "memory")
; #define PG8_WAIT_L(n) asm volatile("s_waitcnt lgkmcnt(" #n ")" ::: "memory")
; #define PG8_BAR __builtin_amdgcn_s_barrier()
; #define PG8_SCHED __builtin_amdgcn_sched_barrier(0)
; template <class Epi, class Sched, bool ALIGN_EPI = false, bool SP2 = false>
; __device__ __forceinline__ void gemm_phase(PG8_LAS unsigned char* lds, const Gemm g, const Sched& S, const Epi& E) {
;     ...
;             PG8_WAIT_V(8); PG8_WAIT_L(0); PG8_BAR; PG8_MMA(0, 0, At, B0); PG8_MMA(0, 1, At, B1); PG8_BAR; PG8_SCHED;
;             PG8_LDA(At, 1, 1); PG8_STAGE(PG8_SB(1, 0), b3, voffB); PG8_STAGE(PG8_SB(1, 1), b3 + hstep, voffB); PG8_STAGE(PG8_SA(1, 0), a3, voffA);
;             PG8_WAIT_V(8); PG8_WAIT_L(0); PG8_BAR; PG8_MMA(1, 0, At, B0); PG8_MMA(1, 1, At, B1); PG8_BAR; PG8_SCHED;
	v_mfma_f32_16x16x32_bf16 v[36:39], v[166:169], v[214:217], v[36:39]
	v_mfma_f32_16x16x32_bf16 v[32:35], v[174:177], v[214:217], v[32:35]
	s_setprio 0
	s_add_i32 s56, s78, s60
	v_lshl_add_u64 v[218:219], v[218:219], 0, s[12:13]
	s_mov_b32 m0, s56
	ds_read_b128 v[178:181], v207 offset:49152
	ds_read_b128 v[182:185], v207 offset:50176
	ds_read_b128 v[186:189], v207 offset:51200
	ds_read_b128 v[190:193], v207 offset:52224
	ds_read_b128 v[194:197], v207 offset:53248
	ds_read_b128 v[198:201], v207 offset:54272
	ds_read_b128 v[210:213], v207 offset:55296
	ds_read_b128 v[214:217], v207 offset:56320
	global_load_lds_dwordx4 v[218:219], off
	s_add_i32 m0, s56, 0x2000
	s_add_u32 s54, s54, 0x80080
	v_lshl_add_u64 v[218:219], v[220:221], 0, s[12:13]
	s_addc_u32 s55, s55, 0
	s_add_i32 s56, s79, s60
	global_load_lds_dwordx4 v[218:219], off
	v_lshl_add_u64 v[218:219], s[54:55], 0, v[138:139]
	s_mov_b32 m0, s56
	s_nop 0
	global_load_lds_dwordx4 v[218:219], off
	v_lshl_add_u64 v[218:219], s[54:55], 0, v[142:143]
	s_add_i32 m0, s56, 0x2000
	s_nop 0
	global_load_lds_dwordx4 v[218:219], off
	v_lshl_add_u64 v[218:219], v[222:223], 0, s[12:13]
	s_mov_b32 m0, s70
	s_nop 0
	global_load_lds_dwordx4 v[218:219], off
	v_lshl_add_u64 v[218:219], v[224:225], 0, s[12:13]
	s_mov_b32 m0, s71
	s_nop 0
	global_load_lds_dwordx4 v[218:219], off
	s_waitcnt vmcnt(8)
	s_waitcnt lgkmcnt(0)
	s_setprio 1
	s_barrier
	v_mfma_f32_16x16x32_bf16 v[92:95], v[128:131], v[178:181], v[92:95]
	v_mfma_f32_16x16x32_bf16 v[88:91], v[154:157], v[178:181], v[88:91]
	v_mfma_f32_16x16x32_bf16 v[84:87], v[128:131], v[186:189], v[84:87]
	v_mfma_f32_16x16x32_bf16 v[80:83], v[154:157], v[186:189], v[80:83]
	v_mfma_f32_16x16x32_bf16 v[76:79], v[128:131], v[194:197], v[76:79]
	v_mfma_f32_16x16x32_bf16 v[72:75], v[154:157], v[194:197], v[72:75]
	v_mfma_f32_16x16x32_bf16 v[68:71], v[128:131], v[210:213], v[68:71]
	v_mfma_f32_16x16x32_bf16 v[64:67], v[154:157], v[210:213], v[64:67]
	v_mfma_f32_16x16x32_bf16 v[92:95], v[132:135], v[182:185], v[92:95]
	v_mfma_f32_16x16x32_bf16 v[88:91], v[158:161], v[182:185], v[88:91]
	v_mfma_f32_16x16x32_bf16 v[84:87], v[132:135], v[190:193], v[84:87]
	v_mfma_f32_16x16x32_bf16 v[80:83], v[158:161], v[190:193], v[80:83]
	v_mfma_f32_16x16x32_bf16 v[76:79], v[132:135], v[198:201], v[76:79]
	v_mfma_f32_16x16x32_bf16 v[72:75], v[158:161], v[198:201], v[72:75]
	v_mfma_f32_16x16x32_bf16 v[68:71], v[132:135], v[214:217], v[68:71]
	v_mfma_f32_16x16x32_bf16 v[64:67], v[158:161], v[214:217], v[64:67]
	v_mfma_f32_16x16x32_bf16 v[28:31], v[162:165], v[178:181], v[28:31]
	v_mfma_f32_16x16x32_bf16 v[24:27], v[170:173], v[178:181], v[24:27]
	v_mfma_f32_16x16x32_bf16 v[20:23], v[162:165], v[186:189], v[20:23]
	v_mfma_f32_16x16x32_bf16 v[16:19], v[170:173], v[186:189], v[16:19]
	v_mfma_f32_16x16x32_bf16 v[12:15], v[162:165], v[194:197], v[12:15]
	v_mfma_f32_16x16x32_bf16 v[8:11], v[170:173], v[194:197], v[8:11]
	v_mfma_f32_16x16x32_bf16 v[4:7], v[162:165], v[210:213], v[4:7]
	v_mfma_f32_16x16x32_bf16 v[0:3], v[170:173], v[210:213], v[0:3]
	v_mfma_f32_16x16x32_bf16 v[28:31], v[166:169], v[182:185], v[28:31]
	v_mfma_f32_16x16x32_bf16 v[24:27], v[174:177], v[182:185], v[24:27]
	v_mfma_f32_16x16x32_bf16 v[20:23], v[166:169], v[190:193], v[20:23]
	v_mfma_f32_16x16x32_bf16 v[16:19], v[174:177], v[190:193], v[16:19]
	v_mfma_f32_16x16x32_bf16 v[12:15], v[166:169], v[198:201], v[12:15]
	v_mfma_f32_16x16x32_bf16 v[8:11], v[174:177], v[198:201], v[8:11]
	s_setprio 2
	s_barrier
	v_mfma_f32_16x16x32_bf16 v[4:7], v[166:169], v[214:217], v[4:7]
	v_mfma_f32_16x16x32_bf16 v[0:3], v[174:177], v[214:217], v[0:3]
	s_setprio 0
	s_add_i32 s77, s77, 2
	s_add_u32 s52, s52, 0x100
	s_addc_u32 s53, s53, 0
	s_add_u32 s75, s75, 0x100
	s_addc_u32 s76, s76, 0
	s_cmp_gt_u32 s77, 29
	s_cbranch_scc0 .LBB0_1051
	s_and_b64 vcc, exec, s[14:15]
	s_cbranch_vccz .LBB0_1054
	s_barrier

; #define PG8_STAGE(bufoff, gbase, voff) do { _Pragma("unroll") for (int _i = 0; _i < 2; ++_i) \
;         __builtin_amdgcn_global_load_lds((const unsigned*)((const char*)(gbase) + (voff)[_i]), (PG8_LAS unsigned*)(lds + (bufoff) + ldsw + _i * 8192), 16, 0, 0); } while (0)
; #define PG8_LDA(dst, b, h) do { _Pragma("unroll") for (int m = 0; m < 4; ++m) _Pragma("unroll") for (int k = 0; k < 2; ++k) dst[m][k] = *(const PG8_LAS bf16x8*)(lds + PG8_SA(b, h) + aoff + m * 2048 + k * 1024); } while (0)
; #define PG8_LDB(dst, b, h) do { _Pragma("unroll") for (int n = 0; n < 2; ++n) _Pragma("unroll") for (int k = 0; k < 2; ++k) dst[n][k] = *(const PG8_LAS bf16x8*)(lds + PG8_SB(b, h) + boff + n * 2048 + k * 1024); } while (0)
; #define PG8_MMA(ai, bj, At, Bt) do { __builtin_amdgcn_s_setprio(1); _Pragma("unroll") for (int m = 0; m < 4; ++m) _Pragma("unroll") for (int n = 0; n < 2; ++n) _Pragma("unroll") for (int k = 0; k < 2; ++k) \
;         acc[ai][bj][m][n] = __builtin_amdgcn_mfma_f32_16x16x32_bf16(Bt[n][k], At[m][k], acc[ai][bj][m][n], 0, 0, 0); __builtin_amdgcn_s_setprio(0); } while (0)
; #define PG8_WAIT_V(n) asm volatile("s_waitcnt vmcnt(" #n ")" ::: "memory")
; #define PG8_WAIT_L(n) asm volatile("s_waitcnt lgkmcnt(" #n ")" ::: "memory")
; #define PG8_BAR __builtin_amdgcn_s_barrier()
; template <class Epi, class Sched, bool ALIGN_EPI = false, bool SP2 = false>
; __device__ __forceinline__ void gemm_phase(PG8_LAS unsigned char* lds, const Gemm g, const Sched& S, const Epi& E) {
;     ...
;             const bool last = (t == nt - 2);
;             const char* a1 = cA + (size_t)(t + 1) * kstep;
;             const char* a2 = last ? nA : cA + (size_t)(t + 2) * kstep; const char* b2 = last ? nB : cB + (size_t)(t + 2) * kstep;
;             const char* a3 = a2 + kstep; const char* b3 = b2 + kstep;
;             if constexpr (SP2) {
;             PG8_LDB(B0, 0, 0); PG8_LDB(B1, 0, 1); PG8_SCHED; PG8_LDA(At, 0, 0); PG8_STAGE(PG8_SA(1, 1), a1 + hstep, voffA);
;             PG8_WAIT_V(8); PG8_WAIT_L(0); PG8_BAR; PG8_MMA(0, 0, At, B0); PG8_MMA(0, 1, At, B1); PG8_BAR; PG8_SCHED;
;             PG8_LDA(At, 0, 1); PG8_STAGE(PG8_SB(0, 0), b2, voffB); PG8_STAGE(PG8_SB(0, 1), b2 + hstep, voffB); PG8_STAGE(PG8_SA(0, 0), a2, voffA);
;             PG8_WAIT_V(8); PG8_WAIT_L(0); PG8_BAR; PG8_MMA(1, 0, At, B0); PG8_MMA(1, 1, At, B1); PG8_BAR; PG8_SCHED;
.LBB0_1142:
	ds_read_b128 v[80:83], v171
	ds_read_b128 v[84:87], v171 offset:1024
	ds_read_b128 v[88:91], v171 offset:2048
	ds_read_b128 v[92:95], v171 offset:3072
	ds_read_b128 v[164:167], v172
	ds_read_b128 v[176:179], v172 offset:1024
	ds_read_b128 v[180:183], v172 offset:2048
	ds_read_b128 v[184:187], v172 offset:3072
	s_add_u32 s44, s42, 0xfff80080
	s_addc_u32 s45, s43, -1
	s_cmp_eq_u32 s64, 28
	s_cselect_b32 s47, s15, s45
	s_cselect_b32 s46, s60, s44
	s_cselect_b32 s45, s13, s63
	s_cselect_b32 s44, s61, s62
	v_lshl_add_u64 v[220:221], s[42:43], 0, v[156:157]
	s_add_i32 m0, s41, 0xc000
	ds_read_b128 v[188:191], v173
	ds_read_b128 v[192:195], v173 offset:1024
	ds_read_b128 v[196:199], v173 offset:2048
	ds_read_b128 v[200:203], v173 offset:3072
	ds_read_b128 v[204:207], v173 offset:4096
	ds_read_b128 v[208:211], v173 offset:5120
	ds_read_b128 v[212:215], v173 offset:6144
	ds_read_b128 v[216:219], v173 offset:7168
	global_load_lds_dwordx4 v[220:221], off
	v_lshl_add_u64 v[220:221], s[42:43], 0, v[158:159]
	s_add_i32 m0, s41, 0xe000
	s_nop 0
	global_load_lds_dwordx4 v[220:221], off
	s_waitcnt vmcnt(8)
	s_waitcnt lgkmcnt(0)
	s_setprio 1
	s_barrier
	v_mfma_f32_16x16x32_bf16 v[140:143], v[80:83], v[188:191], v[140:143]
	v_mfma_f32_16x16x32_bf16 v[136:139], v[88:91], v[188:191], v[136:139]
	v_mfma_f32_16x16x32_bf16 v[124:127], v[80:83], v[196:199], v[124:127]
	v_mfma_f32_16x16x32_bf16 v[120:123], v[88:91], v[196:199], v[120:123]
	v_mfma_f32_16x16x32_bf16 v[108:111], v[80:83], v[204:207], v[108:111]
	v_mfma_f32_16x16x32_bf16 v[104:107], v[88:91], v[204:207], v[104:107]
	v_mfma_f32_16x16x32_bf16 v[76:79], v[80:83], v[212:215], v[76:79]
	v_mfma_f32_16x16x32_bf16 v[72:75], v[88:91], v[212:215], v[72:75]
	v_mfma_f32_16x16x32_bf16 v[140:143], v[84:87], v[192:195], v[140:143]
	v_mfma_f32_16x16x32_bf16 v[136:139], v[92:95], v[192:195], v[136:139]
	v_mfma_f32_16x16x32_bf16 v[124:127], v[84:87], v[200:203], v[124:127]
	v_mfma_f32_16x16x32_bf16 v[120:123], v[92:95], v[200:203], v[120:123]
	v_mfma_f32_16x16x32_bf16 v[108:111], v[84:87], v[208:211], v[108:111]
	v_mfma_f32_16x16x32_bf16 v[104:107], v[92:95], v[208:211], v[104:107]
	v_mfma_f32_16x16x32_bf16 v[76:79], v[84:87], v[216:219], v[76:79]
	v_mfma_f32_16x16x32_bf16 v[72:75], v[92:95], v[216:219], v[72:75]
	v_mfma_f32_16x16x32_bf16 v[132:135], v[164:167], v[188:191], v[132:135]
	v_mfma_f32_16x16x32_bf16 v[128:131], v[180:183], v[188:191], v[128:131]
	v_mfma_f32_16x16x32_bf16 v[116:119], v[164:167], v[196:199], v[116:119]
	v_mfma_f32_16x16x32_bf16 v[112:115], v[180:183], v[196:199], v[112:115]
	v_mfma_f32_16x16x32_bf16 v[100:103], v[164:167], v[204:207], v[100:103]
	v_mfma_f32_16x16x32_bf16 v[96:99], v[180:183], v[204:207], v[96:99]
	v_mfma_f32_16x16x32_bf16 v[68:71], v[164:167], v[212:215], v[68:71]
	v_mfma_f32_16x16x32_bf16 v[64:67], v[180:183], v[212:215], v[64:67]
	v_mfma_f32_16x16x32_bf16 v[132:135], v[176:179], v[192:195], v[132:135]
	v_mfma_f32_16x16x32_bf16 v[128:131], v[184:187], v[192:195], v[128:131]
	v_mfma_f32_16x16x32_bf16 v[116:119], v[176:179], v[200:203], v[116:119]
	v_mfma_f32_16x16x32_bf16 v[112:115], v[184:187], v[200:203], v[112:115]
	v_mfma_f32_16x16x32_bf16 v[100:103], v[176:179], v[208:211], v[100:103]
	v_mfma_f32_16x16x32_bf16 v[96:99], v[184:187], v[208:211], v[96:99]
	s_setprio 2
	s_barrier
	v_mfma_f32_16x16x32_bf16 v[68:71], v[176:179], v[216:219], v[68:71]
	v_mfma_f32_16x16x32_bf16 v[64:67], v[184:187], v[216:219], v[64:67]
	s_setprio 0
	s_add_i32 s65, s56, s33
	v_lshl_add_u64 v[220:221], s[44:45], 0, v[148:149]
	s_mov_b32 m0, s65
	ds_read_b128 v[188:191], v173 offset:16384
	ds_read_b128 v[192:195], v173 offset:17408
	ds_read_b128 v[196:199], v173 offset:18432
	ds_read_b128 v[200:203], v173 offset:19456
	ds_read_b128 v[204:207], v173 offset:20480
	ds_read_b128 v[208:211], v173 offset:21504
	ds_read_b128 v[212:215], v173 offset:22528
	ds_read_b128 v[216:219], v173 offset:23552
	global_load_lds_dwordx4 v[220:221], off
	s_add_i32 m0, s65, 0x2000
	s_add_u32 s66, s44, 0x80000
	v_lshl_add_u64 v[222:223], s[44:45], 0, v[152:153]
	s_addc_u32 s67, s45, 0
	s_add_i32 s65, s57, s33
	global_load_lds_dwordx4 v[222:223], off
	v_lshl_add_u64 v[224:225], s[66:67], 0, v[148:149]
	s_mov_b32 m0, s65
	v_lshl_add_u64 v[226:227], s[46:47], 0, v[150:151]
	global_load_lds_dwordx4 v[224:225], off
	v_lshl_add_u64 v[224:225], s[66:67], 0, v[152:153]
	s_add_i32 m0, s65, 0x2000
	s_nop 0
	global_load_lds_dwordx4 v[224:225], off
	v_lshl_add_u64 v[224:225], s[46:47], 0, v[144:145]
	s_mov_b32 m0, s41
	s_nop 0
	global_load_lds_dwordx4 v[224:225], off
	s_mov_b32 m0, s48
	s_nop 0
	global_load_lds_dwordx4 v[226:227], off
	s_waitcnt vmcnt(8)
	s_waitcnt lgkmcnt(0)
	s_setprio 1
	s_barrier
; #define PG8_STAGE(bufoff, gbase, voff) do { _Pragma("unroll") for (int _i = 0; _i < 2; ++_i) \
;         __builtin_amdgcn_global_load_lds((const unsigned*)((const char*)(gbase) + (voff)[_i]), (PG8_LAS unsigned*)(lds + (bufoff) + ldsw + _i * 8192), 16, 0, 0); } while (0)
; #define PG8_LDA(dst, b, h) do { _Pragma("unroll") for (int m = 0; m < 4; ++m) _Pragma("unroll") for (int k = 0; k < 2; ++k) dst[m][k] = *(const PG8_LAS bf16x8*)(lds + PG8_SA(b, h) + aoff + m * 2048 + k * 1024); } while (0)
; #define PG8_LDB(dst, b, h) do { _Pragma("unroll") for (int n = 0; n < 2; ++n) _Pragma("unroll") for (int k = 0; k < 2; ++k) dst[n][k] = *(const PG8_LAS bf16x8*)(lds + PG8_SB(b, h) + boff + n * 2048 + k * 1024); } while (0)
; #define PG8_MMA(ai, bj, At, Bt) do { __builtin_amdgcn_s_setprio(1); _Pragma("unroll") for (int m = 0; m < 4; ++m) _Pragma("unroll") for (int n = 0; n < 2; ++n) _Pragma("unroll") for (int k = 0; k < 2; ++k) \
;         acc[ai][bj][m][n] = __builtin_amdgcn_mfma_f32_16x16x32_bf16(Bt[n][k], At[m][k], acc[ai][bj][m][n], 0, 0, 0); __builtin_amdgcn_s_setprio(0); } while (0)
; #define PG8_WAIT_V(n) asm volatile("s_waitcnt vmcnt(" #n ")" ::: "memory")
; #define PG8_WAIT_L(n) asm volatile("s_waitcnt lgkmcnt(" #n ")" ::: "memory")
; #define PG8_BAR __builtin_amdgcn_s_barrier()
; #define PG8_SCHED __builtin_amdgcn_sched_barrier(0)
; template <class Epi, class Sched, bool ALIGN_EPI = false, bool SP2 = false>
; __device__ __forceinline__ void gemm_phase(PG8_LAS unsigned char* lds, const Gemm g, const Sched& S, const Epi& E) {
;     ...
;             PG8_LDB(B0, 0, 0); PG8_LDB(B1, 0, 1); PG8_SCHED; PG8_LDA(At, 0, 0); PG8_STAGE(PG8_SA(1, 1), a1 + hstep, voffA);
;             PG8_WAIT_V(8); PG8_WAIT_L(0); PG8_BAR; PG8_MMA(0, 0, At, B0); PG8_MMA(0, 1, At, B1); PG8_BAR; PG8_SCHED;
;             PG8_LDA(At, 0, 1); PG8_STAGE(PG8_SB(0, 0), b2, voffB); PG8_STAGE(PG8_SB(0, 1), b2 + hstep, voffB); PG8_STAGE(PG8_SA(0, 0), a2, voffA);
;             PG8_WAIT_V(8); PG8_WAIT_L(0); PG8_BAR; PG8_MMA(1, 0, At, B0); PG8_MMA(1, 1, At, B1); PG8_BAR; PG8_SCHED;
;             PG8_LDB(B0, 1, 0); PG8_LDB(B1, 1, 1); PG8_SCHED; PG8_LDA(At, 1, 0); PG8_STAGE(PG8_SA(0, 1), a2 + hstep, voffA);
;             PG8_WAIT_V(8); PG8_WAIT_L(0); PG8_BAR; PG8_MMA(0, 0, At, B0); PG8_MMA(0, 1, At, B1); PG8_BAR; PG8_SCHED;
	v_mfma_f32_16x16x32_bf16 v[60:63], v[80:83], v[188:191], v[60:63]
	v_mfma_f32_16x16x32_bf16 v[56:59], v[88:91], v[188:191], v[56:59]
	v_mfma_f32_16x16x32_bf16 v[44:47], v[80:83], v[196:199], v[44:47]
	v_mfma_f32_16x16x32_bf16 v[40:43], v[88:91], v[196:199], v[40:43]
	v_mfma_f32_16x16x32_bf16 v[28:31], v[80:83], v[204:207], v[28:31]
	v_mfma_f32_16x16x32_bf16 v[24:27], v[88:91], v[204:207], v[24:27]
	v_mfma_f32_16x16x32_bf16 v[12:15], v[80:83], v[212:215], v[12:15]
	v_mfma_f32_16x16x32_bf16 v[8:11], v[88:91], v[212:215], v[8:11]
	v_mfma_f32_16x16x32_bf16 v[60:63], v[84:87], v[192:195], v[60:63]
	v_mfma_f32_16x16x32_bf16 v[56:59], v[92:95], v[192:195], v[56:59]
	v_mfma_f32_16x16x32_bf16 v[44:47], v[84:87], v[200:203], v[44:47]
	v_mfma_f32_16x16x32_bf16 v[40:43], v[92:95], v[200:203], v[40:43]
	v_mfma_f32_16x16x32_bf16 v[28:31], v[84:87], v[208:211], v[28:31]
	v_mfma_f32_16x16x32_bf16 v[24:27], v[92:95], v[208:211], v[24:27]
	v_mfma_f32_16x16x32_bf16 v[12:15], v[84:87], v[216:219], v[12:15]
	v_mfma_f32_16x16x32_bf16 v[8:11], v[92:95], v[216:219], v[8:11]
	v_mfma_f32_16x16x32_bf16 v[52:55], v[164:167], v[188:191], v[52:55]
	v_mfma_f32_16x16x32_bf16 v[48:51], v[180:183], v[188:191], v[48:51]
	v_mfma_f32_16x16x32_bf16 v[36:39], v[164:167], v[196:199], v[36:39]
	v_mfma_f32_16x16x32_bf16 v[32:35], v[180:183], v[196:199], v[32:35]
	v_mfma_f32_16x16x32_bf16 v[20:23], v[164:167], v[204:207], v[20:23]
	v_mfma_f32_16x16x32_bf16 v[16:19], v[180:183], v[204:207], v[16:19]
	v_mfma_f32_16x16x32_bf16 v[4:7], v[164:167], v[212:215], v[4:7]
	v_mfma_f32_16x16x32_bf16 v[0:3], v[180:183], v[212:215], v[0:3]
	v_mfma_f32_16x16x32_bf16 v[52:55], v[176:179], v[192:195], v[52:55]
	v_mfma_f32_16x16x32_bf16 v[48:51], v[184:187], v[192:195], v[48:51]
	v_mfma_f32_16x16x32_bf16 v[36:39], v[176:179], v[200:203], v[36:39]
	v_mfma_f32_16x16x32_bf16 v[32:35], v[184:187], v[200:203], v[32:35]
	v_mfma_f32_16x16x32_bf16 v[20:23], v[176:179], v[208:211], v[20:23]
	v_mfma_f32_16x16x32_bf16 v[16:19], v[184:187], v[208:211], v[16:19]
	s_setprio 2
	s_barrier
	v_mfma_f32_16x16x32_bf16 v[4:7], v[176:179], v[216:219], v[4:7]
	v_mfma_f32_16x16x32_bf16 v[0:3], v[184:187], v[216:219], v[0:3]
	s_setprio 0
	s_add_i32 s65, 0, 0x18000
	s_add_i32 s66, 0, 0x1c000
	v_add_u32_e32 v92, s65, v169
	v_add_u32_e32 v184, s66, v169
	ds_read_b128 v[80:83], v92
	ds_read_b128 v[84:87], v92 offset:1024
	ds_read_b128 v[88:91], v92 offset:2048
	ds_read_b128 v[92:95], v92 offset:3072
	ds_read_b128 v[164:167], v184
	ds_read_b128 v[176:179], v184 offset:1024
	ds_read_b128 v[180:183], v184 offset:2048
	ds_read_b128 v[184:187], v184 offset:3072
	s_add_u32 s46, s46, 0x80000
	s_addc_u32 s47, s47, 0
	s_mov_b32 m0, s49
	v_lshl_add_u64 v[228:229], s[46:47], 0, v[144:145]
	ds_read_b128 v[188:191], v173 offset:32768
	ds_read_b128 v[192:195], v173 offset:33792
	ds_read_b128 v[196:199], v173 offset:34816
	ds_read_b128 v[200:203], v173 offset:35840
	ds_read_b128 v[204:207], v173 offset:36864
	ds_read_b128 v[208:211], v173 offset:37888
	ds_read_b128 v[212:215], v173 offset:38912
	ds_read_b128 v[216:219], v173 offset:39936
	global_load_lds_dwordx4 v[228:229], off
	v_lshl_add_u64 v[228:229], s[46:47], 0, v[150:151]
	s_mov_b32 m0, s50
	s_nop 0
	global_load_lds_dwordx4 v[228:229], off
	s_waitcnt vmcnt(8)
	s_waitcnt lgkmcnt(0)
	s_setprio 1
	s_barrier
	v_mfma_f32_16x16x32_bf16 v[140:143], v[80:83], v[188:191], v[140:143]
	v_mfma_f32_16x16x32_bf16 v[136:139], v[88:91], v[188:191], v[136:139]
	v_mfma_f32_16x16x32_bf16 v[124:127], v[80:83], v[196:199], v[124:127]
	v_mfma_f32_16x16x32_bf16 v[120:123], v[88:91], v[196:199], v[120:123]
	v_mfma_f32_16x16x32_bf16 v[108:111], v[80:83], v[204:207], v[108:111]
	v_mfma_f32_16x16x32_bf16 v[104:107], v[88:91], v[204:207], v[104:107]
	v_mfma_f32_16x16x32_bf16 v[76:79], v[80:83], v[212:215], v[76:79]
	v_mfma_f32_16x16x32_bf16 v[72:75], v[88:91], v[212:215], v[72:75]
	v_mfma_f32_16x16x32_bf16 v[140:143], v[84:87], v[192:195], v[140:143]
	v_mfma_f32_16x16x32_bf16 v[136:139], v[92:95], v[192:195], v[136:139]
	v_mfma_f32_16x16x32_bf16 v[124:127], v[84:87], v[200:203], v[124:127]
	v_mfma_f32_16x16x32_bf16 v[120:123], v[92:95], v[200:203], v[120:123]
	v_mfma_f32_16x16x32_bf16 v[108:111], v[84:87], v[208:211], v[108:111]
	v_mfma_f32_16x16x32_bf16 v[104:107], v[92:95], v[208:211], v[104:107]
	v_mfma_f32_16x16x32_bf16 v[76:79], v[84:87], v[216:219], v[76:79]
	v_mfma_f32_16x16x32_bf16 v[72:75], v[92:95], v[216:219], v[72:75]
	v_mfma_f32_16x16x32_bf16 v[132:135], v[164:167], v[188:191], v[132:135]
	v_mfma_f32_16x16x32_bf16 v[128:131], v[180:183], v[188:191], v[128:131]
	v_mfma_f32_16x16x32_bf16 v[116:119], v[164:167], v[196:199], v[116:119]
	v_mfma_f32_16x16x32_bf16 v[112:115], v[180:183], v[196:199], v[112:115]
	v_mfma_f32_16x16x32_bf16 v[100:103], v[164:167], v[204:207], v[100:103]
	v_mfma_f32_16x16x32_bf16 v[96:99], v[180:183], v[204:207], v[96:99]
	v_mfma_f32_16x16x32_bf16 v[68:71], v[164:167], v[212:215], v[68:71]
	v_mfma_f32_16x16x32_bf16 v[64:67], v[180:183], v[212:215], v[64:67]
	v_mfma_f32_16x16x32_bf16 v[132:135], v[176:179], v[192:195], v[132:135]
	v_mfma_f32_16x16x32_bf16 v[128:131], v[184:187], v[192:195], v[128:131]
	v_mfma_f32_16x16x32_bf16 v[116:119], v[176:179], v[200:203], v[116:119]
	v_mfma_f32_16x16x32_bf16 v[112:115], v[184:187], v[200:203], v[112:115]
	v_mfma_f32_16x16x32_bf16 v[100:103], v[176:179], v[208:211], v[100:103]
	v_mfma_f32_16x16x32_bf16 v[96:99], v[184:187], v[208:211], v[96:99]
	s_setprio 2
	s_barrier
; #define PG8_STAGE(bufoff, gbase, voff) do { _Pragma("unroll") for (int _i = 0; _i < 2; ++_i) \
;         __builtin_amdgcn_global_load_lds((const unsigned*)((const char*)(gbase) + (voff)[_i]), (PG8_LAS unsigned*)(lds + (bufoff) + ldsw + _i * 8192), 16, 0, 0); } while (0)
; #define PG8_LDA(dst, b, h) do { _Pragma("unroll") for (int m = 0; m < 4; ++m) _Pragma("unroll") for (int k = 0; k < 2; ++k) dst[m][k] = *(const PG8_LAS bf16x8*)(lds + PG8_SA(b, h) + aoff + m * 2048 + k * 1024); } while (0)
; #define PG8_MMA(ai, bj, At, Bt) do { __builtin_amdgcn_s_setprio(1); _Pragma("unroll") for (int m = 0; m < 4; ++m) _Pragma("unroll") for (int n = 0; n < 2; ++n) _Pragma("unroll") for (int k = 0; k < 2; ++k) \
;         acc[ai][bj][m][n] = __builtin_amdgcn_mfma_f32_16x16x32_bf16(Bt[n][k], At[m][k], acc[ai][bj][m][n], 0, 0, 0); __builtin_amdgcn_s_setprio(0); } while (0)
; #define PG8_WAIT_V(n) asm volatile("s_waitcnt vmcnt(" #n ")" ::: "memory")
; #define PG8_WAIT_L(n) asm volatile("s_waitcnt lgkmcnt(" #n ")" ::: "memory")
; #define PG8_BAR __builtin_amdgcn_s_barrier()
; #define PG8_SCHED __builtin_amdgcn_sched_barrier(0)
; template <class Epi, class Sched, bool ALIGN_EPI = false, bool SP2 = false>
; __device__ __forceinline__ void gemm_phase(PG8_LAS unsigned char* lds, const Gemm g, const Sched& S, const Epi& E) {
;     ...
;             PG8_WAIT_V(8); PG8_WAIT_L(0); PG8_BAR; PG8_MMA(0, 0, At, B0); PG8_MMA(0, 1, At, B1); PG8_BAR; PG8_SCHED;
;             PG8_LDA(At, 1, 1); PG8_STAGE(PG8_SB(1, 0), b3, voffB); PG8_STAGE(PG8_SB(1, 1), b3 + hstep, voffB); PG8_STAGE(PG8_SA(1, 0), a3, voffA);
;             PG8_WAIT_V(8); PG8_WAIT_L(0); PG8_BAR; PG8_MMA(1, 0, At, B0); PG8_MMA(1, 1, At, B1); PG8_BAR; PG8_SCHED;
	v_mfma_f32_16x16x32_bf16 v[68:71], v[176:179], v[216:219], v[68:71]
	v_mfma_f32_16x16x32_bf16 v[64:67], v[184:187], v[216:219], v[64:67]
	s_setprio 0
	s_add_i32 s46, s65, s33
	v_lshl_add_u64 v[220:221], v[220:221], 0, s[8:9]
	s_mov_b32 m0, s46
	ds_read_b128 v[188:191], v173 offset:49152
	ds_read_b128 v[192:195], v173 offset:50176
	ds_read_b128 v[196:199], v173 offset:51200
	ds_read_b128 v[200:203], v173 offset:52224
	ds_read_b128 v[204:207], v173 offset:53248
	ds_read_b128 v[208:211], v173 offset:54272
	ds_read_b128 v[212:215], v173 offset:55296
	ds_read_b128 v[216:219], v173 offset:56320
	global_load_lds_dwordx4 v[220:221], off
	s_add_i32 m0, s46, 0x2000
	s_add_u32 s44, s44, 0x80080
	v_lshl_add_u64 v[220:221], v[222:223], 0, s[8:9]
	s_addc_u32 s45, s45, 0
	s_add_i32 s46, s66, s33
	global_load_lds_dwordx4 v[220:221], off
	v_lshl_add_u64 v[220:221], s[44:45], 0, v[148:149]
	s_mov_b32 m0, s46
	s_nop 0
	global_load_lds_dwordx4 v[220:221], off
	v_lshl_add_u64 v[220:221], s[44:45], 0, v[152:153]
	s_add_i32 m0, s46, 0x2000
	s_nop 0
	global_load_lds_dwordx4 v[220:221], off
	v_lshl_add_u64 v[220:221], v[224:225], 0, s[8:9]
	s_mov_b32 m0, s52
	s_nop 0
	global_load_lds_dwordx4 v[220:221], off
	v_lshl_add_u64 v[220:221], v[226:227], 0, s[8:9]
	s_mov_b32 m0, s53
	s_nop 0
	global_load_lds_dwordx4 v[220:221], off
	s_waitcnt vmcnt(8)
	s_waitcnt lgkmcnt(0)
	s_setprio 1
	s_barrier
	v_mfma_f32_16x16x32_bf16 v[60:63], v[80:83], v[188:191], v[60:63]
	v_mfma_f32_16x16x32_bf16 v[56:59], v[88:91], v[188:191], v[56:59]
	v_mfma_f32_16x16x32_bf16 v[44:47], v[80:83], v[196:199], v[44:47]
	v_mfma_f32_16x16x32_bf16 v[40:43], v[88:91], v[196:199], v[40:43]
	v_mfma_f32_16x16x32_bf16 v[28:31], v[80:83], v[204:207], v[28:31]
	v_mfma_f32_16x16x32_bf16 v[24:27], v[88:91], v[204:207], v[24:27]
	v_mfma_f32_16x16x32_bf16 v[12:15], v[80:83], v[212:215], v[12:15]
	v_mfma_f32_16x16x32_bf16 v[8:11], v[88:91], v[212:215], v[8:11]
	v_mfma_f32_16x16x32_bf16 v[60:63], v[84:87], v[192:195], v[60:63]
	v_mfma_f32_16x16x32_bf16 v[56:59], v[92:95], v[192:195], v[56:59]
	v_mfma_f32_16x16x32_bf16 v[44:47], v[84:87], v[200:203], v[44:47]
	v_mfma_f32_16x16x32_bf16 v[40:43], v[92:95], v[200:203], v[40:43]
	v_mfma_f32_16x16x32_bf16 v[28:31], v[84:87], v[208:211], v[28:31]
	v_mfma_f32_16x16x32_bf16 v[24:27], v[92:95], v[208:211], v[24:27]
	v_mfma_f32_16x16x32_bf16 v[12:15], v[84:87], v[216:219], v[12:15]
	v_mfma_f32_16x16x32_bf16 v[8:11], v[92:95], v[216:219], v[8:11]
	v_mfma_f32_16x16x32_bf16 v[52:55], v[164:167], v[188:191], v[52:55]
	v_mfma_f32_16x16x32_bf16 v[48:51], v[180:183], v[188:191], v[48:51]
	v_mfma_f32_16x16x32_bf16 v[36:39], v[164:167], v[196:199], v[36:39]
	v_mfma_f32_16x16x32_bf16 v[32:35], v[180:183], v[196:199], v[32:35]
	v_mfma_f32_16x16x32_bf16 v[20:23], v[164:167], v[204:207], v[20:23]
	v_mfma_f32_16x16x32_bf16 v[16:19], v[180:183], v[204:207], v[16:19]
	v_mfma_f32_16x16x32_bf16 v[4:7], v[164:167], v[212:215], v[4:7]
	v_mfma_f32_16x16x32_bf16 v[0:3], v[180:183], v[212:215], v[0:3]
	v_mfma_f32_16x16x32_bf16 v[52:55], v[176:179], v[192:195], v[52:55]
	v_mfma_f32_16x16x32_bf16 v[48:51], v[184:187], v[192:195], v[48:51]
	v_mfma_f32_16x16x32_bf16 v[36:39], v[176:179], v[200:203], v[36:39]
	v_mfma_f32_16x16x32_bf16 v[32:35], v[184:187], v[200:203], v[32:35]
	v_mfma_f32_16x16x32_bf16 v[20:23], v[176:179], v[208:211], v[20:23]
	v_mfma_f32_16x16x32_bf16 v[16:19], v[184:187], v[208:211], v[16:19]
	s_setprio 2
	s_barrier
	v_mfma_f32_16x16x32_bf16 v[4:7], v[176:179], v[216:219], v[4:7]
	v_mfma_f32_16x16x32_bf16 v[0:3], v[184:187], v[216:219], v[0:3]
	s_setprio 0
	s_add_i32 s64, s64, 2
	s_add_u32 s42, s42, 0x100
	s_addc_u32 s43, s43, 0
	s_add_u32 s62, s62, 0x100
	s_addc_u32 s63, s63, 0
	s_cmp_gt_u32 s64, 29
	s_cbranch_scc0 .LBB0_1142
	s_and_b64 vcc, exec, s[10:11]
	s_cbranch_vccz .LBB0_1145
	s_barrier

; #define PG8_STAGE(bufoff, gbase, voff) do { _Pragma("unroll") for (int _i = 0; _i < 2; ++_i) \
;         __builtin_amdgcn_global_load_lds((const unsigned*)((const char*)(gbase) + (voff)[_i]), (PG8_LAS unsigned*)(lds + (bufoff) + ldsw + _i * 8192), 16, 0, 0); } while (0)
; #define PG8_LDA(dst, b, h) do { _Pragma("unroll") for (int m = 0; m < 4; ++m) _Pragma("unroll") for (int k = 0; k < 2; ++k) dst[m][k] = *(const PG8_LAS bf16x8*)(lds + PG8_SA(b, h) + aoff + m * 2048 + k * 1024); } while (0)
; #define PG8_LDB(dst, b, h) do { _Pragma("unroll") for (int n = 0; n < 2; ++n) _Pragma("unroll") for (int k = 0; k < 2; ++k) dst[n][k] = *(const PG8_LAS bf16x8*)(lds + PG8_SB(b, h) + boff + n * 2048 + k * 1024); } while (0)
; #define PG8_MMA(ai, bj, At, Bt) do { __builtin_amdgcn_s_setprio(1); _Pragma("unroll") for (int m = 0; m < 4; ++m) _Pragma("unroll") for (int n = 0; n < 2; ++n) _Pragma("unroll") for (int k = 0; k < 2; ++k) \
;         acc[ai][bj][m][n] = __builtin_amdgcn_mfma_f32_16x16x32_bf16(Bt[n][k], At[m][k], acc[ai][bj][m][n], 0, 0, 0); __builtin_amdgcn_s_setprio(0); } while (0)
; #define PG8_WAIT_V(n) asm volatile("s_waitcnt vmcnt(" #n ")" ::: "memory")
; #define PG8_WAIT_L(n) asm volatile("s_waitcnt lgkmcnt(" #n ")" ::: "memory")
; #define PG8_BAR __builtin_amdgcn_s_barrier()
; template <class Epi, class Sched, bool ALIGN_EPI = false, bool SP2 = false>
; __device__ __forceinline__ void gemm_phase(PG8_LAS unsigned char* lds, const Gemm g, const Sched& S, const Epi& E) {
;     ...
;             const bool last = (t == nt - 2);
;             const char* a1 = cA + (size_t)(t + 1) * kstep;
;             const char* a2 = last ? nA : cA + (size_t)(t + 2) * kstep; const char* b2 = last ? nB : cB + (size_t)(t + 2) * kstep;
;             const char* a3 = a2 + kstep; const char* b3 = b2 + kstep;
;             if constexpr (SP2) {
;             PG8_LDB(B0, 0, 0); PG8_LDB(B1, 0, 1); PG8_SCHED; PG8_LDA(At, 0, 0); PG8_STAGE(PG8_SA(1, 1), a1 + hstep, voffA);
;             PG8_WAIT_V(8); PG8_WAIT_L(0); PG8_BAR; PG8_MMA(0, 0, At, B0); PG8_MMA(0, 1, At, B1); PG8_BAR; PG8_SCHED;
;             PG8_LDA(At, 0, 1); PG8_STAGE(PG8_SB(0, 0), b2, voffB); PG8_STAGE(PG8_SB(0, 1), b2 + hstep, voffB); PG8_STAGE(PG8_SA(0, 0), a2, voffA);
;             PG8_WAIT_V(8); PG8_WAIT_L(0); PG8_BAR; PG8_MMA(1, 0, At, B0); PG8_MMA(1, 1, At, B1); PG8_BAR; PG8_SCHED;
.LBB0_1219:
	ds_read_b128 v[128:131], v167
	ds_read_b128 v[132:135], v167 offset:1024
	ds_read_b128 v[154:157], v167 offset:2048
	ds_read_b128 v[158:161], v167 offset:3072
	ds_read_b128 v[170:173], v168
	ds_read_b128 v[174:177], v168 offset:1024
	ds_read_b128 v[178:181], v168 offset:2048
	ds_read_b128 v[182:185], v168 offset:3072
	s_add_u32 s42, s40, 0xffe00080
	s_addc_u32 s43, s41, -1
	s_cmpk_eq_i32 s63, 0x7c
	s_cselect_b32 s45, s15, s43
	s_cselect_b32 s44, s59, s42
	s_cselect_b32 s43, s13, s62
	s_cselect_b32 s42, s60, s61
	v_lshl_add_u64 v[162:163], s[40:41], 0, v[144:145]
	s_add_i32 m0, s39, 0xc000
	ds_read_b128 v[186:189], v169
	ds_read_b128 v[190:193], v169 offset:1024
	ds_read_b128 v[194:197], v169 offset:2048
	ds_read_b128 v[198:201], v169 offset:3072
	ds_read_b128 v[202:205], v169 offset:4096
	ds_read_b128 v[206:209], v169 offset:5120
	ds_read_b128 v[210:213], v169 offset:6144
	ds_read_b128 v[214:217], v169 offset:7168
	global_load_lds_dwordx4 v[162:163], off
	v_lshl_add_u64 v[162:163], s[40:41], 0, v[148:149]
	s_add_i32 m0, s39, 0xe000
	s_nop 0
	global_load_lds_dwordx4 v[162:163], off
	s_waitcnt vmcnt(8)
	s_waitcnt lgkmcnt(0)
	s_setprio 1
	s_barrier
	v_mfma_f32_16x16x32_bf16 v[124:127], v[128:131], v[186:189], v[124:127]
	v_mfma_f32_16x16x32_bf16 v[120:123], v[154:157], v[186:189], v[120:123]
	v_mfma_f32_16x16x32_bf16 v[116:119], v[128:131], v[194:197], v[116:119]
	v_mfma_f32_16x16x32_bf16 v[112:115], v[154:157], v[194:197], v[112:115]
	v_mfma_f32_16x16x32_bf16 v[108:111], v[128:131], v[202:205], v[108:111]
	v_mfma_f32_16x16x32_bf16 v[104:107], v[154:157], v[202:205], v[104:107]
	v_mfma_f32_16x16x32_bf16 v[100:103], v[128:131], v[210:213], v[100:103]
	v_mfma_f32_16x16x32_bf16 v[96:99], v[154:157], v[210:213], v[96:99]
	v_mfma_f32_16x16x32_bf16 v[124:127], v[132:135], v[190:193], v[124:127]
	v_mfma_f32_16x16x32_bf16 v[120:123], v[158:161], v[190:193], v[120:123]
	v_mfma_f32_16x16x32_bf16 v[116:119], v[132:135], v[198:201], v[116:119]
	v_mfma_f32_16x16x32_bf16 v[112:115], v[158:161], v[198:201], v[112:115]
	v_mfma_f32_16x16x32_bf16 v[108:111], v[132:135], v[206:209], v[108:111]
	v_mfma_f32_16x16x32_bf16 v[104:107], v[158:161], v[206:209], v[104:107]
	v_mfma_f32_16x16x32_bf16 v[100:103], v[132:135], v[214:217], v[100:103]
	v_mfma_f32_16x16x32_bf16 v[96:99], v[158:161], v[214:217], v[96:99]
	v_mfma_f32_16x16x32_bf16 v[68:71], v[170:173], v[186:189], v[68:71]
	v_mfma_f32_16x16x32_bf16 v[60:63], v[178:181], v[186:189], v[60:63]
	v_mfma_f32_16x16x32_bf16 v[52:55], v[170:173], v[194:197], v[52:55]
	v_mfma_f32_16x16x32_bf16 v[48:51], v[178:181], v[194:197], v[48:51]
	v_mfma_f32_16x16x32_bf16 v[44:47], v[170:173], v[202:205], v[44:47]
	v_mfma_f32_16x16x32_bf16 v[40:43], v[178:181], v[202:205], v[40:43]
	v_mfma_f32_16x16x32_bf16 v[36:39], v[170:173], v[210:213], v[36:39]
	v_mfma_f32_16x16x32_bf16 v[32:35], v[178:181], v[210:213], v[32:35]
	v_mfma_f32_16x16x32_bf16 v[68:71], v[174:177], v[190:193], v[68:71]
	v_mfma_f32_16x16x32_bf16 v[60:63], v[182:185], v[190:193], v[60:63]
	v_mfma_f32_16x16x32_bf16 v[52:55], v[174:177], v[198:201], v[52:55]
	v_mfma_f32_16x16x32_bf16 v[48:51], v[182:185], v[198:201], v[48:51]
	v_mfma_f32_16x16x32_bf16 v[44:47], v[174:177], v[206:209], v[44:47]
	v_mfma_f32_16x16x32_bf16 v[40:43], v[182:185], v[206:209], v[40:43]
	s_setprio 2
	s_barrier
	v_mfma_f32_16x16x32_bf16 v[36:39], v[174:177], v[214:217], v[36:39]
	v_mfma_f32_16x16x32_bf16 v[32:35], v[182:185], v[214:217], v[32:35]
	s_setprio 0
	s_add_i32 s64, s56, s33
	v_lshl_add_u64 v[162:163], s[42:43], 0, v[138:139]
	s_mov_b32 m0, s64
	ds_read_b128 v[186:189], v169 offset:16384
	ds_read_b128 v[190:193], v169 offset:17408
	ds_read_b128 v[194:197], v169 offset:18432
	ds_read_b128 v[198:201], v169 offset:19456
	ds_read_b128 v[202:205], v169 offset:20480
	ds_read_b128 v[206:209], v169 offset:21504
	ds_read_b128 v[210:213], v169 offset:22528
	ds_read_b128 v[214:217], v169 offset:23552
	global_load_lds_dwordx4 v[162:163], off
	s_add_i32 m0, s64, 0x2000
	s_add_u32 s64, s42, 0x200000
	v_lshl_add_u64 v[218:219], s[42:43], 0, v[142:143]
	s_addc_u32 s65, s43, 0
	s_add_i32 s66, s57, s33
	global_load_lds_dwordx4 v[218:219], off
	v_lshl_add_u64 v[220:221], s[64:65], 0, v[138:139]
	s_mov_b32 m0, s66
	v_lshl_add_u64 v[222:223], s[44:45], 0, v[140:141]
	global_load_lds_dwordx4 v[220:221], off
	v_lshl_add_u64 v[220:221], s[64:65], 0, v[142:143]
	s_add_i32 m0, s66, 0x2000
	s_nop 0
	global_load_lds_dwordx4 v[220:221], off
	v_lshl_add_u64 v[220:221], s[44:45], 0, v[136:137]
	s_mov_b32 m0, s39
	s_nop 0
	global_load_lds_dwordx4 v[220:221], off
	s_mov_b32 m0, s46
	s_nop 0
	global_load_lds_dwordx4 v[222:223], off
	s_waitcnt vmcnt(8)
	s_waitcnt lgkmcnt(0)
	s_setprio 1
	s_barrier
; #define PG8_STAGE(bufoff, gbase, voff) do { _Pragma("unroll") for (int _i = 0; _i < 2; ++_i) \
;         __builtin_amdgcn_global_load_lds((const unsigned*)((const char*)(gbase) + (voff)[_i]), (PG8_LAS unsigned*)(lds + (bufoff) + ldsw + _i * 8192), 16, 0, 0); } while (0)
; #define PG8_LDA(dst, b, h) do { _Pragma("unroll") for (int m = 0; m < 4; ++m) _Pragma("unroll") for (int k = 0; k < 2; ++k) dst[m][k] = *(const PG8_LAS bf16x8*)(lds + PG8_SA(b, h) + aoff + m * 2048 + k * 1024); } while (0)
; #define PG8_LDB(dst, b, h) do { _Pragma("unroll") for (int n = 0; n < 2; ++n) _Pragma("unroll") for (int k = 0; k < 2; ++k) dst[n][k] = *(const PG8_LAS bf16x8*)(lds + PG8_SB(b, h) + boff + n * 2048 + k * 1024); } while (0)
; #define PG8_MMA(ai, bj, At, Bt) do { __builtin_amdgcn_s_setprio(1); _Pragma("unroll") for (int m = 0; m < 4; ++m) _Pragma("unroll") for (int n = 0; n < 2; ++n) _Pragma("unroll") for (int k = 0; k < 2; ++k) \
;         acc[ai][bj][m][n] = __builtin_amdgcn_mfma_f32_16x16x32_bf16(Bt[n][k], At[m][k], acc[ai][bj][m][n], 0, 0, 0); __builtin_amdgcn_s_setprio(0); } while (0)
; #define PG8_WAIT_V(n) asm volatile("s_waitcnt vmcnt(" #n ")" ::: "memory")
; #define PG8_WAIT_L(n) asm volatile("s_waitcnt lgkmcnt(" #n ")" ::: "memory")
; #define PG8_BAR __builtin_amdgcn_s_barrier()
; #define PG8_SCHED __builtin_amdgcn_sched_barrier(0)
; template <class Epi, class Sched, bool ALIGN_EPI = false, bool SP2 = false>
; __device__ __forceinline__ void gemm_phase(PG8_LAS unsigned char* lds, const Gemm g, const Sched& S, const Epi& E) {
;     ...
;             PG8_LDB(B0, 0, 0); PG8_LDB(B1, 0, 1); PG8_SCHED; PG8_LDA(At, 0, 0); PG8_STAGE(PG8_SA(1, 1), a1 + hstep, voffA);
;             PG8_WAIT_V(8); PG8_WAIT_L(0); PG8_BAR; PG8_MMA(0, 0, At, B0); PG8_MMA(0, 1, At, B1); PG8_BAR; PG8_SCHED;
;             PG8_LDA(At, 0, 1); PG8_STAGE(PG8_SB(0, 0), b2, voffB); PG8_STAGE(PG8_SB(0, 1), b2 + hstep, voffB); PG8_STAGE(PG8_SA(0, 0), a2, voffA);
;             PG8_WAIT_V(8); PG8_WAIT_L(0); PG8_BAR; PG8_MMA(1, 0, At, B0); PG8_MMA(1, 1, At, B1); PG8_BAR; PG8_SCHED;
;             PG8_LDB(B0, 1, 0); PG8_LDB(B1, 1, 1); PG8_SCHED; PG8_LDA(At, 1, 0); PG8_STAGE(PG8_SA(0, 1), a2 + hstep, voffA);
;             PG8_WAIT_V(8); PG8_WAIT_L(0); PG8_BAR; PG8_MMA(0, 0, At, B0); PG8_MMA(0, 1, At, B1); PG8_BAR; PG8_SCHED;
	v_mfma_f32_16x16x32_bf16 v[92:95], v[128:131], v[186:189], v[92:95]
	v_mfma_f32_16x16x32_bf16 v[88:91], v[154:157], v[186:189], v[88:91]
	v_mfma_f32_16x16x32_bf16 v[84:87], v[128:131], v[194:197], v[84:87]
	v_mfma_f32_16x16x32_bf16 v[80:83], v[154:157], v[194:197], v[80:83]
	v_mfma_f32_16x16x32_bf16 v[76:79], v[128:131], v[202:205], v[76:79]
	v_mfma_f32_16x16x32_bf16 v[72:75], v[154:157], v[202:205], v[72:75]
	v_mfma_f32_16x16x32_bf16 v[64:67], v[128:131], v[210:213], v[64:67]
	v_mfma_f32_16x16x32_bf16 v[56:59], v[154:157], v[210:213], v[56:59]
	v_mfma_f32_16x16x32_bf16 v[92:95], v[132:135], v[190:193], v[92:95]
	v_mfma_f32_16x16x32_bf16 v[88:91], v[158:161], v[190:193], v[88:91]
	v_mfma_f32_16x16x32_bf16 v[84:87], v[132:135], v[198:201], v[84:87]
	v_mfma_f32_16x16x32_bf16 v[80:83], v[158:161], v[198:201], v[80:83]
	v_mfma_f32_16x16x32_bf16 v[76:79], v[132:135], v[206:209], v[76:79]
	v_mfma_f32_16x16x32_bf16 v[72:75], v[158:161], v[206:209], v[72:75]
	v_mfma_f32_16x16x32_bf16 v[64:67], v[132:135], v[214:217], v[64:67]
	v_mfma_f32_16x16x32_bf16 v[56:59], v[158:161], v[214:217], v[56:59]
	v_mfma_f32_16x16x32_bf16 v[28:31], v[170:173], v[186:189], v[28:31]
	v_mfma_f32_16x16x32_bf16 v[24:27], v[178:181], v[186:189], v[24:27]
	v_mfma_f32_16x16x32_bf16 v[20:23], v[170:173], v[194:197], v[20:23]
	v_mfma_f32_16x16x32_bf16 v[16:19], v[178:181], v[194:197], v[16:19]
	v_mfma_f32_16x16x32_bf16 v[12:15], v[170:173], v[202:205], v[12:15]
	v_mfma_f32_16x16x32_bf16 v[8:11], v[178:181], v[202:205], v[8:11]
	v_mfma_f32_16x16x32_bf16 v[4:7], v[170:173], v[210:213], v[4:7]
	v_mfma_f32_16x16x32_bf16 v[0:3], v[178:181], v[210:213], v[0:3]
	v_mfma_f32_16x16x32_bf16 v[28:31], v[174:177], v[190:193], v[28:31]
	v_mfma_f32_16x16x32_bf16 v[24:27], v[182:185], v[190:193], v[24:27]
	v_mfma_f32_16x16x32_bf16 v[20:23], v[174:177], v[198:201], v[20:23]
	v_mfma_f32_16x16x32_bf16 v[16:19], v[182:185], v[198:201], v[16:19]
	v_mfma_f32_16x16x32_bf16 v[12:15], v[174:177], v[206:209], v[12:15]
	v_mfma_f32_16x16x32_bf16 v[8:11], v[182:185], v[206:209], v[8:11]
	s_setprio 2
	s_barrier
	v_mfma_f32_16x16x32_bf16 v[4:7], v[174:177], v[214:217], v[4:7]
	v_mfma_f32_16x16x32_bf16 v[0:3], v[182:185], v[214:217], v[0:3]
	s_setprio 0
	s_add_i32 s64, 0, 0x18000
	s_add_i32 s65, 0, 0x1c000
	v_add_u32_e32 v158, s64, v165
	v_add_u32_e32 v182, s65, v165
	ds_read_b128 v[128:131], v158
	ds_read_b128 v[132:135], v158 offset:1024
	ds_read_b128 v[154:157], v158 offset:2048
	ds_read_b128 v[158:161], v158 offset:3072
	ds_read_b128 v[170:173], v182
	ds_read_b128 v[174:177], v182 offset:1024
	ds_read_b128 v[178:181], v182 offset:2048
	ds_read_b128 v[182:185], v182 offset:3072
	s_add_u32 s44, s44, 0x200000
	s_addc_u32 s45, s45, 0
	s_mov_b32 m0, s47
	v_lshl_add_u64 v[224:225], s[44:45], 0, v[136:137]
	ds_read_b128 v[186:189], v169 offset:32768
	ds_read_b128 v[190:193], v169 offset:33792
	ds_read_b128 v[194:197], v169 offset:34816
	ds_read_b128 v[198:201], v169 offset:35840
	ds_read_b128 v[202:205], v169 offset:36864
	ds_read_b128 v[206:209], v169 offset:37888
	ds_read_b128 v[210:213], v169 offset:38912
	ds_read_b128 v[214:217], v169 offset:39936
	global_load_lds_dwordx4 v[224:225], off
	v_lshl_add_u64 v[224:225], s[44:45], 0, v[140:141]
	s_mov_b32 m0, s48
	s_nop 0
	global_load_lds_dwordx4 v[224:225], off
	s_waitcnt vmcnt(8)
	s_waitcnt lgkmcnt(0)
	s_setprio 1
	s_barrier
	v_mfma_f32_16x16x32_bf16 v[124:127], v[128:131], v[186:189], v[124:127]
	v_mfma_f32_16x16x32_bf16 v[120:123], v[154:157], v[186:189], v[120:123]
	v_mfma_f32_16x16x32_bf16 v[116:119], v[128:131], v[194:197], v[116:119]
	v_mfma_f32_16x16x32_bf16 v[112:115], v[154:157], v[194:197], v[112:115]
	v_mfma_f32_16x16x32_bf16 v[108:111], v[128:131], v[202:205], v[108:111]
	v_mfma_f32_16x16x32_bf16 v[104:107], v[154:157], v[202:205], v[104:107]
	v_mfma_f32_16x16x32_bf16 v[100:103], v[128:131], v[210:213], v[100:103]
	v_mfma_f32_16x16x32_bf16 v[96:99], v[154:157], v[210:213], v[96:99]
	v_mfma_f32_16x16x32_bf16 v[124:127], v[132:135], v[190:193], v[124:127]
	v_mfma_f32_16x16x32_bf16 v[120:123], v[158:161], v[190:193], v[120:123]
	v_mfma_f32_16x16x32_bf16 v[116:119], v[132:135], v[198:201], v[116:119]
	v_mfma_f32_16x16x32_bf16 v[112:115], v[158:161], v[198:201], v[112:115]
	v_mfma_f32_16x16x32_bf16 v[108:111], v[132:135], v[206:209], v[108:111]
	v_mfma_f32_16x16x32_bf16 v[104:107], v[158:161], v[206:209], v[104:107]
	v_mfma_f32_16x16x32_bf16 v[100:103], v[132:135], v[214:217], v[100:103]
	v_mfma_f32_16x16x32_bf16 v[96:99], v[158:161], v[214:217], v[96:99]
	v_mfma_f32_16x16x32_bf16 v[68:71], v[170:173], v[186:189], v[68:71]
	v_mfma_f32_16x16x32_bf16 v[60:63], v[178:181], v[186:189], v[60:63]
	v_mfma_f32_16x16x32_bf16 v[52:55], v[170:173], v[194:197], v[52:55]
	v_mfma_f32_16x16x32_bf16 v[48:51], v[178:181], v[194:197], v[48:51]
	v_mfma_f32_16x16x32_bf16 v[44:47], v[170:173], v[202:205], v[44:47]
	v_mfma_f32_16x16x32_bf16 v[40:43], v[178:181], v[202:205], v[40:43]
	v_mfma_f32_16x16x32_bf16 v[36:39], v[170:173], v[210:213], v[36:39]
	v_mfma_f32_16x16x32_bf16 v[32:35], v[178:181], v[210:213], v[32:35]
	v_mfma_f32_16x16x32_bf16 v[68:71], v[174:177], v[190:193], v[68:71]
	v_mfma_f32_16x16x32_bf16 v[60:63], v[182:185], v[190:193], v[60:63]
	v_mfma_f32_16x16x32_bf16 v[52:55], v[174:177], v[198:201], v[52:55]
	v_mfma_f32_16x16x32_bf16 v[48:51], v[182:185], v[198:201], v[48:51]
	v_mfma_f32_16x16x32_bf16 v[44:47], v[174:177], v[206:209], v[44:47]
	v_mfma_f32_16x16x32_bf16 v[40:43], v[182:185], v[206:209], v[40:43]
	s_setprio 2
	s_barrier
; #define PG8_STAGE(bufoff, gbase, voff) do { _Pragma("unroll") for (int _i = 0; _i < 2; ++_i) \
;         __builtin_amdgcn_global_load_lds((const unsigned*)((const char*)(gbase) + (voff)[_i]), (PG8_LAS unsigned*)(lds + (bufoff) + ldsw + _i * 8192), 16, 0, 0); } while (0)
; #define PG8_LDA(dst, b, h) do { _Pragma("unroll") for (int m = 0; m < 4; ++m) _Pragma("unroll") for (int k = 0; k < 2; ++k) dst[m][k] = *(const PG8_LAS bf16x8*)(lds + PG8_SA(b, h) + aoff + m * 2048 + k * 1024); } while (0)
; #define PG8_MMA(ai, bj, At, Bt) do { __builtin_amdgcn_s_setprio(1); _Pragma("unroll") for (int m = 0; m < 4; ++m) _Pragma("unroll") for (int n = 0; n < 2; ++n) _Pragma("unroll") for (int k = 0; k < 2; ++k) \
;         acc[ai][bj][m][n] = __builtin_amdgcn_mfma_f32_16x16x32_bf16(Bt[n][k], At[m][k], acc[ai][bj][m][n], 0, 0, 0); __builtin_amdgcn_s_setprio(0); } while (0)
; #define PG8_WAIT_V(n) asm volatile("s_waitcnt vmcnt(" #n ")" ::: "memory")
; #define PG8_WAIT_L(n) asm volatile("s_waitcnt lgkmcnt(" #n ")" ::: "memory")
; #define PG8_BAR __builtin_amdgcn_s_barrier()
; #define PG8_SCHED __builtin_amdgcn_sched_barrier(0)
; template <class Epi, class Sched, bool ALIGN_EPI = false, bool SP2 = false>
; __device__ __forceinline__ void gemm_phase(PG8_LAS unsigned char* lds, const Gemm g, const Sched& S, const Epi& E) {
;     ...
;             PG8_WAIT_V(8); PG8_WAIT_L(0); PG8_BAR; PG8_MMA(0, 0, At, B0); PG8_MMA(0, 1, At, B1); PG8_BAR; PG8_SCHED;
;             PG8_LDA(At, 1, 1); PG8_STAGE(PG8_SB(1, 0), b3, voffB); PG8_STAGE(PG8_SB(1, 1), b3 + hstep, voffB); PG8_STAGE(PG8_SA(1, 0), a3, voffA);
;             PG8_WAIT_V(8); PG8_WAIT_L(0); PG8_BAR; PG8_MMA(1, 0, At, B0); PG8_MMA(1, 1, At, B1); PG8_BAR; PG8_SCHED;
	v_mfma_f32_16x16x32_bf16 v[36:39], v[174:177], v[214:217], v[36:39]
	v_mfma_f32_16x16x32_bf16 v[32:35], v[182:185], v[214:217], v[32:35]
	s_setprio 0
	s_add_i32 s44, s64, s33
	v_lshl_add_u64 v[162:163], v[162:163], 0, s[8:9]
	s_mov_b32 m0, s44
	ds_read_b128 v[186:189], v169 offset:49152
	ds_read_b128 v[190:193], v169 offset:50176
	ds_read_b128 v[194:197], v169 offset:51200
	ds_read_b128 v[198:201], v169 offset:52224
	ds_read_b128 v[202:205], v169 offset:53248
	ds_read_b128 v[206:209], v169 offset:54272
	ds_read_b128 v[210:213], v169 offset:55296
	ds_read_b128 v[214:217], v169 offset:56320
	global_load_lds_dwordx4 v[162:163], off
	s_add_i32 m0, s44, 0x2000
	s_add_u32 s42, s42, 0x200080
	v_lshl_add_u64 v[162:163], v[218:219], 0, s[8:9]
	s_addc_u32 s43, s43, 0
	s_add_i32 s44, s65, s33
	global_load_lds_dwordx4 v[162:163], off
	v_lshl_add_u64 v[162:163], s[42:43], 0, v[138:139]
	s_mov_b32 m0, s44
	s_nop 0
	global_load_lds_dwordx4 v[162:163], off
	v_lshl_add_u64 v[162:163], s[42:43], 0, v[142:143]
	s_add_i32 m0, s44, 0x2000
	s_nop 0
	global_load_lds_dwordx4 v[162:163], off
	v_lshl_add_u64 v[162:163], v[220:221], 0, s[8:9]
	s_mov_b32 m0, s52
	s_nop 0
	global_load_lds_dwordx4 v[162:163], off
	v_lshl_add_u64 v[162:163], v[222:223], 0, s[8:9]
	s_mov_b32 m0, s53
	s_nop 0
	global_load_lds_dwordx4 v[162:163], off
	s_waitcnt vmcnt(8)
	s_waitcnt lgkmcnt(0)
	s_setprio 1
	s_barrier
	v_mfma_f32_16x16x32_bf16 v[92:95], v[128:131], v[186:189], v[92:95]
	v_mfma_f32_16x16x32_bf16 v[88:91], v[154:157], v[186:189], v[88:91]
	v_mfma_f32_16x16x32_bf16 v[84:87], v[128:131], v[194:197], v[84:87]
	v_mfma_f32_16x16x32_bf16 v[80:83], v[154:157], v[194:197], v[80:83]
	v_mfma_f32_16x16x32_bf16 v[76:79], v[128:131], v[202:205], v[76:79]
	v_mfma_f32_16x16x32_bf16 v[72:75], v[154:157], v[202:205], v[72:75]
	v_mfma_f32_16x16x32_bf16 v[64:67], v[128:131], v[210:213], v[64:67]
	v_mfma_f32_16x16x32_bf16 v[56:59], v[154:157], v[210:213], v[56:59]
	v_mfma_f32_16x16x32_bf16 v[92:95], v[132:135], v[190:193], v[92:95]
	v_mfma_f32_16x16x32_bf16 v[88:91], v[158:161], v[190:193], v[88:91]
	v_mfma_f32_16x16x32_bf16 v[84:87], v[132:135], v[198:201], v[84:87]
	v_mfma_f32_16x16x32_bf16 v[80:83], v[158:161], v[198:201], v[80:83]
	v_mfma_f32_16x16x32_bf16 v[76:79], v[132:135], v[206:209], v[76:79]
	v_mfma_f32_16x16x32_bf16 v[72:75], v[158:161], v[206:209], v[72:75]
	v_mfma_f32_16x16x32_bf16 v[64:67], v[132:135], v[214:217], v[64:67]
	v_mfma_f32_16x16x32_bf16 v[56:59], v[158:161], v[214:217], v[56:59]
	v_mfma_f32_16x16x32_bf16 v[28:31], v[170:173], v[186:189], v[28:31]
	v_mfma_f32_16x16x32_bf16 v[24:27], v[178:181], v[186:189], v[24:27]
	v_mfma_f32_16x16x32_bf16 v[20:23], v[170:173], v[194:197], v[20:23]
	v_mfma_f32_16x16x32_bf16 v[16:19], v[178:181], v[194:197], v[16:19]
	v_mfma_f32_16x16x32_bf16 v[12:15], v[170:173], v[202:205], v[12:15]
	v_mfma_f32_16x16x32_bf16 v[8:11], v[178:181], v[202:205], v[8:11]
	v_mfma_f32_16x16x32_bf16 v[4:7], v[170:173], v[210:213], v[4:7]
	v_mfma_f32_16x16x32_bf16 v[0:3], v[178:181], v[210:213], v[0:3]
	v_mfma_f32_16x16x32_bf16 v[28:31], v[174:177], v[190:193], v[28:31]
	v_mfma_f32_16x16x32_bf16 v[24:27], v[182:185], v[190:193], v[24:27]
	v_mfma_f32_16x16x32_bf16 v[20:23], v[174:177], v[198:201], v[20:23]
	v_mfma_f32_16x16x32_bf16 v[16:19], v[182:185], v[198:201], v[16:19]
	v_mfma_f32_16x16x32_bf16 v[12:15], v[174:177], v[206:209], v[12:15]
	v_mfma_f32_16x16x32_bf16 v[8:11], v[182:185], v[206:209], v[8:11]
	s_setprio 2
	s_barrier
	v_mfma_f32_16x16x32_bf16 v[4:7], v[174:177], v[214:217], v[4:7]
	v_mfma_f32_16x16x32_bf16 v[0:3], v[182:185], v[214:217], v[0:3]
	s_setprio 0
	s_add_i32 s63, s63, 2
	s_add_u32 s40, s40, 0x100
	s_addc_u32 s41, s41, 0
	s_add_u32 s61, s61, 0x100
	s_addc_u32 s62, s62, 0
	s_cmpk_gt_u32 s63, 0x7d
	s_cbranch_scc0 .LBB0_1219
	s_and_b64 vcc, exec, s[10:11]
	s_cbranch_vccz .LBB0_1222
	s_barrier
